# solve DPP broadcast reads the accumulator directly (no copy / zero-init), scalar -log2e multiplies and 1.0 adds of adjacent register pairs packed into v_pk_mul_f32 / v_pk_add_f32 (trans hazard padded)
# speedup vs baseline: 1.0034x; 1.0034x over previous
.LBB0_53:
	v_lshl_or_b32 v144, s6, 7, v152
	s_sub_i32 s6, s7, s5
	v_lshl_add_u32 v155, s6, 10, v151
	ds_read2_b32 v[148:149], v155 offset1:16
	v_lshl_add_u32 v154, s7, 8, v1
	v_ashrrev_i32_e32 v145, 31, v144
	v_mov_b64_e32 v[142:143], s[80:81]
	v_mad_i64_i32 v[146:147], s[6:7], v154, s86, v[142:143]
	s_waitcnt lgkmcnt(0)
	v_pk_mul_f32 v[126:127], v[126:127], v[148:149] op_sel_hi:[1,0]
	v_pk_mul_f32 v[122:123], v[122:123], v[148:149] op_sel_hi:[1,0]
	v_pk_mul_f32 v[156:157], v[126:127], s[96:97] op_sel_hi:[1,0]
	v_exp_f32_e32 v156, v156
	v_exp_f32_e32 v157, v157
	v_pk_mul_f32 v[124:125], v[124:125], v[148:149] op_sel_hi:[1,0]
	v_pk_mul_f32 v[118:119], v[118:119], v[148:149] op_sel_hi:[1,0]
	v_pk_add_f32 v[156:157], v[156:157], 1.0 op_sel_hi:[1,0]
	v_rcp_f32_e32 v156, v156
	v_rcp_f32_e32 v157, v157
	v_pk_mul_f32 v[114:115], v[114:115], v[148:149] op_sel_hi:[1,0]
	v_pk_mul_f32 v[116:117], v[116:117], v[148:149] op_sel_hi:[1,0]
	v_lshlrev_b64 v[144:145], 1, v[144:145]
	v_pk_mul_f32 v[126:127], v[126:127], v[156:157]
	v_lshl_add_u64 v[146:147], v[146:147], 0, v[144:145]
	v_pk_mul_f32 v[122:123], v[122:123], v[126:127]
	v_pk_mul_f32 v[126:127], v[128:129], v[148:149] op_sel_hi:[1,0]
	s_mov_b64 s[28:29], -1
	v_pk_mul_f32 v[128:129], v[126:127], s[96:97] op_sel_hi:[1,0]
	v_exp_f32_e32 v128, v128
	v_exp_f32_e32 v129, v129
	s_andn2_b64 vcc, exec, s[42:43]
	v_pk_add_f32 v[128:129], v[128:129], 1.0 op_sel_hi:[1,0]
	v_rcp_f32_e32 v128, v128
	v_rcp_f32_e32 v129, v129
	s_nop 0
	v_pk_mul_f32 v[126:127], v[126:127], v[128:129]
	v_pk_mul_f32 v[124:125], v[124:125], v[126:127]
	v_pk_mul_f32 v[126:127], v[118:119], s[96:97] op_sel_hi:[1,0]
	v_exp_f32_e32 v126, v126
	v_exp_f32_e32 v127, v127
	s_nop 0
	v_pk_add_f32 v[126:127], v[126:127], 1.0 op_sel_hi:[1,0]
	v_rcp_f32_e32 v126, v126
	v_rcp_f32_e32 v127, v127
	s_nop 0
	v_pk_mul_f32 v[118:119], v[118:119], v[126:127]
	v_pk_mul_f32 v[118:119], v[114:115], v[118:119]
	v_pk_mul_f32 v[114:115], v[120:121], v[148:149] op_sel_hi:[1,0]
	v_pk_mul_f32 v[120:121], v[114:115], s[96:97] op_sel_hi:[1,0]
	v_exp_f32_e32 v120, v120
	v_exp_f32_e32 v121, v121
	s_nop 0
	v_pk_add_f32 v[120:121], v[120:121], 1.0 op_sel_hi:[1,0]
	v_rcp_f32_e32 v120, v120
	v_rcp_f32_e32 v121, v121
	s_nop 0
	v_pk_mul_f32 v[114:115], v[114:115], v[120:121]
	v_pk_mul_f32 v[120:121], v[116:117], v[114:115]
	v_cvt_pk_bf16_f32 v114, v122, v123
	v_cvt_pk_bf16_f32 v115, v124, v125
	v_cvt_pk_bf16_f32 v116, v118, v119
	v_cvt_pk_bf16_f32 v117, v120, v121
	global_store_dwordx4 v[146:147], v[114:117], off
	s_nop 1
	v_mov_b32_e32 v116, v149
	v_pk_mul_f32 v[110:111], v[110:111], v[116:117] op_sel_hi:[1,0]
	v_or_b32_e32 v114, 16, v154
	v_mul_f32_e32 v117, 0xbfb8aa3b, v110
	v_exp_f32_e32 v117, v117
	v_mad_i64_i32 v[114:115], s[6:7], v114, s86, v[142:143]
	v_lshl_add_u64 v[114:115], v[114:115], 0, v[144:145]
	v_add_f32_e32 v117, 1.0, v117
	v_rcp_f32_e32 v118, v117
	v_pk_mul_f32 v[106:107], v[106:107], v[116:117] op_sel_hi:[1,0]
	v_mul_f32_e32 v117, 0xbfb8aa3b, v111
	v_exp_f32_e32 v117, v117
	s_nop 0
	v_add_f32_e32 v117, 1.0, v117
	v_rcp_f32_e32 v119, v117
	v_pk_mul_f32 v[108:109], v[108:109], v[116:117] op_sel_hi:[1,0]
	v_pk_mul_f32 v[102:103], v[102:103], v[116:117] op_sel_hi:[1,0]
	v_pk_mul_f32 v[98:99], v[98:99], v[116:117] op_sel_hi:[1,0]
	v_pk_mul_f32 v[110:111], v[110:111], v[118:119]
	v_pk_mul_f32 v[100:101], v[100:101], v[116:117] op_sel_hi:[1,0]
	v_pk_mul_f32 v[106:107], v[106:107], v[110:111]
	v_pk_mul_f32 v[110:111], v[112:113], v[116:117] op_sel_hi:[1,0]
	v_pk_mul_f32 v[112:113], v[110:111], s[96:97] op_sel_hi:[1,0]
	v_exp_f32_e32 v112, v112
	v_exp_f32_e32 v113, v113
	s_nop 0
	v_pk_add_f32 v[112:113], v[112:113], 1.0 op_sel_hi:[1,0]
	v_rcp_f32_e32 v112, v112
	v_rcp_f32_e32 v113, v113
	s_nop 0
	v_pk_mul_f32 v[110:111], v[110:111], v[112:113]
	v_pk_mul_f32 v[108:109], v[108:109], v[110:111]
	v_pk_mul_f32 v[110:111], v[102:103], s[96:97] op_sel_hi:[1,0]
	v_exp_f32_e32 v110, v110
	v_exp_f32_e32 v111, v111
	s_nop 0
	v_pk_add_f32 v[110:111], v[110:111], 1.0 op_sel_hi:[1,0]
	v_rcp_f32_e32 v110, v110
	v_rcp_f32_e32 v111, v111
	s_nop 0
	v_pk_mul_f32 v[102:103], v[102:103], v[110:111]
	v_pk_mul_f32 v[102:103], v[98:99], v[102:103]
	v_pk_mul_f32 v[98:99], v[104:105], v[116:117] op_sel_hi:[1,0]
	v_pk_mul_f32 v[104:105], v[98:99], s[96:97] op_sel_hi:[1,0]
	v_exp_f32_e32 v104, v104
	v_exp_f32_e32 v105, v105
	s_nop 0
	v_pk_add_f32 v[104:105], v[104:105], 1.0 op_sel_hi:[1,0]
	v_rcp_f32_e32 v104, v104
	v_rcp_f32_e32 v105, v105
	s_nop 0
	v_pk_mul_f32 v[98:99], v[98:99], v[104:105]
	v_pk_mul_f32 v[104:105], v[100:101], v[98:99]
	v_cvt_pk_bf16_f32 v98, v106, v107
	v_cvt_pk_bf16_f32 v99, v108, v109
	v_cvt_pk_bf16_f32 v100, v102, v103
	v_cvt_pk_bf16_f32 v101, v104, v105
	global_store_dwordx4 v[114:115], v[98:101], off
	ds_read2_b32 v[100:101], v155 offset0:32 offset1:48
	s_waitcnt lgkmcnt(0)
	v_pk_mul_f32 v[94:95], v[94:95], v[100:101] op_sel_hi:[1,0]
	v_pk_mul_f32 v[102:103], v[94:95], s[96:97] op_sel_hi:[1,0]
	v_exp_f32_e32 v102, v102
	v_exp_f32_e32 v103, v103
	v_pk_mul_f32 v[90:91], v[90:91], v[100:101] op_sel_hi:[1,0]
	v_pk_mul_f32 v[92:93], v[92:93], v[100:101] op_sel_hi:[1,0]
	v_pk_add_f32 v[102:103], v[102:103], 1.0 op_sel_hi:[1,0]
	v_rcp_f32_e32 v102, v102
	v_rcp_f32_e32 v103, v103
	v_pk_mul_f32 v[86:87], v[86:87], v[100:101] op_sel_hi:[1,0]
	v_pk_mul_f32 v[82:83], v[82:83], v[100:101] op_sel_hi:[1,0]
	v_or_b32_e32 v98, 32, v154
	v_pk_mul_f32 v[94:95], v[94:95], v[102:103]
	v_pk_mul_f32 v[84:85], v[84:85], v[100:101] op_sel_hi:[1,0]
	v_pk_mul_f32 v[90:91], v[90:91], v[94:95]
	v_pk_mul_f32 v[94:95], v[96:97], v[100:101] op_sel_hi:[1,0]
	v_mad_i64_i32 v[98:99], s[6:7], v98, s86, v[142:143]
	v_pk_mul_f32 v[96:97], v[94:95], s[96:97] op_sel_hi:[1,0]
	v_exp_f32_e32 v96, v96
	v_exp_f32_e32 v97, v97
	v_lshl_add_u64 v[98:99], v[98:99], 0, v[144:145]
	v_pk_add_f32 v[96:97], v[96:97], 1.0 op_sel_hi:[1,0]
	v_rcp_f32_e32 v96, v96
	v_rcp_f32_e32 v97, v97
	s_nop 0
	v_pk_mul_f32 v[94:95], v[94:95], v[96:97]
	v_pk_mul_f32 v[92:93], v[92:93], v[94:95]
	v_pk_mul_f32 v[94:95], v[86:87], s[96:97] op_sel_hi:[1,0]
	v_exp_f32_e32 v94, v94
	v_exp_f32_e32 v95, v95
	s_nop 0
	v_pk_add_f32 v[94:95], v[94:95], 1.0 op_sel_hi:[1,0]
	v_rcp_f32_e32 v94, v94
	v_rcp_f32_e32 v95, v95
	s_nop 0
	v_pk_mul_f32 v[86:87], v[86:87], v[94:95]
	v_pk_mul_f32 v[86:87], v[82:83], v[86:87]
	v_pk_mul_f32 v[82:83], v[88:89], v[100:101] op_sel_hi:[1,0]
	v_pk_mul_f32 v[88:89], v[82:83], s[96:97] op_sel_hi:[1,0]
	v_exp_f32_e32 v88, v88
	v_exp_f32_e32 v89, v89
	s_nop 0
	v_pk_add_f32 v[88:89], v[88:89], 1.0 op_sel_hi:[1,0]
	v_rcp_f32_e32 v88, v88
	v_rcp_f32_e32 v89, v89
	s_nop 0
	v_pk_mul_f32 v[82:83], v[82:83], v[88:89]
	v_pk_mul_f32 v[88:89], v[84:85], v[82:83]
	v_cvt_pk_bf16_f32 v82, v90, v91
	v_cvt_pk_bf16_f32 v83, v92, v93
	v_cvt_pk_bf16_f32 v84, v86, v87
	v_cvt_pk_bf16_f32 v85, v88, v89
	global_store_dwordx4 v[98:99], v[82:85], off
	s_nop 1
	v_mov_b32_e32 v84, v101
	v_pk_mul_f32 v[78:79], v[78:79], v[84:85] op_sel_hi:[1,0]
	v_or_b32_e32 v82, 48, v154
	v_mul_f32_e32 v85, 0xbfb8aa3b, v78
	v_exp_f32_e32 v85, v85
	v_mad_i64_i32 v[82:83], s[6:7], v82, s86, v[142:143]
	v_lshl_add_u64 v[82:83], v[82:83], 0, v[144:145]
	v_add_f32_e32 v85, 1.0, v85
	v_rcp_f32_e32 v86, v85
	v_pk_mul_f32 v[74:75], v[74:75], v[84:85] op_sel_hi:[1,0]
	v_mul_f32_e32 v85, 0xbfb8aa3b, v79
	v_exp_f32_e32 v85, v85
	s_nop 0
	v_add_f32_e32 v85, 1.0, v85
	v_rcp_f32_e32 v87, v85
	v_pk_mul_f32 v[76:77], v[76:77], v[84:85] op_sel_hi:[1,0]
	v_pk_mul_f32 v[70:71], v[70:71], v[84:85] op_sel_hi:[1,0]
	v_pk_mul_f32 v[66:67], v[66:67], v[84:85] op_sel_hi:[1,0]
	v_pk_mul_f32 v[78:79], v[78:79], v[86:87]
	v_pk_mul_f32 v[68:69], v[68:69], v[84:85] op_sel_hi:[1,0]
	v_pk_mul_f32 v[74:75], v[74:75], v[78:79]
	v_pk_mul_f32 v[78:79], v[80:81], v[84:85] op_sel_hi:[1,0]
	v_pk_mul_f32 v[80:81], v[78:79], s[96:97] op_sel_hi:[1,0]
	v_exp_f32_e32 v80, v80
	v_exp_f32_e32 v81, v81
	s_nop 0
	v_pk_add_f32 v[80:81], v[80:81], 1.0 op_sel_hi:[1,0]
	v_rcp_f32_e32 v80, v80
	v_rcp_f32_e32 v81, v81
	s_nop 0
	v_pk_mul_f32 v[78:79], v[78:79], v[80:81]
	v_pk_mul_f32 v[76:77], v[76:77], v[78:79]
	v_pk_mul_f32 v[78:79], v[70:71], s[96:97] op_sel_hi:[1,0]
	v_exp_f32_e32 v78, v78
	v_exp_f32_e32 v79, v79
	s_nop 0
	v_pk_add_f32 v[78:79], v[78:79], 1.0 op_sel_hi:[1,0]
	v_rcp_f32_e32 v78, v78
	v_rcp_f32_e32 v79, v79
	s_nop 0
	v_pk_mul_f32 v[70:71], v[70:71], v[78:79]
	v_pk_mul_f32 v[70:71], v[66:67], v[70:71]
	v_pk_mul_f32 v[66:67], v[72:73], v[84:85] op_sel_hi:[1,0]
	v_pk_mul_f32 v[72:73], v[66:67], s[96:97] op_sel_hi:[1,0]
	v_exp_f32_e32 v72, v72
	v_exp_f32_e32 v73, v73
	s_nop 0
	v_pk_add_f32 v[72:73], v[72:73], 1.0 op_sel_hi:[1,0]
	v_rcp_f32_e32 v72, v72
	v_rcp_f32_e32 v73, v73
	s_nop 0
	v_pk_mul_f32 v[66:67], v[66:67], v[72:73]
	v_pk_mul_f32 v[72:73], v[68:69], v[66:67]
	v_cvt_pk_bf16_f32 v66, v74, v75
	v_cvt_pk_bf16_f32 v67, v76, v77
	v_cvt_pk_bf16_f32 v68, v70, v71
	v_cvt_pk_bf16_f32 v69, v72, v73
	global_store_dwordx4 v[82:83], v[66:69], off
	ds_read2_b32 v[68:69], v155 offset0:128 offset1:144
	s_waitcnt lgkmcnt(0)
	v_pk_mul_f32 v[62:63], v[62:63], v[68:69] op_sel_hi:[1,0]
	v_pk_mul_f32 v[70:71], v[62:63], s[96:97] op_sel_hi:[1,0]
	v_exp_f32_e32 v70, v70
	v_exp_f32_e32 v71, v71
	v_pk_mul_f32 v[58:59], v[58:59], v[68:69] op_sel_hi:[1,0]
	v_pk_mul_f32 v[60:61], v[60:61], v[68:69] op_sel_hi:[1,0]
	v_pk_add_f32 v[70:71], v[70:71], 1.0 op_sel_hi:[1,0]
	v_rcp_f32_e32 v70, v70
	v_rcp_f32_e32 v71, v71
	v_pk_mul_f32 v[54:55], v[54:55], v[68:69] op_sel_hi:[1,0]
	v_pk_mul_f32 v[50:51], v[50:51], v[68:69] op_sel_hi:[1,0]
	v_add_u32_e32 v66, 0x80, v154
	v_pk_mul_f32 v[62:63], v[62:63], v[70:71]
	v_pk_mul_f32 v[52:53], v[52:53], v[68:69] op_sel_hi:[1,0]
	v_pk_mul_f32 v[58:59], v[58:59], v[62:63]
	v_pk_mul_f32 v[62:63], v[64:65], v[68:69] op_sel_hi:[1,0]
	v_mad_i64_i32 v[66:67], s[6:7], v66, s86, v[142:143]
	v_pk_mul_f32 v[64:65], v[62:63], s[96:97] op_sel_hi:[1,0]
	v_exp_f32_e32 v64, v64
	v_exp_f32_e32 v65, v65
	v_lshl_add_u64 v[66:67], v[66:67], 0, v[144:145]
	v_pk_add_f32 v[64:65], v[64:65], 1.0 op_sel_hi:[1,0]
	v_rcp_f32_e32 v64, v64
	v_rcp_f32_e32 v65, v65
	s_nop 0
	v_pk_mul_f32 v[62:63], v[62:63], v[64:65]
	v_pk_mul_f32 v[60:61], v[60:61], v[62:63]
	v_pk_mul_f32 v[62:63], v[54:55], s[96:97] op_sel_hi:[1,0]
	v_exp_f32_e32 v62, v62
	v_exp_f32_e32 v63, v63
	s_nop 0
	v_pk_add_f32 v[62:63], v[62:63], 1.0 op_sel_hi:[1,0]
	v_rcp_f32_e32 v62, v62
	v_rcp_f32_e32 v63, v63
	s_nop 0
	v_pk_mul_f32 v[54:55], v[54:55], v[62:63]
	v_pk_mul_f32 v[54:55], v[50:51], v[54:55]
	v_pk_mul_f32 v[50:51], v[56:57], v[68:69] op_sel_hi:[1,0]
	v_pk_mul_f32 v[56:57], v[50:51], s[96:97] op_sel_hi:[1,0]
	v_exp_f32_e32 v56, v56
	v_exp_f32_e32 v57, v57
	s_nop 0
	v_pk_add_f32 v[56:57], v[56:57], 1.0 op_sel_hi:[1,0]
	v_rcp_f32_e32 v56, v56
	v_rcp_f32_e32 v57, v57
	s_nop 0
	v_pk_mul_f32 v[50:51], v[50:51], v[56:57]
	v_pk_mul_f32 v[56:57], v[52:53], v[50:51]
	v_cvt_pk_bf16_f32 v50, v58, v59
	v_cvt_pk_bf16_f32 v51, v60, v61
	v_cvt_pk_bf16_f32 v52, v54, v55
	v_cvt_pk_bf16_f32 v53, v56, v57
	global_store_dwordx4 v[66:67], v[50:53], off
	s_nop 1
	v_mov_b32_e32 v52, v69
	v_pk_mul_f32 v[46:47], v[46:47], v[52:53] op_sel_hi:[1,0]
	v_add_u32_e32 v50, 0x90, v154
	v_mul_f32_e32 v53, 0xbfb8aa3b, v46
	v_exp_f32_e32 v53, v53
	v_mad_i64_i32 v[50:51], s[6:7], v50, s86, v[142:143]
	v_lshl_add_u64 v[50:51], v[50:51], 0, v[144:145]
	v_add_f32_e32 v53, 1.0, v53
	v_rcp_f32_e32 v54, v53
	v_pk_mul_f32 v[42:43], v[42:43], v[52:53] op_sel_hi:[1,0]
	v_mul_f32_e32 v53, 0xbfb8aa3b, v47
	v_exp_f32_e32 v53, v53
	s_nop 0
	v_add_f32_e32 v53, 1.0, v53
	v_rcp_f32_e32 v55, v53
	v_pk_mul_f32 v[44:45], v[44:45], v[52:53] op_sel_hi:[1,0]
	v_pk_mul_f32 v[38:39], v[38:39], v[52:53] op_sel_hi:[1,0]
	v_pk_mul_f32 v[34:35], v[34:35], v[52:53] op_sel_hi:[1,0]
	v_pk_mul_f32 v[46:47], v[46:47], v[54:55]
	v_pk_mul_f32 v[36:37], v[36:37], v[52:53] op_sel_hi:[1,0]
	v_pk_mul_f32 v[42:43], v[42:43], v[46:47]
	v_pk_mul_f32 v[46:47], v[48:49], v[52:53] op_sel_hi:[1,0]
	v_pk_mul_f32 v[48:49], v[46:47], s[96:97] op_sel_hi:[1,0]
	v_exp_f32_e32 v48, v48
	v_exp_f32_e32 v49, v49
	s_nop 0
	v_pk_add_f32 v[48:49], v[48:49], 1.0 op_sel_hi:[1,0]
	v_rcp_f32_e32 v48, v48
	v_rcp_f32_e32 v49, v49
	s_nop 0
	v_pk_mul_f32 v[46:47], v[46:47], v[48:49]
	v_pk_mul_f32 v[44:45], v[44:45], v[46:47]
	v_pk_mul_f32 v[46:47], v[38:39], s[96:97] op_sel_hi:[1,0]
	v_exp_f32_e32 v46, v46
	v_exp_f32_e32 v47, v47
	s_nop 0
	v_pk_add_f32 v[46:47], v[46:47], 1.0 op_sel_hi:[1,0]
	v_rcp_f32_e32 v46, v46
	v_rcp_f32_e32 v47, v47
	s_nop 0
	v_pk_mul_f32 v[38:39], v[38:39], v[46:47]
	v_pk_mul_f32 v[38:39], v[34:35], v[38:39]
	v_pk_mul_f32 v[34:35], v[40:41], v[52:53] op_sel_hi:[1,0]
	v_pk_mul_f32 v[40:41], v[34:35], s[96:97] op_sel_hi:[1,0]
	v_exp_f32_e32 v40, v40
	v_exp_f32_e32 v41, v41
	s_nop 0
	v_pk_add_f32 v[40:41], v[40:41], 1.0 op_sel_hi:[1,0]
	v_rcp_f32_e32 v40, v40
	v_rcp_f32_e32 v41, v41
	s_nop 0
	v_pk_mul_f32 v[34:35], v[34:35], v[40:41]
	v_pk_mul_f32 v[40:41], v[36:37], v[34:35]
	v_cvt_pk_bf16_f32 v34, v42, v43
	v_cvt_pk_bf16_f32 v35, v44, v45
	v_cvt_pk_bf16_f32 v36, v38, v39
	v_cvt_pk_bf16_f32 v37, v40, v41
	global_store_dwordx4 v[50:51], v[34:37], off
	ds_read2_b32 v[36:37], v155 offset0:160 offset1:176
	s_waitcnt lgkmcnt(0)
	v_pk_mul_f32 v[30:31], v[30:31], v[36:37] op_sel_hi:[1,0]
	v_pk_mul_f32 v[38:39], v[30:31], s[96:97] op_sel_hi:[1,0]
	v_exp_f32_e32 v38, v38
	v_exp_f32_e32 v39, v39
	v_pk_mul_f32 v[26:27], v[26:27], v[36:37] op_sel_hi:[1,0]
	v_pk_mul_f32 v[28:29], v[28:29], v[36:37] op_sel_hi:[1,0]
	v_pk_add_f32 v[38:39], v[38:39], 1.0 op_sel_hi:[1,0]
	v_rcp_f32_e32 v38, v38
	v_rcp_f32_e32 v39, v39
	v_pk_mul_f32 v[22:23], v[22:23], v[36:37] op_sel_hi:[1,0]
	v_pk_mul_f32 v[18:19], v[18:19], v[36:37] op_sel_hi:[1,0]
	v_add_u32_e32 v34, 0xa0, v154
	v_pk_mul_f32 v[30:31], v[30:31], v[38:39]
	v_pk_mul_f32 v[20:21], v[20:21], v[36:37] op_sel_hi:[1,0]
	v_pk_mul_f32 v[26:27], v[26:27], v[30:31]
	v_pk_mul_f32 v[30:31], v[32:33], v[36:37] op_sel_hi:[1,0]
	v_mad_i64_i32 v[34:35], s[6:7], v34, s86, v[142:143]
	v_pk_mul_f32 v[32:33], v[30:31], s[96:97] op_sel_hi:[1,0]
	v_exp_f32_e32 v32, v32
	v_exp_f32_e32 v33, v33
	v_lshl_add_u64 v[34:35], v[34:35], 0, v[144:145]
	v_pk_add_f32 v[32:33], v[32:33], 1.0 op_sel_hi:[1,0]
	v_rcp_f32_e32 v32, v32
	v_rcp_f32_e32 v33, v33
	s_nop 0
	v_pk_mul_f32 v[30:31], v[30:31], v[32:33]
	v_pk_mul_f32 v[28:29], v[28:29], v[30:31]
	v_pk_mul_f32 v[30:31], v[22:23], s[96:97] op_sel_hi:[1,0]
	v_exp_f32_e32 v30, v30
	v_exp_f32_e32 v31, v31
	s_nop 0
	v_pk_add_f32 v[30:31], v[30:31], 1.0 op_sel_hi:[1,0]
	v_rcp_f32_e32 v30, v30
	v_rcp_f32_e32 v31, v31
	s_nop 0
	v_pk_mul_f32 v[22:23], v[22:23], v[30:31]
	v_pk_mul_f32 v[22:23], v[18:19], v[22:23]
	v_pk_mul_f32 v[18:19], v[24:25], v[36:37] op_sel_hi:[1,0]
	v_pk_mul_f32 v[24:25], v[18:19], s[96:97] op_sel_hi:[1,0]
	v_exp_f32_e32 v24, v24
	v_exp_f32_e32 v25, v25
	s_nop 0
	v_pk_add_f32 v[24:25], v[24:25], 1.0 op_sel_hi:[1,0]
	v_rcp_f32_e32 v24, v24
	v_rcp_f32_e32 v25, v25
	s_nop 0
	v_pk_mul_f32 v[18:19], v[18:19], v[24:25]
	v_pk_mul_f32 v[24:25], v[20:21], v[18:19]
	v_cvt_pk_bf16_f32 v18, v26, v27
	v_cvt_pk_bf16_f32 v19, v28, v29
	v_cvt_pk_bf16_f32 v20, v22, v23
	v_cvt_pk_bf16_f32 v21, v24, v25
	global_store_dwordx4 v[34:35], v[18:21], off
	s_nop 1
	v_mov_b32_e32 v20, v37
	v_pk_mul_f32 v[14:15], v[14:15], v[20:21] op_sel_hi:[1,0]
	v_add_u32_e32 v18, 0xb0, v154
	v_mul_f32_e32 v21, 0xbfb8aa3b, v14
	v_exp_f32_e32 v21, v21
	v_mad_i64_i32 v[18:19], s[6:7], v18, s86, v[142:143]
	v_lshl_add_u64 v[18:19], v[18:19], 0, v[144:145]
	v_add_f32_e32 v21, 1.0, v21
	v_rcp_f32_e32 v22, v21
	v_pk_mul_f32 v[10:11], v[10:11], v[20:21] op_sel_hi:[1,0]
	v_mul_f32_e32 v21, 0xbfb8aa3b, v15
	v_exp_f32_e32 v21, v21
	s_nop 0
	v_add_f32_e32 v21, 1.0, v21
	v_rcp_f32_e32 v23, v21
	v_pk_mul_f32 v[12:13], v[12:13], v[20:21] op_sel_hi:[1,0]
	v_pk_mul_f32 v[6:7], v[6:7], v[20:21] op_sel_hi:[1,0]
	v_pk_mul_f32 v[2:3], v[2:3], v[20:21] op_sel_hi:[1,0]
	v_pk_mul_f32 v[14:15], v[14:15], v[22:23]
	v_pk_mul_f32 v[4:5], v[4:5], v[20:21] op_sel_hi:[1,0]
	v_pk_mul_f32 v[10:11], v[10:11], v[14:15]
	v_pk_mul_f32 v[14:15], v[16:17], v[20:21] op_sel_hi:[1,0]
	v_pk_mul_f32 v[16:17], v[14:15], s[96:97] op_sel_hi:[1,0]
	v_exp_f32_e32 v16, v16
	v_exp_f32_e32 v17, v17
	s_nop 0
	v_pk_add_f32 v[16:17], v[16:17], 1.0 op_sel_hi:[1,0]
	v_rcp_f32_e32 v16, v16
	v_rcp_f32_e32 v17, v17
	s_nop 0
	v_pk_mul_f32 v[14:15], v[14:15], v[16:17]
	v_pk_mul_f32 v[12:13], v[12:13], v[14:15]
	v_pk_mul_f32 v[14:15], v[6:7], s[96:97] op_sel_hi:[1,0]
	v_exp_f32_e32 v14, v14
	v_exp_f32_e32 v15, v15
	s_nop 0
	v_pk_add_f32 v[14:15], v[14:15], 1.0 op_sel_hi:[1,0]
	v_rcp_f32_e32 v14, v14
	v_rcp_f32_e32 v15, v15
	s_nop 0
	v_pk_mul_f32 v[6:7], v[6:7], v[14:15]
	v_pk_mul_f32 v[6:7], v[2:3], v[6:7]
	v_pk_mul_f32 v[2:3], v[8:9], v[20:21] op_sel_hi:[1,0]
	v_pk_mul_f32 v[8:9], v[2:3], s[96:97] op_sel_hi:[1,0]
	v_exp_f32_e32 v8, v8
	v_exp_f32_e32 v9, v9
	s_nop 0
	v_pk_add_f32 v[8:9], v[8:9], 1.0 op_sel_hi:[1,0]
	v_rcp_f32_e32 v8, v8
	v_rcp_f32_e32 v9, v9
	s_nop 0
	v_pk_mul_f32 v[2:3], v[2:3], v[8:9]
	v_pk_mul_f32 v[8:9], v[4:5], v[2:3]
	v_cvt_pk_bf16_f32 v2, v10, v11
	v_cvt_pk_bf16_f32 v3, v12, v13
	v_cvt_pk_bf16_f32 v4, v6, v7
	v_cvt_pk_bf16_f32 v5, v8, v9
	global_store_dwordx4 v[18:19], v[2:5], off
	s_cbranch_vccnz .LBB0_46
	s_andn2_b64 vcc, exec, s[44:45]
	s_cbranch_vccnz .LBB0_45
	s_barrier
	s_branch .LBB0_45

.LBB0_216:
	s_and_b64 vcc, exec, s[28:29]
	s_cbranch_vccz .LBB0_236
	s_setprio 2
	v_lshlrev_b32_e32 v3, 2, v1
	v_ashrrev_i32_e32 v33, 7, v1
	s_movk_i32 s6, 0x2080
	v_and_b32_e32 v32, 12, v3
	v_ashrrev_i32_e32 v14, 2, v1
	v_mul_lo_u32 v2, v33, s6
	v_lshlrev_b32_e32 v19, 2, v32
	v_readlane_b32 s6, v253, 51
	v_and_b32_e32 v15, 31, v14
	v_cmp_eq_u32_e32 vcc, v32, v15
	v_add3_u32 v6, s6, v2, v19
	v_mov_b32_e32 v7, v6
	v_cndmask_b32_e64 v12, 0, 1.0, vcc
	v_or_b32_e32 v31, 1, v32
	v_cmp_eq_u32_e32 vcc, v31, v15
	v_or_b32_e32 v30, 2, v32
	ds_read_b128 v[2:5], v7
	ds_read_b128 v[8:11], v7 offset:64
	v_add_u32_e32 v7, 0x100, v6
	v_cndmask_b32_e64 v13, 0, 1.0, vcc
	v_cmp_eq_u32_e32 vcc, v30, v15
	v_or_b32_e32 v29, 3, v32
	v_or_b32_e32 v28, 16, v32
	v_cndmask_b32_e64 v16, 0, 1.0, vcc
	v_cmp_eq_u32_e32 vcc, v29, v15
	s_waitcnt vmcnt(1)
	ds_read_b128 v[98:101], v7
	ds_read_b128 v[102:105], v7 offset:64
	v_add_u32_e32 v7, 0x200, v6
	v_cndmask_b32_e64 v17, 0, 1.0, vcc
	v_cmp_eq_u32_e32 vcc, v28, v15
	v_or_b32_e32 v27, 17, v32
	v_or_b32_e32 v26, 18, v32
	v_cndmask_b32_e64 v22, 0, 1.0, vcc
	v_cmp_eq_u32_e32 vcc, v27, v15
	ds_read_b128 v[106:109], v7
	ds_read_b128 v[110:113], v7 offset:64
	v_cndmask_b32_e64 v23, 0, 1.0, vcc
	v_cmp_eq_u32_e32 vcc, v26, v15
	v_or_b32_e32 v21, 19, v32
	s_nop 0
	v_cndmask_b32_e64 v114, 0, 1.0, vcc
	v_cmp_eq_u32_e32 vcc, v21, v15
	v_mov_b32_dpp v18, v12 quad_perm:[0,0,0,0] row_mask:0xf bank_mask:0xf
	v_add_u32_e32 v7, 0x300, v6
	v_cndmask_b32_e64 v115, 0, 1.0, vcc
	s_waitcnt lgkmcnt(5)
	v_pk_fma_f32 v[12:13], v[2:3], v[18:19], v[12:13] op_sel_hi:[1,0,1] neg_lo:[0,1,0] neg_hi:[0,1,0]
	v_pk_fma_f32 v[16:17], v[4:5], v[18:19], v[16:17] op_sel_hi:[1,0,1] neg_lo:[0,1,0] neg_hi:[0,1,0]
	s_waitcnt lgkmcnt(4)
	v_pk_fma_f32 v[22:23], v[8:9], v[18:19], v[22:23] op_sel_hi:[1,0,1] neg_lo:[0,1,0] neg_hi:[0,1,0]
	v_pk_fma_f32 v[114:115], v[10:11], v[18:19], v[114:115] op_sel_hi:[1,0,1] neg_lo:[0,1,0] neg_hi:[0,1,0]
	ds_read_b128 v[2:5], v7
	ds_read_b128 v[8:11], v7 offset:64
	v_mov_b32_e32 v20, v131
	v_readlane_b32 s6, v253, 52
	v_mov_b32_dpp v18, v13 quad_perm:[0,0,0,0] row_mask:0xf bank_mask:0xf
	v_add_u32_e32 v7, 0x400, v6
	s_waitcnt lgkmcnt(5)
	v_pk_fma_f32 v[16:17], v[100:101], v[18:19], v[16:17] op_sel_hi:[1,0,1] neg_lo:[0,1,0] neg_hi:[0,1,0]
	v_pk_fma_f32 v[12:13], v[98:99], v[18:19], v[12:13] op_sel_hi:[1,0,1] neg_lo:[0,1,0] neg_hi:[0,1,0]
	s_waitcnt lgkmcnt(4)
	v_pk_fma_f32 v[114:115], v[104:105], v[18:19], v[114:115] op_sel_hi:[1,0,1] neg_lo:[0,1,0] neg_hi:[0,1,0]
	v_pk_fma_f32 v[22:23], v[102:103], v[18:19], v[22:23] op_sel_hi:[1,0,1] neg_lo:[0,1,0] neg_hi:[0,1,0]
	ds_read_b128 v[98:101], v7
	ds_read_b128 v[102:105], v7 offset:64
	s_movk_i32 s8, 0x48
	v_cmp_eq_u32_e32 vcc, 1, v33
	v_mov_b32_dpp v18, v16 quad_perm:[0,0,0,0] row_mask:0xf bank_mask:0xf
	v_add_u32_e32 v7, 0x500, v6
	s_waitcnt lgkmcnt(5)
	v_pk_fma_f32 v[16:17], v[108:109], v[18:19], v[16:17] op_sel_hi:[1,0,1] neg_lo:[0,1,0] neg_hi:[0,1,0]
	v_pk_fma_f32 v[12:13], v[106:107], v[18:19], v[12:13] op_sel_hi:[1,0,1] neg_lo:[0,1,0] neg_hi:[0,1,0]
	s_waitcnt lgkmcnt(4)
	v_pk_fma_f32 v[114:115], v[112:113], v[18:19], v[114:115] op_sel_hi:[1,0,1] neg_lo:[0,1,0] neg_hi:[0,1,0]
	v_pk_fma_f32 v[22:23], v[110:111], v[18:19], v[22:23] op_sel_hi:[1,0,1] neg_lo:[0,1,0] neg_hi:[0,1,0]
	ds_read_b128 v[106:109], v7
	ds_read_b128 v[110:113], v7 offset:64
	v_mov_b32_dpp v18, v17 quad_perm:[0,0,0,0] row_mask:0xf bank_mask:0xf
	v_add_u32_e32 v7, 0x600, v6
	s_waitcnt lgkmcnt(5)
	v_pk_fma_f32 v[12:13], v[2:3], v[18:19], v[12:13] op_sel_hi:[1,0,1] neg_lo:[0,1,0] neg_hi:[0,1,0]
	v_pk_fma_f32 v[16:17], v[4:5], v[18:19], v[16:17] op_sel_hi:[1,0,1] neg_lo:[0,1,0] neg_hi:[0,1,0]
	s_waitcnt lgkmcnt(4)
	v_pk_fma_f32 v[114:115], v[10:11], v[18:19], v[114:115] op_sel_hi:[1,0,1] neg_lo:[0,1,0] neg_hi:[0,1,0]
	v_pk_fma_f32 v[22:23], v[8:9], v[18:19], v[22:23] op_sel_hi:[1,0,1] neg_lo:[0,1,0] neg_hi:[0,1,0]
	ds_read_b128 v[2:5], v7
	ds_read_b128 v[8:11], v7 offset:64
	v_mov_b32_dpp v18, v12 quad_perm:[1,1,1,1] row_mask:0xf bank_mask:0xf
	v_add_u32_e32 v7, 0x700, v6
	s_waitcnt lgkmcnt(5)
	v_pk_fma_f32 v[12:13], v[98:99], v[18:19], v[12:13] op_sel_hi:[1,0,1] neg_lo:[0,1,0] neg_hi:[0,1,0]
	v_pk_fma_f32 v[16:17], v[100:101], v[18:19], v[16:17] op_sel_hi:[1,0,1] neg_lo:[0,1,0] neg_hi:[0,1,0]
	s_waitcnt lgkmcnt(4)
	v_pk_fma_f32 v[22:23], v[102:103], v[18:19], v[22:23] op_sel_hi:[1,0,1] neg_lo:[0,1,0] neg_hi:[0,1,0]
	v_pk_fma_f32 v[114:115], v[104:105], v[18:19], v[114:115] op_sel_hi:[1,0,1] neg_lo:[0,1,0] neg_hi:[0,1,0]
	ds_read_b128 v[98:101], v7
	ds_read_b128 v[102:105], v7 offset:64
	v_mov_b32_dpp v18, v13 quad_perm:[1,1,1,1] row_mask:0xf bank_mask:0xf
	v_add_u32_e32 v7, 0x800, v6
	s_waitcnt lgkmcnt(5)
	v_pk_fma_f32 v[16:17], v[108:109], v[18:19], v[16:17] op_sel_hi:[1,0,1] neg_lo:[0,1,0] neg_hi:[0,1,0]
	v_pk_fma_f32 v[12:13], v[106:107], v[18:19], v[12:13] op_sel_hi:[1,0,1] neg_lo:[0,1,0] neg_hi:[0,1,0]
	s_waitcnt lgkmcnt(4)
	v_pk_fma_f32 v[114:115], v[112:113], v[18:19], v[114:115] op_sel_hi:[1,0,1] neg_lo:[0,1,0] neg_hi:[0,1,0]
	v_pk_fma_f32 v[22:23], v[110:111], v[18:19], v[22:23] op_sel_hi:[1,0,1] neg_lo:[0,1,0] neg_hi:[0,1,0]
	ds_read_b128 v[106:109], v7
	ds_read_b128 v[110:113], v7 offset:64
	v_mov_b32_dpp v18, v16 quad_perm:[1,1,1,1] row_mask:0xf bank_mask:0xf
	v_add_u32_e32 v7, 0x900, v6
	s_waitcnt lgkmcnt(5)
	v_pk_fma_f32 v[16:17], v[4:5], v[18:19], v[16:17] op_sel_hi:[1,0,1] neg_lo:[0,1,0] neg_hi:[0,1,0]
	v_pk_fma_f32 v[12:13], v[2:3], v[18:19], v[12:13] op_sel_hi:[1,0,1] neg_lo:[0,1,0] neg_hi:[0,1,0]
	s_waitcnt lgkmcnt(4)
	v_pk_fma_f32 v[22:23], v[8:9], v[18:19], v[22:23] op_sel_hi:[1,0,1] neg_lo:[0,1,0] neg_hi:[0,1,0]
	v_pk_fma_f32 v[114:115], v[10:11], v[18:19], v[114:115] op_sel_hi:[1,0,1] neg_lo:[0,1,0] neg_hi:[0,1,0]
	ds_read_b128 v[2:5], v7
	ds_read_b128 v[8:11], v7 offset:64
	v_mov_b32_dpp v18, v17 quad_perm:[1,1,1,1] row_mask:0xf bank_mask:0xf
	v_add_u32_e32 v7, 0xa00, v6
	s_waitcnt lgkmcnt(5)
	v_pk_fma_f32 v[12:13], v[98:99], v[18:19], v[12:13] op_sel_hi:[1,0,1] neg_lo:[0,1,0] neg_hi:[0,1,0]
	v_pk_fma_f32 v[16:17], v[100:101], v[18:19], v[16:17] op_sel_hi:[1,0,1] neg_lo:[0,1,0] neg_hi:[0,1,0]
	s_waitcnt lgkmcnt(4)
	v_pk_fma_f32 v[114:115], v[104:105], v[18:19], v[114:115] op_sel_hi:[1,0,1] neg_lo:[0,1,0] neg_hi:[0,1,0]
	v_pk_fma_f32 v[22:23], v[102:103], v[18:19], v[22:23] op_sel_hi:[1,0,1] neg_lo:[0,1,0] neg_hi:[0,1,0]
	ds_read_b128 v[98:101], v7
	ds_read_b128 v[102:105], v7 offset:64
	v_mov_b32_dpp v18, v12 quad_perm:[2,2,2,2] row_mask:0xf bank_mask:0xf
	v_add_u32_e32 v7, 0xb00, v6
	s_waitcnt lgkmcnt(5)
	v_pk_fma_f32 v[12:13], v[106:107], v[18:19], v[12:13] op_sel_hi:[1,0,1] neg_lo:[0,1,0] neg_hi:[0,1,0]
	v_pk_fma_f32 v[16:17], v[108:109], v[18:19], v[16:17] op_sel_hi:[1,0,1] neg_lo:[0,1,0] neg_hi:[0,1,0]
	s_waitcnt lgkmcnt(4)
	v_pk_fma_f32 v[22:23], v[110:111], v[18:19], v[22:23] op_sel_hi:[1,0,1] neg_lo:[0,1,0] neg_hi:[0,1,0]
	v_pk_fma_f32 v[114:115], v[112:113], v[18:19], v[114:115] op_sel_hi:[1,0,1] neg_lo:[0,1,0] neg_hi:[0,1,0]
	ds_read_b128 v[106:109], v7
	ds_read_b128 v[110:113], v7 offset:64
	v_mov_b32_dpp v18, v13 quad_perm:[2,2,2,2] row_mask:0xf bank_mask:0xf
	v_add_u32_e32 v7, 0xc00, v6
	s_waitcnt lgkmcnt(5)
	v_pk_fma_f32 v[16:17], v[4:5], v[18:19], v[16:17] op_sel_hi:[1,0,1] neg_lo:[0,1,0] neg_hi:[0,1,0]
	v_pk_fma_f32 v[12:13], v[2:3], v[18:19], v[12:13] op_sel_hi:[1,0,1] neg_lo:[0,1,0] neg_hi:[0,1,0]
	s_waitcnt lgkmcnt(4)
	v_pk_fma_f32 v[114:115], v[10:11], v[18:19], v[114:115] op_sel_hi:[1,0,1] neg_lo:[0,1,0] neg_hi:[0,1,0]
	v_pk_fma_f32 v[22:23], v[8:9], v[18:19], v[22:23] op_sel_hi:[1,0,1] neg_lo:[0,1,0] neg_hi:[0,1,0]
	ds_read_b128 v[2:5], v7
	ds_read_b128 v[8:11], v7 offset:64
	v_mov_b32_dpp v18, v16 quad_perm:[2,2,2,2] row_mask:0xf bank_mask:0xf
	v_add_u32_e32 v7, 0xd00, v6
	s_waitcnt lgkmcnt(5)
	v_pk_fma_f32 v[16:17], v[100:101], v[18:19], v[16:17] op_sel_hi:[1,0,1] neg_lo:[0,1,0] neg_hi:[0,1,0]
	v_pk_fma_f32 v[12:13], v[98:99], v[18:19], v[12:13] op_sel_hi:[1,0,1] neg_lo:[0,1,0] neg_hi:[0,1,0]
	s_waitcnt lgkmcnt(4)
	v_pk_fma_f32 v[22:23], v[102:103], v[18:19], v[22:23] op_sel_hi:[1,0,1] neg_lo:[0,1,0] neg_hi:[0,1,0]
	v_pk_fma_f32 v[114:115], v[104:105], v[18:19], v[114:115] op_sel_hi:[1,0,1] neg_lo:[0,1,0] neg_hi:[0,1,0]
	ds_read_b128 v[98:101], v7
	ds_read_b128 v[102:105], v7 offset:64
	v_mov_b32_dpp v18, v17 quad_perm:[2,2,2,2] row_mask:0xf bank_mask:0xf
	v_add_u32_e32 v7, 0xe00, v6
	s_waitcnt lgkmcnt(5)
	v_pk_fma_f32 v[12:13], v[106:107], v[18:19], v[12:13] op_sel_hi:[1,0,1] neg_lo:[0,1,0] neg_hi:[0,1,0]
	v_pk_fma_f32 v[16:17], v[108:109], v[18:19], v[16:17] op_sel_hi:[1,0,1] neg_lo:[0,1,0] neg_hi:[0,1,0]
	s_waitcnt lgkmcnt(4)
	v_pk_fma_f32 v[114:115], v[112:113], v[18:19], v[114:115] op_sel_hi:[1,0,1] neg_lo:[0,1,0] neg_hi:[0,1,0]
	v_pk_fma_f32 v[22:23], v[110:111], v[18:19], v[22:23] op_sel_hi:[1,0,1] neg_lo:[0,1,0] neg_hi:[0,1,0]
	ds_read_b128 v[106:109], v7
	ds_read_b128 v[110:113], v7 offset:64
	v_mov_b32_dpp v18, v12 quad_perm:[3,3,3,3] row_mask:0xf bank_mask:0xf
	v_add_u32_e32 v7, 0xf00, v6
	s_waitcnt lgkmcnt(5)
	v_pk_fma_f32 v[12:13], v[2:3], v[18:19], v[12:13] op_sel_hi:[1,0,1] neg_lo:[0,1,0] neg_hi:[0,1,0]
	v_pk_fma_f32 v[16:17], v[4:5], v[18:19], v[16:17] op_sel_hi:[1,0,1] neg_lo:[0,1,0] neg_hi:[0,1,0]
	s_waitcnt lgkmcnt(4)
	v_pk_fma_f32 v[22:23], v[8:9], v[18:19], v[22:23] op_sel_hi:[1,0,1] neg_lo:[0,1,0] neg_hi:[0,1,0]
	v_pk_fma_f32 v[114:115], v[10:11], v[18:19], v[114:115] op_sel_hi:[1,0,1] neg_lo:[0,1,0] neg_hi:[0,1,0]
	ds_read_b128 v[2:5], v7
	ds_read_b128 v[8:11], v7 offset:64
	v_mov_b32_dpp v18, v13 quad_perm:[3,3,3,3] row_mask:0xf bank_mask:0xf
	v_add_u32_e32 v7, 0x1000, v6
	s_waitcnt lgkmcnt(5)
	v_pk_fma_f32 v[16:17], v[100:101], v[18:19], v[16:17] op_sel_hi:[1,0,1] neg_lo:[0,1,0] neg_hi:[0,1,0]
	v_pk_fma_f32 v[12:13], v[98:99], v[18:19], v[12:13] op_sel_hi:[1,0,1] neg_lo:[0,1,0] neg_hi:[0,1,0]
	s_waitcnt lgkmcnt(4)
	v_pk_fma_f32 v[104:105], v[104:105], v[18:19], v[114:115] op_sel_hi:[1,0,1] neg_lo:[0,1,0] neg_hi:[0,1,0]
	ds_read_b128 v[98:101], v7 offset:64
	v_pk_fma_f32 v[22:23], v[102:103], v[18:19], v[22:23] op_sel_hi:[1,0,1] neg_lo:[0,1,0] neg_hi:[0,1,0]
	v_mov_b32_dpp v18, v16 quad_perm:[3,3,3,3] row_mask:0xf bank_mask:0xf
	v_add_u32_e32 v7, 0x1100, v6
	s_waitcnt lgkmcnt(4)
	v_pk_fma_f32 v[16:17], v[108:109], v[18:19], v[16:17] op_sel_hi:[1,0,1] neg_lo:[0,1,0] neg_hi:[0,1,0]
	v_pk_fma_f32 v[114:115], v[106:107], v[18:19], v[12:13] op_sel_hi:[1,0,1] neg_lo:[0,1,0] neg_hi:[0,1,0]
	s_waitcnt lgkmcnt(3)
	v_pk_fma_f32 v[12:13], v[110:111], v[18:19], v[22:23] op_sel_hi:[1,0,1] neg_lo:[0,1,0] neg_hi:[0,1,0]
	v_pk_fma_f32 v[22:23], v[112:113], v[18:19], v[104:105] op_sel_hi:[1,0,1] neg_lo:[0,1,0] neg_hi:[0,1,0]
	ds_read_b128 v[102:105], v7 offset:64
	v_mov_b32_dpp v18, v17 quad_perm:[3,3,3,3] row_mask:0xf bank_mask:0xf
	v_add_u32_e32 v7, 0x1200, v6
	s_waitcnt lgkmcnt(2)
	v_pk_fma_f32 v[12:13], v[8:9], v[18:19], v[12:13] op_sel_hi:[1,0,1] neg_lo:[0,1,0] neg_hi:[0,1,0]
	v_pk_fma_f32 v[22:23], v[10:11], v[18:19], v[22:23] op_sel_hi:[1,0,1] neg_lo:[0,1,0] neg_hi:[0,1,0]
	ds_read_b128 v[8:11], v7 offset:64
	v_mov_b32_e32 v7, v12
	v_pk_fma_f32 v[2:3], v[2:3], v[18:19], v[114:115] op_sel_hi:[1,0,1] neg_lo:[0,1,0] neg_hi:[0,1,0]
	s_nop 0
	v_mov_b32_dpp v20, v7 quad_perm:[0,0,0,0] row_mask:0xf bank_mask:0xf
	v_add_u32_e32 v7, 0x1300, v6
	s_waitcnt lgkmcnt(2)
	v_pk_fma_f32 v[12:13], v[98:99], v[20:21], v[12:13] op_sel_hi:[1,0,1] neg_lo:[0,1,0] neg_hi:[0,1,0]
	v_pk_fma_f32 v[22:23], v[100:101], v[20:21], v[22:23] op_sel_hi:[1,0,1] neg_lo:[0,1,0] neg_hi:[0,1,0]
	ds_read_b128 v[98:101], v7 offset:64
	v_mov_b32_dpp v20, v13 quad_perm:[0,0,0,0] row_mask:0xf bank_mask:0xf
	v_add_u32_e32 v7, 0x1400, v6
	s_waitcnt lgkmcnt(2)
	v_pk_fma_f32 v[22:23], v[104:105], v[20:21], v[22:23] op_sel_hi:[1,0,1] neg_lo:[0,1,0] neg_hi:[0,1,0]
	v_pk_fma_f32 v[12:13], v[102:103], v[20:21], v[12:13] op_sel_hi:[1,0,1] neg_lo:[0,1,0] neg_hi:[0,1,0]
	v_mov_b32_e32 v20, v131
	ds_read_b128 v[102:105], v7 offset:64
	v_mov_b32_e32 v7, v22
	s_nop 1
	v_mov_b32_dpp v20, v7 quad_perm:[0,0,0,0] row_mask:0xf bank_mask:0xf
	v_add_u32_e32 v7, 0x1500, v6
	s_waitcnt lgkmcnt(2)
	v_pk_fma_f32 v[22:23], v[10:11], v[20:21], v[22:23] op_sel_hi:[1,0,1] neg_lo:[0,1,0] neg_hi:[0,1,0]
	v_pk_fma_f32 v[12:13], v[8:9], v[20:21], v[12:13] op_sel_hi:[1,0,1] neg_lo:[0,1,0] neg_hi:[0,1,0]
	v_mov_b32_e32 v20, v131
	ds_read_b128 v[8:11], v7 offset:64
	v_mov_b32_e32 v7, v23
	s_nop 1
	v_mov_b32_dpp v20, v7 quad_perm:[0,0,0,0] row_mask:0xf bank_mask:0xf
	v_add_u32_e32 v7, 0x1600, v6
	s_waitcnt lgkmcnt(2)
	v_pk_fma_f32 v[12:13], v[98:99], v[20:21], v[12:13] op_sel_hi:[1,0,1] neg_lo:[0,1,0] neg_hi:[0,1,0]
	v_pk_fma_f32 v[22:23], v[100:101], v[20:21], v[22:23] op_sel_hi:[1,0,1] neg_lo:[0,1,0] neg_hi:[0,1,0]
	ds_read_b128 v[98:101], v7 offset:64
	v_mov_b32_dpp v20, v12 quad_perm:[1,1,1,1] row_mask:0xf bank_mask:0xf
	v_add_u32_e32 v7, 0x1700, v6
	s_waitcnt lgkmcnt(2)
	v_pk_fma_f32 v[12:13], v[102:103], v[20:21], v[12:13] op_sel_hi:[1,0,1] neg_lo:[0,1,0] neg_hi:[0,1,0]
	v_pk_fma_f32 v[22:23], v[104:105], v[20:21], v[22:23] op_sel_hi:[1,0,1] neg_lo:[0,1,0] neg_hi:[0,1,0]
	ds_read_b128 v[102:105], v7 offset:64
	v_mov_b32_dpp v20, v13 quad_perm:[1,1,1,1] row_mask:0xf bank_mask:0xf
	v_add_u32_e32 v7, 0x1800, v6
	s_waitcnt lgkmcnt(2)
	v_pk_fma_f32 v[22:23], v[10:11], v[20:21], v[22:23] op_sel_hi:[1,0,1] neg_lo:[0,1,0] neg_hi:[0,1,0]
	v_pk_fma_f32 v[12:13], v[8:9], v[20:21], v[12:13] op_sel_hi:[1,0,1] neg_lo:[0,1,0] neg_hi:[0,1,0]
	v_mov_b32_e32 v20, v131
	ds_read_b128 v[8:11], v7 offset:64
	v_mov_b32_e32 v7, v22
	s_nop 1
	v_mov_b32_dpp v20, v7 quad_perm:[1,1,1,1] row_mask:0xf bank_mask:0xf
	v_add_u32_e32 v7, 0x1900, v6
	s_waitcnt lgkmcnt(2)
	v_pk_fma_f32 v[22:23], v[100:101], v[20:21], v[22:23] op_sel_hi:[1,0,1] neg_lo:[0,1,0] neg_hi:[0,1,0]
	v_pk_fma_f32 v[12:13], v[98:99], v[20:21], v[12:13] op_sel_hi:[1,0,1] neg_lo:[0,1,0] neg_hi:[0,1,0]
	v_mov_b32_e32 v20, v131
	ds_read_b128 v[98:101], v7 offset:64
	v_mov_b32_e32 v7, v23
	s_nop 1
	v_mov_b32_dpp v20, v7 quad_perm:[1,1,1,1] row_mask:0xf bank_mask:0xf
	v_add_u32_e32 v7, 0x1a00, v6
	s_waitcnt lgkmcnt(2)
	v_pk_fma_f32 v[12:13], v[102:103], v[20:21], v[12:13] op_sel_hi:[1,0,1] neg_lo:[0,1,0] neg_hi:[0,1,0]
	v_pk_fma_f32 v[22:23], v[104:105], v[20:21], v[22:23] op_sel_hi:[1,0,1] neg_lo:[0,1,0] neg_hi:[0,1,0]
	ds_read_b128 v[102:105], v7 offset:64
	v_mov_b32_dpp v20, v12 quad_perm:[2,2,2,2] row_mask:0xf bank_mask:0xf
	v_add_u32_e32 v7, 0x1b00, v6
	s_waitcnt lgkmcnt(2)
	v_pk_fma_f32 v[8:9], v[8:9], v[20:21], v[12:13] op_sel_hi:[1,0,1] neg_lo:[0,1,0] neg_hi:[0,1,0]
	v_mov_b32_e32 v12, v131
	ds_read_b128 v[106:109], v7 offset:64
	v_mov_b32_e32 v7, v9
	v_pk_fma_f32 v[10:11], v[10:11], v[20:21], v[22:23] op_sel_hi:[1,0,1] neg_lo:[0,1,0] neg_hi:[0,1,0]
	v_mov_b32_e32 v20, v131
	v_mov_b32_dpp v12, v7 quad_perm:[2,2,2,2] row_mask:0xf bank_mask:0xf
	v_add_u32_e32 v7, 0x1c00, v6
	s_waitcnt lgkmcnt(2)
	v_pk_fma_f32 v[10:11], v[100:101], v[12:13], v[10:11] op_sel_hi:[1,0,1] neg_lo:[0,1,0] neg_hi:[0,1,0]
	v_pk_fma_f32 v[8:9], v[98:99], v[12:13], v[8:9] op_sel_hi:[1,0,1] neg_lo:[0,1,0] neg_hi:[0,1,0]
	v_mov_b32_e32 v12, v131
	ds_read_b128 v[98:101], v7 offset:64
	v_mov_b32_e32 v7, v10
	s_nop 1
	v_mov_b32_dpp v12, v7 quad_perm:[2,2,2,2] row_mask:0xf bank_mask:0xf
	v_add_u32_e32 v7, 0x1d00, v6
	s_waitcnt lgkmcnt(2)
	v_pk_fma_f32 v[22:23], v[104:105], v[12:13], v[10:11] op_sel_hi:[1,0,1] neg_lo:[0,1,0] neg_hi:[0,1,0]
	v_pk_fma_f32 v[8:9], v[102:103], v[12:13], v[8:9] op_sel_hi:[1,0,1] neg_lo:[0,1,0] neg_hi:[0,1,0]
	v_add_u32_e32 v6, 0x1e00, v6
	ds_read_b128 v[10:13], v7 offset:64
	v_mov_b32_e32 v7, v23
	s_nop 1
	v_mov_b32_dpp v20, v7 quad_perm:[2,2,2,2] row_mask:0xf bank_mask:0xf
	s_waitcnt lgkmcnt(2)
	v_pk_fma_f32 v[102:103], v[106:107], v[20:21], v[8:9] op_sel_hi:[1,0,1] neg_lo:[0,1,0] neg_hi:[0,1,0]
	v_pk_fma_f32 v[22:23], v[108:109], v[20:21], v[22:23] op_sel_hi:[1,0,1] neg_lo:[0,1,0] neg_hi:[0,1,0]
	ds_read_b128 v[6:9], v6 offset:64
	v_mov_b32_dpp v20, v102 quad_perm:[3,3,3,3] row_mask:0xf bank_mask:0xf
	s_waitcnt lgkmcnt(2)
	v_pk_fma_f32 v[100:101], v[100:101], v[20:21], v[22:23] op_sel_hi:[1,0,1] neg_lo:[0,1,0] neg_hi:[0,1,0]
	v_pk_fma_f32 v[22:23], v[98:99], v[20:21], v[102:103] op_sel_hi:[1,0,1] neg_lo:[0,1,0] neg_hi:[0,1,0]
	v_mov_b32_e32 v24, v131
	v_mov_b32_e32 v20, v23
	v_lshlrev_b32_e32 v98, 5, v33
	v_lshl_add_u32 v33, v15, 2, s6
	v_mov_b32_dpp v24, v20 quad_perm:[3,3,3,3] row_mask:0xf bank_mask:0xf
	v_and_b32_e32 v20, -4, v1
	s_waitcnt lgkmcnt(1)
	v_pk_fma_f32 v[12:13], v[12:13], v[24:25], v[100:101] op_sel_hi:[1,0,1] neg_lo:[0,1,0] neg_hi:[0,1,0]
	v_add_u32_e32 v20, 0, v20
	v_mov_b32_e32 v93, v12
	s_waitcnt vmcnt(0)
	v_add_u32_e32 v97, 0x24a00, v20
	v_add_u32_e32 v20, 0x24b00, v20
	ds_read_b32 v97, v97
	ds_read_b32 v99, v20
	v_mov_b32_e32 v20, 0
	s_waitcnt lgkmcnt(1)
	v_mul_f32_e32 v100, v2, v97
	v_mov_b32_dpp v20, v93 quad_perm:[3,3,3,3] row_mask:0xf bank_mask:0xf
	s_waitcnt lgkmcnt(0)
	v_mul_f32_e32 v93, v97, v99
	v_or_b32_e32 v99, v32, v98
	v_cvt_pk_bf16_f32 v102, v100, s0
	v_mad_u64_u32 v[100:101], s[6:7], v99, s8, v[14:15]
	v_lshl_add_u32 v99, v100, 1, 0
	v_add_u32_e32 v100, 0x18000, v99
	ds_write_b16 v100, v102
	v_mul_f32_e32 v100, v2, v93
	v_cvt_pk_bf16_f32 v100, v100, s0
	v_add_u32_e32 v99, 0x1a400, v99
	ds_write_b16 v99, v100
	s_and_saveexec_b64 s[28:29], vcc
	s_cbranch_execz .LBB0_219
	v_mad_u32_u24 v99, v32, s8, v14
	v_lshl_add_u32 v99, v99, 1, 0
	s_movk_i32 s6, 0x90
	v_add_u32_e32 v100, 0x18000, v99
	v_add_u32_e32 v99, 0x1a400, v99
	v_mad_u32_u24 v32, v32, s6, v33
	ds_write_b16 v100, v131
	ds_write_b16 v99, v131
	ds_write_b32 v32, v2

.LBB0_257:
	s_add_i32 s7, s50, s54
	s_add_i32 s8, s51, s54
	s_cmpk_lt_i32 s8, 0x200
	s_cselect_b32 s7, s8, s7
	s_lshl_b32 s7, s7, 6
	s_and_b32 s8, s7, 0xfc0
	s_sub_i32 s10, s8, 30
	s_add_i32 s8, s10, s49
	s_and_b32 s7, s7, 0xfffff000
	s_max_i32 s8, s8, 0
	s_add_i32 s8, s8, s7
	v_and_b32_e32 v14, 0xff, v10
	v_mad_i64_i32 v[10:11], s[8:9], s8, v238, v[42:43]
	s_add_i32 s8, s10, s48
	s_max_i32 s8, s8, 0
	s_add_i32 s8, s8, s7
	v_mad_i64_i32 v[12:13], s[8:9], s8, v238, v[42:43]
	s_add_i32 s8, s10, s47
	s_max_i32 s8, s8, 0
	s_add_i32 s8, s8, s7
	s_waitcnt lgkmcnt(0)
	s_barrier
	global_load_dwordx2 v[152:153], v[10:11], off offset:1024
	global_load_dwordx2 v[154:155], v[10:11], off offset:1536
	global_load_dwordx2 v[148:149], v[12:13], off offset:1024
	global_load_dwordx2 v[150:151], v[12:13], off offset:1536
	v_mad_i64_i32 v[10:11], s[8:9], s8, v238, v[42:43]
	s_add_i32 s8, s10, s46
	s_max_i32 s8, s8, 0
	s_add_i32 s8, s8, s7
	v_mad_i64_i32 v[12:13], s[8:9], s8, v238, v[42:43]
	s_add_i32 s8, s10, s45
	s_max_i32 s8, s8, 0
	s_add_i32 s8, s8, s7
	global_load_dwordx2 v[144:145], v[10:11], off offset:1024
	global_load_dwordx2 v[146:147], v[10:11], off offset:1536
	global_load_dwordx2 v[140:141], v[12:13], off offset:1024
	global_load_dwordx2 v[142:143], v[12:13], off offset:1536
	v_mad_i64_i32 v[10:11], s[8:9], s8, v238, v[42:43]
	s_add_i32 s8, s10, s44
	s_max_i32 s8, s8, 0
	s_add_i32 s8, s8, s7
	v_mad_i64_i32 v[12:13], s[8:9], s8, v238, v[42:43]
	s_add_i32 s8, s10, s43
	s_max_i32 s8, s8, 0
	s_add_i32 s8, s8, s7
	global_load_dwordx2 v[136:137], v[10:11], off offset:1024
	global_load_dwordx2 v[138:139], v[10:11], off offset:1536
	global_load_dwordx2 v[132:133], v[12:13], off offset:1024
	global_load_dwordx2 v[134:135], v[12:13], off offset:1536
	v_mad_i64_i32 v[10:11], s[8:9], s8, v238, v[42:43]
	s_add_i32 s8, s10, s42
	s_max_i32 s8, s8, 0
	s_add_i32 s8, s8, s7
	v_mad_i64_i32 v[12:13], s[8:9], s8, v238, v[42:43]
	s_add_i32 s8, s10, s41
	s_max_i32 s8, s8, 0
	s_add_i32 s8, s8, s7
	global_load_dwordx2 v[126:127], v[10:11], off offset:1024
	global_load_dwordx2 v[128:129], v[10:11], off offset:1536
	global_load_dwordx2 v[122:123], v[12:13], off offset:1024
	global_load_dwordx2 v[124:125], v[12:13], off offset:1536
	v_mad_i64_i32 v[10:11], s[8:9], s8, v238, v[42:43]
	s_add_i32 s8, s10, s40
	s_max_i32 s8, s8, 0
	s_add_i32 s8, s8, s7
	v_mad_i64_i32 v[12:13], s[8:9], s8, v238, v[42:43]
	s_add_i32 s8, s10, s34
	s_max_i32 s8, s8, 0
	s_add_i32 s8, s8, s7
	global_load_dwordx2 v[118:119], v[10:11], off offset:1024
	global_load_dwordx2 v[120:121], v[10:11], off offset:1536
	global_load_dwordx2 v[114:115], v[12:13], off offset:1024
	global_load_dwordx2 v[116:117], v[12:13], off offset:1536
	v_mad_i64_i32 v[10:11], s[8:9], s8, v238, v[42:43]
	s_add_i32 s10, s10, s5
	s_lshl_b32 s6, s6, 7
	s_max_i32 s8, s10, 0
	s_and_b32 s6, s6, 0xffff8000
	s_add_i32 s8, s8, s7
	s_add_i32 s6, s6, 0
	v_mad_i64_i32 v[12:13], s[8:9], s8, v238, v[42:43]
	v_lshl_add_u32 v163, v14, 2, s6
	global_load_dwordx2 v[110:111], v[10:11], off offset:1024
	global_load_dwordx2 v[112:113], v[10:11], off offset:1536
	global_load_dwordx2 v[106:107], v[12:13], off offset:1024
	global_load_dwordx2 v[108:109], v[12:13], off offset:1536
	ds_read2st64_b32 v[26:27], v163 offset1:4
	ds_read2st64_b32 v[28:29], v163 offset0:8 offset1:12
	ds_read2st64_b32 v[30:31], v163 offset0:16 offset1:20
	ds_read2st64_b32 v[32:33], v163 offset0:24 offset1:28
	ds_read2st64_b32 v[160:161], v163 offset0:32 offset1:36
	ds_read2st64_b32 v[158:159], v163 offset0:40 offset1:44
	ds_read2st64_b32 v[156:157], v163 offset0:48 offset1:52
	ds_read2st64_b32 v[40:41], v163 offset0:56 offset1:60
	ds_read2st64_b32 v[38:39], v163 offset0:64 offset1:68
	ds_read2st64_b32 v[36:37], v163 offset0:72 offset1:76
	ds_read2st64_b32 v[34:35], v163 offset0:80 offset1:84
	ds_read2st64_b32 v[24:25], v163 offset0:88 offset1:92
	ds_read2st64_b32 v[22:23], v163 offset0:96 offset1:100
	ds_read2st64_b32 v[20:21], v163 offset0:104 offset1:108
	ds_read2st64_b32 v[10:11], v163 offset0:120 offset1:124
	ds_read2st64_b32 v[18:19], v163 offset0:112 offset1:116
	ds_read2st64_b32 v[12:13], v163 offset0:128 offset1:132
	ds_read2st64_b32 v[14:15], v163 offset0:136 offset1:140
	ds_read2st64_b32 v[16:17], v163 offset0:144 offset1:148
	s_waitcnt vmcnt(49) lgkmcnt(4)
	v_mul_f32_e32 v105, v103, v10
	v_mul_f32_e32 v165, v44, v27
	s_waitcnt vmcnt(24)
	v_mov_b32_e32 v164, v104
	v_pk_fma_f32 v[26:27], v[44:45], v[26:27], v[104:105]
	v_pk_fma_f32 v[164:165], v[46:47], v[28:29], v[164:165]
	v_pk_fma_f32 v[26:27], v[48:49], v[28:29], v[26:27]
	v_pk_fma_f32 v[164:165], v[50:51], v[30:31], v[164:165]
	v_pk_fma_f32 v[26:27], v[52:53], v[30:31], v[26:27]
	v_pk_fma_f32 v[164:165], v[54:55], v[32:33], v[164:165]
	v_pk_fma_f32 v[26:27], v[56:57], v[32:33], v[26:27]
	v_pk_fma_f32 v[164:165], v[58:59], v[160:161], v[164:165]
	v_pk_fma_f32 v[26:27], v[60:61], v[160:161], v[26:27]
	v_pk_fma_f32 v[164:165], v[62:63], v[158:159], v[164:165]
	v_pk_fma_f32 v[26:27], v[64:65], v[158:159], v[26:27]
	v_pk_fma_f32 v[164:165], v[66:67], v[156:157], v[164:165]
	v_pk_fma_f32 v[26:27], v[68:69], v[156:157], v[26:27]
	v_pk_fma_f32 v[164:165], v[70:71], v[40:41], v[164:165]
	v_pk_fma_f32 v[26:27], v[72:73], v[40:41], v[26:27]
	v_pk_fma_f32 v[164:165], v[74:75], v[38:39], v[164:165]
	v_pk_fma_f32 v[26:27], v[76:77], v[38:39], v[26:27]
	v_pk_fma_f32 v[164:165], v[78:79], v[36:37], v[164:165]
	v_pk_fma_f32 v[26:27], v[80:81], v[36:37], v[26:27]
	v_pk_fma_f32 v[164:165], v[82:83], v[34:35], v[164:165]
	v_pk_fma_f32 v[26:27], v[84:85], v[34:35], v[26:27]
	v_pk_fma_f32 v[164:165], v[86:87], v[24:25], v[164:165]
	v_pk_fma_f32 v[26:27], v[88:89], v[24:25], v[26:27]
	v_pk_fma_f32 v[164:165], v[90:91], v[22:23], v[164:165]
	v_pk_fma_f32 v[26:27], v[92:93], v[22:23], v[26:27]
	v_pk_fma_f32 v[164:165], v[94:95], v[20:21], v[164:165]
	v_pk_fma_f32 v[26:27], v[96:97], v[20:21], v[26:27]
	s_waitcnt lgkmcnt(3)
	v_pk_fma_f32 v[164:165], v[98:99], v[18:19], v[164:165]
	v_pk_fma_f32 v[26:27], v[100:101], v[18:19], v[26:27]
	v_pk_fma_f32 v[166:167], v[102:103], v[10:11], v[164:165]
	v_add_f32_e32 v164, v26, v27
	v_mul_f32_e32 v27, v44, v29
	v_mov_b32_e32 v26, v104
	v_pk_fma_f32 v[26:27], v[46:47], v[30:31], v[26:27]
	v_add_f32_e32 v165, v166, v167
	v_pk_fma_f32 v[26:27], v[50:51], v[32:33], v[26:27]
	s_waitcnt lgkmcnt(2)
	v_mul_f32_e32 v105, v103, v12
	v_pk_fma_f32 v[26:27], v[54:55], v[160:161], v[26:27]
	v_pk_fma_f32 v[28:29], v[44:45], v[28:29], v[104:105]
	v_pk_fma_f32 v[26:27], v[58:59], v[158:159], v[26:27]
	v_pk_fma_f32 v[28:29], v[48:49], v[30:31], v[28:29]
	v_pk_fma_f32 v[26:27], v[62:63], v[156:157], v[26:27]
	v_pk_fma_f32 v[28:29], v[52:53], v[32:33], v[28:29]
	v_pk_fma_f32 v[26:27], v[66:67], v[40:41], v[26:27]
	v_pk_fma_f32 v[28:29], v[56:57], v[160:161], v[28:29]
	v_pk_fma_f32 v[26:27], v[70:71], v[38:39], v[26:27]
	v_pk_fma_f32 v[28:29], v[60:61], v[158:159], v[28:29]
	v_pk_fma_f32 v[26:27], v[74:75], v[36:37], v[26:27]
	v_pk_fma_f32 v[28:29], v[64:65], v[156:157], v[28:29]
	v_pk_fma_f32 v[26:27], v[78:79], v[34:35], v[26:27]
	v_pk_fma_f32 v[28:29], v[68:69], v[40:41], v[28:29]
	v_pk_fma_f32 v[26:27], v[82:83], v[24:25], v[26:27]
	v_pk_fma_f32 v[28:29], v[72:73], v[38:39], v[28:29]
	v_pk_fma_f32 v[26:27], v[86:87], v[22:23], v[26:27]
	v_pk_fma_f32 v[28:29], v[76:77], v[36:37], v[28:29]
	v_pk_fma_f32 v[26:27], v[90:91], v[20:21], v[26:27]
	v_pk_fma_f32 v[28:29], v[80:81], v[34:35], v[28:29]
	v_pk_fma_f32 v[26:27], v[94:95], v[18:19], v[26:27]
	v_pk_fma_f32 v[28:29], v[84:85], v[24:25], v[28:29]
	v_pk_fma_f32 v[26:27], v[98:99], v[10:11], v[26:27]
	v_pk_fma_f32 v[28:29], v[88:89], v[22:23], v[28:29]
	v_pk_fma_f32 v[26:27], v[102:103], v[12:13], v[26:27]
	v_pk_fma_f32 v[28:29], v[92:93], v[20:21], v[28:29]
	v_add_f32_e32 v167, v26, v27
	v_mul_f32_e32 v27, v44, v31
	v_mov_b32_e32 v26, v104
	v_pk_fma_f32 v[26:27], v[46:47], v[32:33], v[26:27]
	v_pk_fma_f32 v[28:29], v[96:97], v[18:19], v[28:29]
	v_pk_fma_f32 v[26:27], v[50:51], v[160:161], v[26:27]
	v_pk_fma_f32 v[28:29], v[100:101], v[10:11], v[28:29]
	v_pk_fma_f32 v[26:27], v[54:55], v[158:159], v[26:27]
	s_waitcnt lgkmcnt(1)
	v_mul_f32_e32 v105, v103, v14
	v_pk_fma_f32 v[26:27], v[58:59], v[156:157], v[26:27]
	v_add_f32_e32 v166, v28, v29
	v_pk_fma_f32 v[26:27], v[62:63], v[40:41], v[26:27]
	v_pk_fma_f32 v[28:29], v[44:45], v[30:31], v[104:105]
	v_pk_fma_f32 v[26:27], v[66:67], v[38:39], v[26:27]
	v_pk_fma_f32 v[28:29], v[48:49], v[32:33], v[28:29]
	v_pk_fma_f32 v[26:27], v[70:71], v[36:37], v[26:27]
	v_pk_fma_f32 v[28:29], v[52:53], v[160:161], v[28:29]
	v_pk_fma_f32 v[26:27], v[74:75], v[34:35], v[26:27]
	v_pk_fma_f32 v[28:29], v[56:57], v[158:159], v[28:29]
	v_pk_fma_f32 v[26:27], v[78:79], v[24:25], v[26:27]
	v_pk_fma_f32 v[28:29], v[60:61], v[156:157], v[28:29]
	v_pk_fma_f32 v[26:27], v[82:83], v[22:23], v[26:27]
	v_pk_fma_f32 v[28:29], v[64:65], v[40:41], v[28:29]
	v_pk_fma_f32 v[26:27], v[86:87], v[20:21], v[26:27]
	v_pk_fma_f32 v[28:29], v[68:69], v[38:39], v[28:29]
	v_pk_fma_f32 v[26:27], v[90:91], v[18:19], v[26:27]
	v_pk_fma_f32 v[28:29], v[72:73], v[36:37], v[28:29]
	v_pk_fma_f32 v[26:27], v[94:95], v[10:11], v[26:27]
	v_pk_fma_f32 v[28:29], v[76:77], v[34:35], v[28:29]
	v_pk_fma_f32 v[26:27], v[98:99], v[12:13], v[26:27]
	v_pk_fma_f32 v[28:29], v[80:81], v[24:25], v[28:29]
	v_pk_fma_f32 v[26:27], v[102:103], v[14:15], v[26:27]
	v_pk_fma_f32 v[28:29], v[84:85], v[22:23], v[28:29]
	v_add_f32_e32 v169, v26, v27
	v_mul_f32_e32 v27, v44, v33
	v_mov_b32_e32 v26, v104
	v_pk_fma_f32 v[26:27], v[46:47], v[160:161], v[26:27]
	v_pk_fma_f32 v[28:29], v[88:89], v[20:21], v[28:29]
	v_pk_fma_f32 v[26:27], v[50:51], v[158:159], v[26:27]
	v_pk_fma_f32 v[28:29], v[92:93], v[18:19], v[28:29]
	v_pk_fma_f32 v[26:27], v[54:55], v[156:157], v[26:27]
	v_pk_fma_f32 v[28:29], v[96:97], v[10:11], v[28:29]
	v_pk_fma_f32 v[26:27], v[58:59], v[40:41], v[26:27]
	v_pk_fma_f32 v[28:29], v[100:101], v[12:13], v[28:29]
	v_pk_fma_f32 v[26:27], v[62:63], v[38:39], v[26:27]
	s_waitcnt lgkmcnt(0)
	v_mul_f32_e32 v105, v103, v16
	v_pk_fma_f32 v[26:27], v[66:67], v[36:37], v[26:27]
	v_add_f32_e32 v168, v28, v29
	v_pk_fma_f32 v[26:27], v[70:71], v[34:35], v[26:27]
	v_pk_fma_f32 v[28:29], v[44:45], v[32:33], v[104:105]
	v_pk_fma_f32 v[26:27], v[74:75], v[24:25], v[26:27]
	v_pk_fma_f32 v[28:29], v[48:49], v[160:161], v[28:29]
	v_pk_fma_f32 v[26:27], v[78:79], v[22:23], v[26:27]
	v_pk_fma_f32 v[28:29], v[52:53], v[158:159], v[28:29]
	v_pk_fma_f32 v[26:27], v[82:83], v[20:21], v[26:27]
	v_pk_fma_f32 v[28:29], v[56:57], v[156:157], v[28:29]
	v_pk_fma_f32 v[26:27], v[86:87], v[18:19], v[26:27]
	v_pk_fma_f32 v[28:29], v[60:61], v[40:41], v[28:29]
	v_pk_fma_f32 v[26:27], v[90:91], v[10:11], v[26:27]
	v_mul_f32_e32 v173, v44, v161
	v_pk_fma_f32 v[26:27], v[94:95], v[12:13], v[26:27]
	v_pk_fma_f32 v[28:29], v[64:65], v[38:39], v[28:29]
	v_pk_fma_f32 v[26:27], v[98:99], v[14:15], v[26:27]
	v_pk_fma_f32 v[28:29], v[68:69], v[36:37], v[28:29]
	v_pk_fma_f32 v[30:31], v[102:103], v[16:17], v[26:27]
	ds_read2st64_b32 v[26:27], v163 offset0:152 offset1:156
	v_pk_fma_f32 v[28:29], v[72:73], v[34:35], v[28:29]
	v_add_f32_e32 v171, v30, v31
	v_pk_fma_f32 v[28:29], v[76:77], v[24:25], v[28:29]
	v_mov_b32_e32 v172, v104
	s_waitcnt lgkmcnt(0)
	v_mul_f32_e32 v105, v103, v26
	v_pk_fma_f32 v[160:161], v[44:45], v[160:161], v[104:105]
	v_pk_fma_f32 v[28:29], v[80:81], v[22:23], v[28:29]
	v_pk_fma_f32 v[160:161], v[48:49], v[158:159], v[160:161]
	v_pk_fma_f32 v[28:29], v[84:85], v[20:21], v[28:29]
	v_pk_fma_f32 v[160:161], v[52:53], v[156:157], v[160:161]
	v_pk_fma_f32 v[28:29], v[88:89], v[18:19], v[28:29]
	v_pk_fma_f32 v[160:161], v[56:57], v[40:41], v[160:161]
	v_pk_fma_f32 v[28:29], v[92:93], v[10:11], v[28:29]
	v_pk_fma_f32 v[160:161], v[60:61], v[38:39], v[160:161]
	v_pk_fma_f32 v[28:29], v[96:97], v[12:13], v[28:29]
	v_pk_fma_f32 v[160:161], v[64:65], v[36:37], v[160:161]
	v_pk_fma_f32 v[28:29], v[100:101], v[14:15], v[28:29]
	v_pk_fma_f32 v[160:161], v[68:69], v[34:35], v[160:161]
	v_add_f32_e32 v170, v28, v29
	v_pk_fma_f32 v[160:161], v[72:73], v[24:25], v[160:161]
	ds_read2st64_b32 v[28:29], v163 offset0:160 offset1:164
	ds_read2st64_b32 v[30:31], v163 offset0:168 offset1:172
	ds_read2st64_b32 v[32:33], v163 offset0:176 offset1:180
	v_pk_fma_f32 v[160:161], v[76:77], v[22:23], v[160:161]
	v_pk_fma_f32 v[172:173], v[46:47], v[158:159], v[172:173]
	v_pk_fma_f32 v[160:161], v[80:81], v[20:21], v[160:161]
	s_waitcnt lgkmcnt(2)
	v_mul_f32_e32 v105, v103, v28
	v_pk_fma_f32 v[160:161], v[84:85], v[18:19], v[160:161]
	v_pk_fma_f32 v[172:173], v[50:51], v[156:157], v[172:173]
	v_pk_fma_f32 v[160:161], v[88:89], v[10:11], v[160:161]
	v_pk_fma_f32 v[172:173], v[54:55], v[40:41], v[172:173]
	v_pk_fma_f32 v[160:161], v[92:93], v[12:13], v[160:161]
	v_pk_fma_f32 v[172:173], v[58:59], v[38:39], v[172:173]
	v_pk_fma_f32 v[160:161], v[96:97], v[14:15], v[160:161]
	v_pk_fma_f32 v[172:173], v[62:63], v[36:37], v[172:173]
	v_pk_fma_f32 v[160:161], v[100:101], v[16:17], v[160:161]
	v_pk_fma_f32 v[172:173], v[66:67], v[34:35], v[172:173]
	v_add_f32_e32 v174, v160, v161
	v_mul_f32_e32 v161, v44, v159
	v_pk_fma_f32 v[158:159], v[44:45], v[158:159], v[104:105]
	v_mov_b32_e32 v160, v104
	v_pk_fma_f32 v[158:159], v[48:49], v[156:157], v[158:159]
	s_waitcnt lgkmcnt(1)
	v_mul_f32_e32 v105, v103, v30
	v_pk_fma_f32 v[158:159], v[52:53], v[40:41], v[158:159]
	v_pk_fma_f32 v[160:161], v[46:47], v[156:157], v[160:161]
	v_pk_fma_f32 v[158:159], v[56:57], v[38:39], v[158:159]
	v_pk_fma_f32 v[160:161], v[50:51], v[40:41], v[160:161]
	v_pk_fma_f32 v[158:159], v[60:61], v[36:37], v[158:159]
	v_pk_fma_f32 v[172:173], v[70:71], v[24:25], v[172:173]
	v_pk_fma_f32 v[158:159], v[64:65], v[34:35], v[158:159]
	v_pk_fma_f32 v[172:173], v[74:75], v[22:23], v[172:173]
	v_pk_fma_f32 v[158:159], v[68:69], v[24:25], v[158:159]
	v_pk_fma_f32 v[172:173], v[78:79], v[20:21], v[172:173]
	v_pk_fma_f32 v[158:159], v[72:73], v[22:23], v[158:159]
	v_pk_fma_f32 v[172:173], v[82:83], v[18:19], v[172:173]
	v_pk_fma_f32 v[158:159], v[76:77], v[20:21], v[158:159]
	v_pk_fma_f32 v[172:173], v[86:87], v[10:11], v[172:173]
	v_pk_fma_f32 v[158:159], v[80:81], v[18:19], v[158:159]
	v_pk_fma_f32 v[172:173], v[90:91], v[12:13], v[172:173]
	v_pk_fma_f32 v[158:159], v[84:85], v[10:11], v[158:159]
	v_pk_fma_f32 v[172:173], v[94:95], v[14:15], v[172:173]
	v_pk_fma_f32 v[158:159], v[88:89], v[12:13], v[158:159]
	v_pk_fma_f32 v[172:173], v[98:99], v[16:17], v[172:173]
	v_pk_fma_f32 v[158:159], v[92:93], v[14:15], v[158:159]
	v_pk_fma_f32 v[160:161], v[54:55], v[38:39], v[160:161]
	v_pk_fma_f32 v[158:159], v[96:97], v[16:17], v[158:159]
	v_pk_fma_f32 v[172:173], v[102:103], v[26:27], v[172:173]
	v_pk_fma_f32 v[158:159], v[100:101], v[26:27], v[158:159]
	v_pk_fma_f32 v[160:161], v[58:59], v[36:37], v[160:161]
	v_add_f32_e32 v176, v158, v159
	v_mul_f32_e32 v159, v44, v157
	v_pk_fma_f32 v[156:157], v[44:45], v[156:157], v[104:105]
	v_mov_b32_e32 v158, v104
	v_pk_fma_f32 v[156:157], v[48:49], v[40:41], v[156:157]
	s_waitcnt lgkmcnt(0)
	v_mul_f32_e32 v105, v103, v32
	v_pk_fma_f32 v[156:157], v[52:53], v[38:39], v[156:157]
	v_pk_fma_f32 v[158:159], v[46:47], v[40:41], v[158:159]
	v_pk_fma_f32 v[156:157], v[56:57], v[36:37], v[156:157]
	v_pk_fma_f32 v[158:159], v[50:51], v[38:39], v[158:159]
	v_pk_fma_f32 v[156:157], v[60:61], v[34:35], v[156:157]
	v_pk_fma_f32 v[158:159], v[54:55], v[36:37], v[158:159]
	v_pk_fma_f32 v[156:157], v[64:65], v[24:25], v[156:157]
	v_pk_fma_f32 v[158:159], v[58:59], v[34:35], v[158:159]
	v_pk_fma_f32 v[156:157], v[68:69], v[22:23], v[156:157]
	v_add_f32_e32 v175, v172, v173
	v_pk_fma_f32 v[156:157], v[72:73], v[20:21], v[156:157]
	v_pk_fma_f32 v[160:161], v[62:63], v[34:35], v[160:161]
	v_pk_fma_f32 v[156:157], v[76:77], v[18:19], v[156:157]
	v_pk_fma_f32 v[158:159], v[62:63], v[24:25], v[158:159]
	v_pk_fma_f32 v[156:157], v[80:81], v[10:11], v[156:157]
	v_mul_f32_e32 v173, v44, v39
	v_pk_fma_f32 v[156:157], v[84:85], v[12:13], v[156:157]
	v_pk_fma_f32 v[160:161], v[66:67], v[24:25], v[160:161]
	v_pk_fma_f32 v[156:157], v[88:89], v[14:15], v[156:157]
	v_pk_fma_f32 v[158:159], v[66:67], v[22:23], v[158:159]
	v_pk_fma_f32 v[156:157], v[92:93], v[16:17], v[156:157]
	v_pk_fma_f32 v[160:161], v[70:71], v[22:23], v[160:161]
	v_pk_fma_f32 v[156:157], v[96:97], v[26:27], v[156:157]
	v_pk_fma_f32 v[158:159], v[70:71], v[20:21], v[158:159]
	v_pk_fma_f32 v[156:157], v[100:101], v[28:29], v[156:157]
	v_pk_fma_f32 v[160:161], v[74:75], v[20:21], v[160:161]
	v_add_f32_e32 v178, v156, v157
	v_mul_f32_e32 v157, v44, v41
	v_pk_fma_f32 v[40:41], v[44:45], v[40:41], v[104:105]
	v_mov_b32_e32 v156, v104
	v_pk_fma_f32 v[40:41], v[48:49], v[38:39], v[40:41]
	v_pk_fma_f32 v[156:157], v[46:47], v[38:39], v[156:157]
	v_pk_fma_f32 v[40:41], v[52:53], v[36:37], v[40:41]
	v_pk_fma_f32 v[156:157], v[50:51], v[36:37], v[156:157]
	v_pk_fma_f32 v[40:41], v[56:57], v[34:35], v[40:41]
	v_pk_fma_f32 v[156:157], v[54:55], v[34:35], v[156:157]
	v_pk_fma_f32 v[40:41], v[60:61], v[24:25], v[40:41]
	v_pk_fma_f32 v[156:157], v[58:59], v[24:25], v[156:157]
	v_pk_fma_f32 v[40:41], v[64:65], v[22:23], v[40:41]
	v_pk_fma_f32 v[156:157], v[62:63], v[22:23], v[156:157]
	v_pk_fma_f32 v[40:41], v[68:69], v[20:21], v[40:41]
	v_pk_fma_f32 v[156:157], v[66:67], v[20:21], v[156:157]
	v_pk_fma_f32 v[40:41], v[72:73], v[18:19], v[40:41]
	v_pk_fma_f32 v[156:157], v[70:71], v[18:19], v[156:157]
	v_pk_fma_f32 v[40:41], v[76:77], v[10:11], v[40:41]
	v_pk_fma_f32 v[158:159], v[74:75], v[18:19], v[158:159]
	v_pk_fma_f32 v[40:41], v[80:81], v[12:13], v[40:41]
	v_pk_fma_f32 v[156:157], v[74:75], v[10:11], v[156:157]
	v_pk_fma_f32 v[40:41], v[84:85], v[14:15], v[40:41]
	v_pk_fma_f32 v[160:161], v[78:79], v[18:19], v[160:161]
	v_pk_fma_f32 v[40:41], v[88:89], v[16:17], v[40:41]
	v_pk_fma_f32 v[158:159], v[78:79], v[10:11], v[158:159]
	v_pk_fma_f32 v[40:41], v[92:93], v[26:27], v[40:41]
	v_pk_fma_f32 v[156:157], v[78:79], v[12:13], v[156:157]
	v_pk_fma_f32 v[40:41], v[96:97], v[28:29], v[40:41]
	v_pk_fma_f32 v[160:161], v[82:83], v[10:11], v[160:161]
	v_pk_fma_f32 v[40:41], v[100:101], v[30:31], v[40:41]
	v_pk_fma_f32 v[158:159], v[82:83], v[12:13], v[158:159]
	v_add_f32_e32 v180, v40, v41
	ds_read2st64_b32 v[40:41], v163 offset0:184 offset1:188
	v_pk_fma_f32 v[156:157], v[82:83], v[14:15], v[156:157]
	v_pk_fma_f32 v[160:161], v[86:87], v[12:13], v[160:161]
	v_pk_fma_f32 v[158:159], v[86:87], v[14:15], v[158:159]
	v_pk_fma_f32 v[156:157], v[86:87], v[16:17], v[156:157]
	s_waitcnt lgkmcnt(0)
	v_mul_f32_e32 v105, v103, v40
	v_pk_fma_f32 v[38:39], v[44:45], v[38:39], v[104:105]
	v_pk_fma_f32 v[160:161], v[90:91], v[14:15], v[160:161]
	v_pk_fma_f32 v[38:39], v[48:49], v[36:37], v[38:39]
	v_pk_fma_f32 v[158:159], v[90:91], v[16:17], v[158:159]
	v_pk_fma_f32 v[38:39], v[52:53], v[34:35], v[38:39]
	v_pk_fma_f32 v[156:157], v[90:91], v[26:27], v[156:157]
	v_pk_fma_f32 v[38:39], v[56:57], v[24:25], v[38:39]
	v_pk_fma_f32 v[160:161], v[94:95], v[16:17], v[160:161]
	v_pk_fma_f32 v[38:39], v[60:61], v[22:23], v[38:39]
	v_pk_fma_f32 v[158:159], v[94:95], v[26:27], v[158:159]
	v_pk_fma_f32 v[38:39], v[64:65], v[20:21], v[38:39]
	v_pk_fma_f32 v[156:157], v[94:95], v[28:29], v[156:157]
	v_pk_fma_f32 v[38:39], v[68:69], v[18:19], v[38:39]
	v_pk_fma_f32 v[160:161], v[98:99], v[26:27], v[160:161]
	v_pk_fma_f32 v[38:39], v[72:73], v[10:11], v[38:39]
	v_pk_fma_f32 v[158:159], v[98:99], v[28:29], v[158:159]
	v_pk_fma_f32 v[38:39], v[76:77], v[12:13], v[38:39]
	v_pk_fma_f32 v[156:157], v[98:99], v[30:31], v[156:157]
	v_pk_fma_f32 v[38:39], v[80:81], v[14:15], v[38:39]
	v_pk_fma_f32 v[160:161], v[102:103], v[28:29], v[160:161]
	v_pk_fma_f32 v[158:159], v[102:103], v[30:31], v[158:159]
	v_pk_fma_f32 v[156:157], v[102:103], v[32:33], v[156:157]
	v_pk_fma_f32 v[38:39], v[84:85], v[16:17], v[38:39]
	v_add_f32_e32 v177, v160, v161
	v_add_f32_e32 v179, v158, v159
	v_add_f32_e32 v181, v156, v157
	ds_read2st64_b32 v[156:157], v163 offset0:192 offset1:196
	ds_read2st64_b32 v[158:159], v163 offset0:200 offset1:204
	ds_read2st64_b32 v[160:161], v163 offset0:208 offset1:212
	v_pk_fma_f32 v[38:39], v[88:89], v[26:27], v[38:39]
	v_mov_b32_e32 v172, v104
	v_pk_fma_f32 v[38:39], v[92:93], v[28:29], v[38:39]
	s_waitcnt lgkmcnt(2)
	v_mul_f32_e32 v105, v103, v156
	v_pk_fma_f32 v[38:39], v[96:97], v[30:31], v[38:39]
	v_pk_fma_f32 v[172:173], v[46:47], v[36:37], v[172:173]
	v_pk_fma_f32 v[38:39], v[100:101], v[32:33], v[38:39]
	v_pk_fma_f32 v[172:173], v[50:51], v[34:35], v[172:173]
	v_add_f32_e32 v182, v38, v39
	v_mul_f32_e32 v39, v44, v37
	v_pk_fma_f32 v[36:37], v[44:45], v[36:37], v[104:105]
	v_mov_b32_e32 v38, v104
	v_pk_fma_f32 v[36:37], v[48:49], v[34:35], v[36:37]
	s_waitcnt lgkmcnt(1)
	v_mul_f32_e32 v105, v103, v158
	v_pk_fma_f32 v[36:37], v[52:53], v[24:25], v[36:37]
	v_pk_fma_f32 v[38:39], v[46:47], v[34:35], v[38:39]
	v_pk_fma_f32 v[36:37], v[56:57], v[22:23], v[36:37]
	v_pk_fma_f32 v[172:173], v[54:55], v[24:25], v[172:173]
	v_pk_fma_f32 v[36:37], v[60:61], v[20:21], v[36:37]
	v_pk_fma_f32 v[38:39], v[50:51], v[24:25], v[38:39]
	v_pk_fma_f32 v[36:37], v[64:65], v[18:19], v[36:37]
	v_pk_fma_f32 v[172:173], v[58:59], v[22:23], v[172:173]
	v_pk_fma_f32 v[36:37], v[68:69], v[10:11], v[36:37]
	v_pk_fma_f32 v[172:173], v[62:63], v[20:21], v[172:173]
	v_pk_fma_f32 v[36:37], v[72:73], v[12:13], v[36:37]
	v_pk_fma_f32 v[172:173], v[66:67], v[18:19], v[172:173]
	v_pk_fma_f32 v[36:37], v[76:77], v[14:15], v[36:37]
	v_pk_fma_f32 v[172:173], v[70:71], v[10:11], v[172:173]
	v_pk_fma_f32 v[36:37], v[80:81], v[16:17], v[36:37]
	v_pk_fma_f32 v[172:173], v[74:75], v[12:13], v[172:173]
	v_pk_fma_f32 v[36:37], v[84:85], v[26:27], v[36:37]
	v_pk_fma_f32 v[172:173], v[78:79], v[14:15], v[172:173]
	v_pk_fma_f32 v[36:37], v[88:89], v[28:29], v[36:37]
	v_pk_fma_f32 v[172:173], v[82:83], v[16:17], v[172:173]
	v_pk_fma_f32 v[36:37], v[92:93], v[30:31], v[36:37]
	v_pk_fma_f32 v[172:173], v[86:87], v[26:27], v[172:173]
	v_pk_fma_f32 v[36:37], v[96:97], v[32:33], v[36:37]
	v_pk_fma_f32 v[172:173], v[90:91], v[28:29], v[172:173]
	v_pk_fma_f32 v[36:37], v[100:101], v[40:41], v[36:37]
	v_pk_fma_f32 v[172:173], v[94:95], v[30:31], v[172:173]
	v_add_f32_e32 v184, v36, v37
	v_mul_f32_e32 v37, v44, v35
	v_pk_fma_f32 v[34:35], v[44:45], v[34:35], v[104:105]
	v_mov_b32_e32 v36, v104
	v_pk_fma_f32 v[34:35], v[48:49], v[24:25], v[34:35]
	s_waitcnt lgkmcnt(0)
	v_mul_f32_e32 v105, v103, v160
	v_pk_fma_f32 v[34:35], v[52:53], v[22:23], v[34:35]
	v_pk_fma_f32 v[36:37], v[46:47], v[24:25], v[36:37]
	v_pk_fma_f32 v[34:35], v[56:57], v[20:21], v[34:35]
	v_pk_fma_f32 v[36:37], v[50:51], v[22:23], v[36:37]
	v_pk_fma_f32 v[34:35], v[60:61], v[18:19], v[34:35]
	v_pk_fma_f32 v[172:173], v[98:99], v[32:33], v[172:173]
	v_pk_fma_f32 v[34:35], v[64:65], v[10:11], v[34:35]
	v_pk_fma_f32 v[38:39], v[54:55], v[22:23], v[38:39]
	v_pk_fma_f32 v[34:35], v[68:69], v[12:13], v[34:35]
	v_pk_fma_f32 v[36:37], v[54:55], v[20:21], v[36:37]
	v_pk_fma_f32 v[34:35], v[72:73], v[14:15], v[34:35]
	v_pk_fma_f32 v[172:173], v[102:103], v[40:41], v[172:173]
	v_pk_fma_f32 v[34:35], v[76:77], v[16:17], v[34:35]
	v_pk_fma_f32 v[38:39], v[58:59], v[20:21], v[38:39]
	v_pk_fma_f32 v[34:35], v[80:81], v[26:27], v[34:35]
	v_pk_fma_f32 v[36:37], v[58:59], v[18:19], v[36:37]
	v_pk_fma_f32 v[34:35], v[84:85], v[28:29], v[34:35]
	v_add_f32_e32 v183, v172, v173
	v_pk_fma_f32 v[34:35], v[88:89], v[30:31], v[34:35]
	v_pk_fma_f32 v[38:39], v[62:63], v[18:19], v[38:39]
	v_pk_fma_f32 v[34:35], v[92:93], v[32:33], v[34:35]
	v_pk_fma_f32 v[36:37], v[62:63], v[10:11], v[36:37]
	v_pk_fma_f32 v[34:35], v[96:97], v[40:41], v[34:35]
	v_mul_f32_e32 v173, v44, v23
	v_pk_fma_f32 v[34:35], v[100:101], v[156:157], v[34:35]
	v_pk_fma_f32 v[38:39], v[66:67], v[10:11], v[38:39]
	v_add_f32_e32 v186, v34, v35
	v_mul_f32_e32 v35, v44, v25
	v_pk_fma_f32 v[24:25], v[44:45], v[24:25], v[104:105]
	v_mov_b32_e32 v34, v104
	v_pk_fma_f32 v[24:25], v[48:49], v[22:23], v[24:25]
	v_pk_fma_f32 v[34:35], v[46:47], v[22:23], v[34:35]
	v_pk_fma_f32 v[24:25], v[52:53], v[20:21], v[24:25]
	v_pk_fma_f32 v[34:35], v[50:51], v[20:21], v[34:35]
	v_pk_fma_f32 v[24:25], v[56:57], v[18:19], v[24:25]
	v_pk_fma_f32 v[34:35], v[54:55], v[18:19], v[34:35]
	v_pk_fma_f32 v[24:25], v[60:61], v[10:11], v[24:25]
	v_pk_fma_f32 v[34:35], v[58:59], v[10:11], v[34:35]
	v_pk_fma_f32 v[24:25], v[64:65], v[12:13], v[24:25]
	v_pk_fma_f32 v[34:35], v[62:63], v[12:13], v[34:35]
	v_pk_fma_f32 v[24:25], v[68:69], v[14:15], v[24:25]
	v_pk_fma_f32 v[36:37], v[66:67], v[12:13], v[36:37]
	v_pk_fma_f32 v[24:25], v[72:73], v[16:17], v[24:25]
	v_pk_fma_f32 v[34:35], v[66:67], v[14:15], v[34:35]
	v_pk_fma_f32 v[24:25], v[76:77], v[26:27], v[24:25]
	v_pk_fma_f32 v[38:39], v[70:71], v[12:13], v[38:39]
	v_pk_fma_f32 v[24:25], v[80:81], v[28:29], v[24:25]
	v_pk_fma_f32 v[36:37], v[70:71], v[14:15], v[36:37]
	v_pk_fma_f32 v[24:25], v[84:85], v[30:31], v[24:25]
	v_pk_fma_f32 v[34:35], v[70:71], v[16:17], v[34:35]
	v_pk_fma_f32 v[24:25], v[88:89], v[32:33], v[24:25]
	v_pk_fma_f32 v[38:39], v[74:75], v[14:15], v[38:39]
	v_pk_fma_f32 v[24:25], v[92:93], v[40:41], v[24:25]
	v_pk_fma_f32 v[36:37], v[74:75], v[16:17], v[36:37]
	v_pk_fma_f32 v[24:25], v[96:97], v[156:157], v[24:25]
	v_pk_fma_f32 v[34:35], v[74:75], v[26:27], v[34:35]
	v_pk_fma_f32 v[24:25], v[100:101], v[158:159], v[24:25]
	v_pk_fma_f32 v[38:39], v[78:79], v[16:17], v[38:39]
	v_add_f32_e32 v188, v24, v25
	ds_read2st64_b32 v[24:25], v163 offset0:216 offset1:220
	v_pk_fma_f32 v[36:37], v[78:79], v[26:27], v[36:37]
	v_pk_fma_f32 v[34:35], v[78:79], v[28:29], v[34:35]
	v_pk_fma_f32 v[38:39], v[82:83], v[26:27], v[38:39]
	v_pk_fma_f32 v[36:37], v[82:83], v[28:29], v[36:37]
	s_waitcnt lgkmcnt(0)
	v_mul_f32_e32 v105, v103, v24
	v_pk_fma_f32 v[22:23], v[44:45], v[22:23], v[104:105]
	v_pk_fma_f32 v[34:35], v[82:83], v[30:31], v[34:35]
	v_pk_fma_f32 v[22:23], v[48:49], v[20:21], v[22:23]
	v_pk_fma_f32 v[38:39], v[86:87], v[28:29], v[38:39]
	v_pk_fma_f32 v[22:23], v[52:53], v[18:19], v[22:23]
	v_pk_fma_f32 v[36:37], v[86:87], v[30:31], v[36:37]
	v_pk_fma_f32 v[22:23], v[56:57], v[10:11], v[22:23]
	v_pk_fma_f32 v[34:35], v[86:87], v[32:33], v[34:35]
	v_pk_fma_f32 v[22:23], v[60:61], v[12:13], v[22:23]
	v_pk_fma_f32 v[38:39], v[90:91], v[30:31], v[38:39]
	v_pk_fma_f32 v[22:23], v[64:65], v[14:15], v[22:23]
	v_pk_fma_f32 v[36:37], v[90:91], v[32:33], v[36:37]
	v_pk_fma_f32 v[22:23], v[68:69], v[16:17], v[22:23]
	v_pk_fma_f32 v[34:35], v[90:91], v[40:41], v[34:35]
	v_pk_fma_f32 v[22:23], v[72:73], v[26:27], v[22:23]
	v_pk_fma_f32 v[38:39], v[94:95], v[32:33], v[38:39]
	v_pk_fma_f32 v[36:37], v[94:95], v[40:41], v[36:37]
	v_pk_fma_f32 v[34:35], v[94:95], v[156:157], v[34:35]
	v_pk_fma_f32 v[22:23], v[76:77], v[28:29], v[22:23]
	v_pk_fma_f32 v[38:39], v[98:99], v[40:41], v[38:39]
	v_pk_fma_f32 v[36:37], v[98:99], v[156:157], v[36:37]
	v_pk_fma_f32 v[34:35], v[98:99], v[158:159], v[34:35]
	v_pk_fma_f32 v[22:23], v[80:81], v[30:31], v[22:23]
	v_pk_fma_f32 v[38:39], v[102:103], v[156:157], v[38:39]
	v_pk_fma_f32 v[36:37], v[102:103], v[158:159], v[36:37]
	v_pk_fma_f32 v[34:35], v[102:103], v[160:161], v[34:35]
	v_pk_fma_f32 v[22:23], v[84:85], v[32:33], v[22:23]
	v_add_f32_e32 v185, v38, v39
	v_add_f32_e32 v187, v36, v37
	v_add_f32_e32 v189, v34, v35
	ds_read2st64_b32 v[34:35], v163 offset0:224 offset1:228
	ds_read2st64_b32 v[36:37], v163 offset0:232 offset1:236
	ds_read2st64_b32 v[38:39], v163 offset0:240 offset1:244
	v_pk_fma_f32 v[22:23], v[88:89], v[40:41], v[22:23]
	v_mov_b32_e32 v172, v104
	v_pk_fma_f32 v[22:23], v[92:93], v[156:157], v[22:23]
	s_waitcnt lgkmcnt(2)
	v_mul_f32_e32 v105, v103, v34
	v_pk_fma_f32 v[22:23], v[96:97], v[158:159], v[22:23]
	v_pk_fma_f32 v[172:173], v[46:47], v[20:21], v[172:173]
	v_pk_fma_f32 v[22:23], v[100:101], v[160:161], v[22:23]
	v_pk_fma_f32 v[172:173], v[50:51], v[18:19], v[172:173]
	v_add_f32_e32 v190, v22, v23
	v_mul_f32_e32 v23, v44, v21
	v_pk_fma_f32 v[20:21], v[44:45], v[20:21], v[104:105]
	v_pk_fma_f32 v[172:173], v[54:55], v[10:11], v[172:173]
	v_pk_fma_f32 v[20:21], v[48:49], v[18:19], v[20:21]
	v_pk_fma_f32 v[172:173], v[58:59], v[12:13], v[172:173]
	v_pk_fma_f32 v[20:21], v[52:53], v[10:11], v[20:21]
	v_pk_fma_f32 v[172:173], v[62:63], v[14:15], v[172:173]
	v_pk_fma_f32 v[20:21], v[56:57], v[12:13], v[20:21]
	v_pk_fma_f32 v[172:173], v[66:67], v[16:17], v[172:173]
	v_pk_fma_f32 v[20:21], v[60:61], v[14:15], v[20:21]
	v_pk_fma_f32 v[172:173], v[70:71], v[26:27], v[172:173]
	v_pk_fma_f32 v[20:21], v[64:65], v[16:17], v[20:21]
	v_pk_fma_f32 v[172:173], v[74:75], v[28:29], v[172:173]
	v_pk_fma_f32 v[20:21], v[68:69], v[26:27], v[20:21]
	v_pk_fma_f32 v[172:173], v[78:79], v[30:31], v[172:173]
	v_pk_fma_f32 v[20:21], v[72:73], v[28:29], v[20:21]
	v_pk_fma_f32 v[172:173], v[82:83], v[32:33], v[172:173]
	v_pk_fma_f32 v[20:21], v[76:77], v[30:31], v[20:21]
	v_pk_fma_f32 v[172:173], v[86:87], v[40:41], v[172:173]
	v_pk_fma_f32 v[20:21], v[80:81], v[32:33], v[20:21]
	v_pk_fma_f32 v[172:173], v[90:91], v[156:157], v[172:173]
	v_pk_fma_f32 v[20:21], v[84:85], v[40:41], v[20:21]
	v_pk_fma_f32 v[172:173], v[94:95], v[158:159], v[172:173]
	v_pk_fma_f32 v[20:21], v[88:89], v[156:157], v[20:21]
	v_pk_fma_f32 v[172:173], v[98:99], v[160:161], v[172:173]
	v_pk_fma_f32 v[20:21], v[92:93], v[158:159], v[20:21]
	v_pk_fma_f32 v[172:173], v[102:103], v[24:25], v[172:173]
	v_pk_fma_f32 v[20:21], v[96:97], v[160:161], v[20:21]
	v_mov_b32_e32 v22, v104
	v_pk_fma_f32 v[20:21], v[100:101], v[24:25], v[20:21]
	s_waitcnt lgkmcnt(1)
	v_mul_f32_e32 v105, v103, v36
	v_add_f32_e32 v172, v172, v173
	v_pk_fma_f32 v[22:23], v[46:47], v[18:19], v[22:23]
	v_add_f32_e32 v173, v20, v21
	v_mul_f32_e32 v21, v44, v19
	v_pk_fma_f32 v[18:19], v[44:45], v[18:19], v[104:105]
	v_pk_fma_f32 v[22:23], v[50:51], v[10:11], v[22:23]
	v_pk_fma_f32 v[18:19], v[48:49], v[10:11], v[18:19]
	v_pk_fma_f32 v[22:23], v[54:55], v[12:13], v[22:23]
	v_pk_fma_f32 v[18:19], v[52:53], v[12:13], v[18:19]
	v_pk_fma_f32 v[22:23], v[58:59], v[14:15], v[22:23]
	v_pk_fma_f32 v[18:19], v[56:57], v[14:15], v[18:19]
	v_pk_fma_f32 v[22:23], v[62:63], v[16:17], v[22:23]
	v_pk_fma_f32 v[18:19], v[60:61], v[16:17], v[18:19]
	v_pk_fma_f32 v[22:23], v[66:67], v[26:27], v[22:23]
	v_pk_fma_f32 v[18:19], v[64:65], v[26:27], v[18:19]
	v_pk_fma_f32 v[22:23], v[70:71], v[28:29], v[22:23]
	v_pk_fma_f32 v[18:19], v[68:69], v[28:29], v[18:19]
	v_pk_fma_f32 v[22:23], v[74:75], v[30:31], v[22:23]
	v_pk_fma_f32 v[18:19], v[72:73], v[30:31], v[18:19]
	v_pk_fma_f32 v[22:23], v[78:79], v[32:33], v[22:23]
	v_pk_fma_f32 v[18:19], v[76:77], v[32:33], v[18:19]
	v_pk_fma_f32 v[22:23], v[82:83], v[40:41], v[22:23]
	v_pk_fma_f32 v[18:19], v[80:81], v[40:41], v[18:19]
	v_pk_fma_f32 v[22:23], v[86:87], v[156:157], v[22:23]
	v_pk_fma_f32 v[18:19], v[84:85], v[156:157], v[18:19]
	v_pk_fma_f32 v[22:23], v[90:91], v[158:159], v[22:23]
	v_pk_fma_f32 v[18:19], v[88:89], v[158:159], v[18:19]
	v_pk_fma_f32 v[22:23], v[94:95], v[160:161], v[22:23]
	v_pk_fma_f32 v[18:19], v[92:93], v[160:161], v[18:19]
	v_pk_fma_f32 v[22:23], v[98:99], v[24:25], v[22:23]
	v_pk_fma_f32 v[18:19], v[96:97], v[24:25], v[18:19]
	v_pk_fma_f32 v[22:23], v[102:103], v[34:35], v[22:23]
	v_pk_fma_f32 v[18:19], v[100:101], v[34:35], v[18:19]
	v_add_f32_e32 v22, v22, v23
	v_mov_b32_e32 v20, v104
	v_add_f32_e32 v23, v18, v19
	s_waitcnt lgkmcnt(0)
	v_mul_f32_e32 v105, v103, v38
	v_mul_f32_e32 v19, v44, v11
	v_mov_b32_e32 v18, v104
	v_pk_fma_f32 v[20:21], v[46:47], v[10:11], v[20:21]
	v_pk_fma_f32 v[10:11], v[44:45], v[10:11], v[104:105]
	v_pk_fma_f32 v[18:19], v[46:47], v[12:13], v[18:19]
	v_pk_fma_f32 v[20:21], v[50:51], v[12:13], v[20:21]
	v_pk_fma_f32 v[10:11], v[48:49], v[12:13], v[10:11]
	v_pk_fma_f32 v[12:13], v[50:51], v[14:15], v[18:19]
	v_pk_fma_f32 v[20:21], v[54:55], v[14:15], v[20:21]
	v_pk_fma_f32 v[10:11], v[52:53], v[14:15], v[10:11]
	v_pk_fma_f32 v[12:13], v[54:55], v[16:17], v[12:13]
	v_pk_fma_f32 v[20:21], v[58:59], v[16:17], v[20:21]
	v_pk_fma_f32 v[10:11], v[56:57], v[16:17], v[10:11]
	v_pk_fma_f32 v[12:13], v[58:59], v[26:27], v[12:13]
	v_pk_fma_f32 v[20:21], v[62:63], v[26:27], v[20:21]
	v_pk_fma_f32 v[10:11], v[60:61], v[26:27], v[10:11]
	v_pk_fma_f32 v[12:13], v[62:63], v[28:29], v[12:13]
	v_pk_fma_f32 v[20:21], v[66:67], v[28:29], v[20:21]
	v_pk_fma_f32 v[10:11], v[64:65], v[28:29], v[10:11]
	v_pk_fma_f32 v[12:13], v[66:67], v[30:31], v[12:13]
	v_pk_fma_f32 v[20:21], v[70:71], v[30:31], v[20:21]
	v_pk_fma_f32 v[10:11], v[68:69], v[30:31], v[10:11]
	v_pk_fma_f32 v[12:13], v[70:71], v[32:33], v[12:13]
	v_pk_fma_f32 v[20:21], v[74:75], v[32:33], v[20:21]
	v_pk_fma_f32 v[10:11], v[72:73], v[32:33], v[10:11]
	v_pk_fma_f32 v[12:13], v[74:75], v[40:41], v[12:13]
	v_pk_fma_f32 v[20:21], v[78:79], v[40:41], v[20:21]
	v_pk_fma_f32 v[10:11], v[76:77], v[40:41], v[10:11]
	v_pk_fma_f32 v[12:13], v[78:79], v[156:157], v[12:13]
	v_pk_fma_f32 v[20:21], v[82:83], v[156:157], v[20:21]
	v_pk_fma_f32 v[10:11], v[80:81], v[156:157], v[10:11]
	v_pk_fma_f32 v[12:13], v[82:83], v[158:159], v[12:13]
	v_pk_fma_f32 v[20:21], v[86:87], v[158:159], v[20:21]
	v_pk_fma_f32 v[10:11], v[84:85], v[158:159], v[10:11]
	v_pk_fma_f32 v[12:13], v[86:87], v[160:161], v[12:13]
	v_pk_fma_f32 v[20:21], v[90:91], v[160:161], v[20:21]
	v_pk_fma_f32 v[10:11], v[88:89], v[160:161], v[10:11]
	v_pk_fma_f32 v[12:13], v[90:91], v[24:25], v[12:13]
	v_pk_fma_f32 v[20:21], v[94:95], v[24:25], v[20:21]
	v_pk_fma_f32 v[10:11], v[92:93], v[24:25], v[10:11]
	v_pk_fma_f32 v[12:13], v[94:95], v[34:35], v[12:13]
	s_lshl_b32 s6, s28, 10
	v_pk_fma_f32 v[20:21], v[98:99], v[34:35], v[20:21]
	v_pk_fma_f32 v[10:11], v[96:97], v[34:35], v[10:11]
	v_pk_fma_f32 v[12:13], v[98:99], v[36:37], v[12:13]
	s_add_i32 s6, s6, 0
	v_pk_fma_f32 v[20:21], v[102:103], v[36:37], v[20:21]
	v_pk_fma_f32 v[10:11], v[100:101], v[36:37], v[10:11]
	v_pk_fma_f32 v[12:13], v[102:103], v[38:39], v[12:13]
	v_add_u32_e32 v105, s6, v162
	v_add_f32_e32 v20, v20, v21
	v_add_f32_e32 v10, v10, v11
	v_add_f32_e32 v11, v12, v13
	s_barrier
	ds_write2st64_b32 v163, v164, v165 offset1:4
	ds_write2st64_b32 v163, v166, v167 offset0:8 offset1:12
	ds_write2st64_b32 v163, v168, v169 offset0:16 offset1:20
	ds_write2st64_b32 v163, v170, v171 offset0:24 offset1:28
	ds_write2st64_b32 v163, v174, v175 offset0:32 offset1:36
	ds_write2st64_b32 v163, v176, v177 offset0:40 offset1:44
	ds_write2st64_b32 v163, v178, v179 offset0:48 offset1:52
	ds_write2st64_b32 v163, v180, v181 offset0:56 offset1:60
	ds_write2st64_b32 v163, v182, v183 offset0:64 offset1:68
	ds_write2st64_b32 v163, v184, v185 offset0:72 offset1:76
	ds_write2st64_b32 v163, v186, v187 offset0:80 offset1:84
	ds_write2st64_b32 v163, v188, v189 offset0:88 offset1:92
	ds_write2st64_b32 v163, v190, v172 offset0:96 offset1:100
	ds_write2st64_b32 v163, v173, v22 offset0:104 offset1:108
	ds_write2st64_b32 v163, v23, v20 offset0:112 offset1:116
	ds_write2st64_b32 v163, v10, v11 offset0:120 offset1:124
	s_waitcnt lgkmcnt(0)
	s_barrier
	ds_read_b128 v[38:41], v105
	ds_read_b128 v[34:37], v105 offset:8192
	ds_read_b128 v[30:33], v105 offset:16384
	ds_read_b128 v[26:29], v105 offset:24576
	ds_read_b128 v[22:25], v105 offset:32768
	ds_read_b128 v[18:21], v105 offset:40960
	s_waitcnt lgkmcnt(5)
	v_mov_b32_e32 v10, v39
	v_mov_b32_e32 v11, v40
	v_mov_b32_e32 v12, v38
	v_mov_b32_e32 v13, v41
	v_pk_add_f32 v[10:11], v[10:11], v[12:13]
	s_waitcnt lgkmcnt(4)
	v_mov_b32_e32 v12, v34
	v_add_f32_e32 v160, v10, v11
	v_mov_b32_e32 v10, v35
	v_mov_b32_e32 v11, v36
	v_mov_b32_e32 v13, v37
	v_pk_add_f32 v[10:11], v[10:11], v[12:13]
	s_waitcnt lgkmcnt(3)
	v_mov_b32_e32 v12, v30
	v_add_f32_e32 v161, v10, v11
	v_mov_b32_e32 v10, v31
	v_mov_b32_e32 v11, v32
	v_mov_b32_e32 v13, v33
	v_pk_add_f32 v[10:11], v[10:11], v[12:13]
	s_waitcnt lgkmcnt(2)
	v_mov_b32_e32 v12, v26
	v_add_f32_e32 v162, v10, v11
	v_mov_b32_e32 v10, v27
	v_mov_b32_e32 v11, v28
	v_mov_b32_e32 v13, v29
	v_pk_add_f32 v[10:11], v[10:11], v[12:13]
	s_waitcnt lgkmcnt(1)
	v_mov_b32_e32 v12, v22
	v_add_f32_e32 v163, v10, v11
	v_mov_b32_e32 v10, v23
	v_mov_b32_e32 v11, v24
	v_mov_b32_e32 v13, v25
	v_pk_add_f32 v[10:11], v[10:11], v[12:13]
	s_waitcnt lgkmcnt(0)
	v_mov_b32_e32 v12, v18
	v_add_f32_e32 v164, v10, v11
	v_mov_b32_e32 v10, v19
	v_mov_b32_e32 v11, v20
	ds_read_b128 v[14:17], v105 offset:49152
	v_mov_b32_e32 v13, v21
	v_pk_add_f32 v[10:11], v[10:11], v[12:13]
	s_add_i32 s28, s52, s28
	v_add_f32_e32 v165, v10, v11
	ds_read_b128 v[10:13], v105 offset:57344
	s_waitcnt lgkmcnt(1)
	v_mov_b32_e32 v156, v15
	v_mov_b32_e32 v157, v16
	v_mov_b32_e32 v158, v14
	v_mov_b32_e32 v159, v17
	v_pk_add_f32 v[156:157], v[156:157], v[158:159]
	s_waitcnt lgkmcnt(0)
	v_mov_b32_e32 v158, v10
	v_add_f32_e32 v105, v156, v157
	v_mov_b32_e32 v156, v11
	v_mov_b32_e32 v157, v12
	v_mov_b32_e32 v159, v13
	v_pk_add_f32 v[156:157], v[156:157], v[158:159]
	v_add_f32_dpp v158, v161, v161 quad_perm:[1,0,3,2] row_mask:0xf bank_mask:0xf bound_ctrl:1
	v_add_f32_e32 v156, v156, v157
	v_add_f32_dpp v157, v160, v160 quad_perm:[1,0,3,2] row_mask:0xf bank_mask:0xf bound_ctrl:1
	v_add_f32_dpp v160, v163, v163 quad_perm:[1,0,3,2] row_mask:0xf bank_mask:0xf bound_ctrl:1
	v_add_f32_dpp v158, v158, v158 quad_perm:[2,3,0,1] row_mask:0xf bank_mask:0xf bound_ctrl:1
	v_add_f32_dpp v157, v157, v157 quad_perm:[2,3,0,1] row_mask:0xf bank_mask:0xf bound_ctrl:1
	v_add_f32_dpp v159, v162, v162 quad_perm:[1,0,3,2] row_mask:0xf bank_mask:0xf bound_ctrl:1
	s_nop 0
	v_add_f32_dpp v157, v157, v157 row_half_mirror row_mask:0xf bank_mask:0xf bound_ctrl:1
	v_add_f32_dpp v158, v158, v158 row_half_mirror row_mask:0xf bank_mask:0xf bound_ctrl:1
	v_add_f32_dpp v159, v159, v159 quad_perm:[2,3,0,1] row_mask:0xf bank_mask:0xf bound_ctrl:1
	v_add_f32_dpp v157, v157, v157 row_mirror row_mask:0xf bank_mask:0xf bound_ctrl:1
	v_add_f32_dpp v158, v158, v158 row_mirror row_mask:0xf bank_mask:0xf bound_ctrl:1
	v_add_f32_dpp v159, v159, v159 row_half_mirror row_mask:0xf bank_mask:0xf bound_ctrl:1
	v_add_f32_dpp v157, v157, v157 row_bcast:15 row_mask:0xa bank_mask:0xf
	v_add_f32_dpp v160, v160, v160 quad_perm:[2,3,0,1] row_mask:0xf bank_mask:0xf bound_ctrl:1
	v_add_f32_dpp v159, v159, v159 row_mirror row_mask:0xf bank_mask:0xf bound_ctrl:1
	v_add_f32_dpp v158, v158, v158 row_bcast:15 row_mask:0xa bank_mask:0xf
	v_add_f32_dpp v161, v164, v164 quad_perm:[1,0,3,2] row_mask:0xf bank_mask:0xf bound_ctrl:1
	v_add_f32_dpp v160, v160, v160 row_half_mirror row_mask:0xf bank_mask:0xf bound_ctrl:1
	v_add_f32_dpp v159, v159, v159 row_bcast:15 row_mask:0xa bank_mask:0xf
	v_add_f32_dpp v161, v161, v161 quad_perm:[2,3,0,1] row_mask:0xf bank_mask:0xf bound_ctrl:1
	v_add_f32_dpp v160, v160, v160 row_mirror row_mask:0xf bank_mask:0xf bound_ctrl:1
	v_add_f32_dpp v162, v165, v165 quad_perm:[1,0,3,2] row_mask:0xf bank_mask:0xf bound_ctrl:1
	v_add_f32_dpp v161, v161, v161 row_half_mirror row_mask:0xf bank_mask:0xf bound_ctrl:1
	v_add_f32_dpp v160, v160, v160 row_bcast:15 row_mask:0xa bank_mask:0xf
	v_add_f32_dpp v162, v162, v162 quad_perm:[2,3,0,1] row_mask:0xf bank_mask:0xf bound_ctrl:1
	v_add_f32_dpp v161, v161, v161 row_mirror row_mask:0xf bank_mask:0xf bound_ctrl:1
	v_add_f32_dpp v105, v105, v105 quad_perm:[1,0,3,2] row_mask:0xf bank_mask:0xf bound_ctrl:1
	v_add_f32_dpp v162, v162, v162 row_half_mirror row_mask:0xf bank_mask:0xf bound_ctrl:1
	v_add_f32_dpp v161, v161, v161 row_bcast:15 row_mask:0xa bank_mask:0xf
	v_add_f32_dpp v105, v105, v105 quad_perm:[2,3,0,1] row_mask:0xf bank_mask:0xf bound_ctrl:1
	v_add_f32_dpp v162, v162, v162 row_mirror row_mask:0xf bank_mask:0xf bound_ctrl:1
	v_add_f32_dpp v156, v156, v156 quad_perm:[1,0,3,2] row_mask:0xf bank_mask:0xf bound_ctrl:1
	v_add_f32_dpp v105, v105, v105 row_half_mirror row_mask:0xf bank_mask:0xf bound_ctrl:1
	v_add_f32_dpp v162, v162, v162 row_bcast:15 row_mask:0xa bank_mask:0xf
	v_add_f32_dpp v156, v156, v156 quad_perm:[2,3,0,1] row_mask:0xf bank_mask:0xf bound_ctrl:1
	v_add_f32_dpp v105, v105, v105 row_mirror row_mask:0xf bank_mask:0xf bound_ctrl:1
	s_nop 0
	v_add_f32_dpp v156, v156, v156 row_half_mirror row_mask:0xf bank_mask:0xf bound_ctrl:1
	s_nop 0
	v_add_f32_dpp v105, v105, v105 row_bcast:15 row_mask:0xa bank_mask:0xf
	v_add_f32_dpp v156, v156, v156 row_mirror row_mask:0xf bank_mask:0xf bound_ctrl:1
	s_nop 1
	v_add_f32_dpp v156, v156, v156 row_bcast:15 row_mask:0xa bank_mask:0xf
	s_nop 1
	v_add_f32_dpp v157, v157, v157 row_bcast:31 row_mask:0xc bank_mask:0xf
	s_nop 0
	v_readlane_b32 s6, v157, 63
	s_nop 0
	v_add_f32_dpp v158, v158, v158 row_bcast:31 row_mask:0xc bank_mask:0xf
	v_fma_f32 v39, s6, v239, v39
	v_fma_f32 v38, s6, v239, v38
	v_add_f32_dpp v159, v159, v159 row_bcast:31 row_mask:0xc bank_mask:0xf
	v_fma_f32 v41, s6, v239, v41
	v_fmac_f32_e32 v40, s6, v239
	v_add_f32_dpp v160, v160, v160 row_bcast:31 row_mask:0xc bank_mask:0xf
	v_readlane_b32 s7, v158, 63
	v_readlane_b32 s8, v159, 63
	v_add_f32_dpp v161, v161, v161 row_bcast:31 row_mask:0xc bank_mask:0xf
	v_pk_mul_f32 v[158:159], v[38:39], v[38:39]
	v_readlane_b32 s9, v160, 63
	v_add_f32_dpp v162, v162, v162 row_bcast:31 row_mask:0xc bank_mask:0xf
	v_readlane_b32 s10, v161, 63
	v_fma_f32 v35, s7, v239, v35
	v_add_f32_dpp v105, v105, v105 row_bcast:31 row_mask:0xc bank_mask:0xf
	v_fma_f32 v34, s7, v239, v34
	v_fma_f32 v37, s7, v239, v37
	v_add_f32_dpp v156, v156, v156 row_bcast:31 row_mask:0xc bank_mask:0xf
	v_fmac_f32_e32 v36, s7, v239
	v_readlane_b32 s55, v156, 63
	v_pk_mul_f32 v[156:157], v[40:41], v[40:41]
	v_readlane_b32 s29, v105, 63
	v_pk_mov_b32 v[160:161], v[158:159], v[156:157] op_sel:[1,0]
	v_mov_b32_e32 v159, v157
	v_pk_add_f32 v[156:157], v[160:161], v[158:159]
	v_pk_mul_f32 v[158:159], v[34:35], v[34:35]
	v_add_f32_e32 v105, v156, v157
	v_pk_mul_f32 v[156:157], v[36:37], v[36:37]
	v_fma_f32 v31, s8, v239, v31
	v_pk_mov_b32 v[160:161], v[158:159], v[156:157] op_sel:[1,0]
	v_mov_b32_e32 v159, v157
	v_pk_add_f32 v[156:157], v[160:161], v[158:159]
	v_fma_f32 v30, s8, v239, v30
	v_fma_f32 v33, s8, v239, v33
	v_fmac_f32_e32 v32, s8, v239
	v_readlane_b32 s11, v162, 63
	v_add_f32_e32 v162, v156, v157
	v_pk_mul_f32 v[156:157], v[32:33], v[32:33]
	v_pk_mul_f32 v[158:159], v[30:31], v[30:31]
	v_fma_f32 v27, s9, v239, v27
	v_pk_mov_b32 v[160:161], v[158:159], v[156:157] op_sel:[1,0]
	v_mov_b32_e32 v159, v157
	v_pk_add_f32 v[156:157], v[160:161], v[158:159]
	v_fma_f32 v26, s9, v239, v26
	v_fma_f32 v29, s9, v239, v29
	v_fmac_f32_e32 v28, s9, v239
	v_add_f32_e32 v163, v156, v157
	v_pk_mul_f32 v[156:157], v[28:29], v[28:29]
	v_pk_mul_f32 v[158:159], v[26:27], v[26:27]
	v_fma_f32 v23, s10, v239, v23
	v_pk_mov_b32 v[160:161], v[158:159], v[156:157] op_sel:[1,0]
	v_mov_b32_e32 v159, v157
	v_pk_add_f32 v[156:157], v[160:161], v[158:159]
	v_fma_f32 v22, s10, v239, v22
	v_fma_f32 v25, s10, v239, v25
	v_fmac_f32_e32 v24, s10, v239
	v_add_f32_e32 v164, v156, v157
	v_pk_mul_f32 v[156:157], v[24:25], v[24:25]
	v_pk_mul_f32 v[158:159], v[22:23], v[22:23]
	v_fma_f32 v19, s11, v239, v19
	v_pk_mov_b32 v[160:161], v[158:159], v[156:157] op_sel:[1,0]
	v_mov_b32_e32 v159, v157
	v_pk_add_f32 v[156:157], v[160:161], v[158:159]
	v_fma_f32 v18, s11, v239, v18
	v_fma_f32 v21, s11, v239, v21
	v_fmac_f32_e32 v20, s11, v239
	v_add_f32_e32 v165, v156, v157
	v_pk_mul_f32 v[156:157], v[20:21], v[20:21]
	v_pk_mul_f32 v[158:159], v[18:19], v[18:19]
	v_fma_f32 v15, s29, v239, v15
	v_pk_mov_b32 v[160:161], v[158:159], v[156:157] op_sel:[1,0]
	v_mov_b32_e32 v159, v157
	v_pk_add_f32 v[156:157], v[160:161], v[158:159]
	v_fma_f32 v14, s29, v239, v14
	v_fma_f32 v17, s29, v239, v17
	v_fmac_f32_e32 v16, s29, v239
	v_add_f32_e32 v166, v156, v157
	v_pk_mul_f32 v[156:157], v[16:17], v[16:17]
	v_pk_mul_f32 v[158:159], v[14:15], v[14:15]
	v_fma_f32 v11, s55, v239, v11
	v_pk_mov_b32 v[160:161], v[158:159], v[156:157] op_sel:[1,0]
	v_mov_b32_e32 v159, v157
	v_pk_add_f32 v[156:157], v[160:161], v[158:159]
	v_fma_f32 v10, s55, v239, v10
	v_fma_f32 v13, s55, v239, v13
	v_fmac_f32_e32 v12, s55, v239
	v_add_f32_e32 v167, v156, v157
	v_pk_mul_f32 v[156:157], v[12:13], v[12:13]
	v_pk_mul_f32 v[158:159], v[10:11], v[10:11]
	v_add_f32_dpp v105, v105, v105 quad_perm:[1,0,3,2] row_mask:0xf bank_mask:0xf bound_ctrl:1
	v_pk_mov_b32 v[160:161], v[158:159], v[156:157] op_sel:[1,0]
	v_mov_b32_e32 v159, v157
	v_pk_add_f32 v[156:157], v[160:161], v[158:159]
	v_add_f32_dpp v105, v105, v105 quad_perm:[2,3,0,1] row_mask:0xf bank_mask:0xf bound_ctrl:1
	v_add_f32_e32 v156, v156, v157
	v_add_f32_dpp v157, v162, v162 quad_perm:[1,0,3,2] row_mask:0xf bank_mask:0xf bound_ctrl:1
	v_add_f32_dpp v105, v105, v105 row_half_mirror row_mask:0xf bank_mask:0xf bound_ctrl:1
	v_add_f32_dpp v158, v163, v163 quad_perm:[1,0,3,2] row_mask:0xf bank_mask:0xf bound_ctrl:1
	v_add_f32_dpp v157, v157, v157 quad_perm:[2,3,0,1] row_mask:0xf bank_mask:0xf bound_ctrl:1
	v_add_f32_dpp v105, v105, v105 row_mirror row_mask:0xf bank_mask:0xf bound_ctrl:1
	s_nop 0
	v_add_f32_dpp v157, v157, v157 row_half_mirror row_mask:0xf bank_mask:0xf bound_ctrl:1
	v_add_f32_dpp v158, v158, v158 quad_perm:[2,3,0,1] row_mask:0xf bank_mask:0xf bound_ctrl:1
	v_add_f32_dpp v105, v105, v105 row_bcast:15 row_mask:0xa bank_mask:0xf
	v_add_f32_dpp v157, v157, v157 row_mirror row_mask:0xf bank_mask:0xf bound_ctrl:1
	v_add_f32_dpp v159, v164, v164 quad_perm:[1,0,3,2] row_mask:0xf bank_mask:0xf bound_ctrl:1
	v_add_f32_dpp v158, v158, v158 row_half_mirror row_mask:0xf bank_mask:0xf bound_ctrl:1
	v_add_f32_dpp v157, v157, v157 row_bcast:15 row_mask:0xa bank_mask:0xf
	v_add_f32_dpp v159, v159, v159 quad_perm:[2,3,0,1] row_mask:0xf bank_mask:0xf bound_ctrl:1
	v_add_f32_dpp v158, v158, v158 row_mirror row_mask:0xf bank_mask:0xf bound_ctrl:1
	v_add_f32_dpp v160, v165, v165 quad_perm:[1,0,3,2] row_mask:0xf bank_mask:0xf bound_ctrl:1
	v_add_f32_dpp v159, v159, v159 row_half_mirror row_mask:0xf bank_mask:0xf bound_ctrl:1
	v_add_f32_dpp v158, v158, v158 row_bcast:15 row_mask:0xa bank_mask:0xf
	v_add_f32_dpp v160, v160, v160 quad_perm:[2,3,0,1] row_mask:0xf bank_mask:0xf bound_ctrl:1
	v_add_f32_dpp v159, v159, v159 row_mirror row_mask:0xf bank_mask:0xf bound_ctrl:1
	v_add_f32_dpp v161, v166, v166 quad_perm:[1,0,3,2] row_mask:0xf bank_mask:0xf bound_ctrl:1
	v_add_f32_dpp v160, v160, v160 row_half_mirror row_mask:0xf bank_mask:0xf bound_ctrl:1
	v_add_f32_dpp v159, v159, v159 row_bcast:15 row_mask:0xa bank_mask:0xf
	v_add_f32_dpp v161, v161, v161 quad_perm:[2,3,0,1] row_mask:0xf bank_mask:0xf bound_ctrl:1
	v_add_f32_dpp v160, v160, v160 row_mirror row_mask:0xf bank_mask:0xf bound_ctrl:1
	v_add_f32_dpp v162, v167, v167 quad_perm:[1,0,3,2] row_mask:0xf bank_mask:0xf bound_ctrl:1
	v_add_f32_dpp v161, v161, v161 row_half_mirror row_mask:0xf bank_mask:0xf bound_ctrl:1
	v_add_f32_dpp v160, v160, v160 row_bcast:15 row_mask:0xa bank_mask:0xf
	v_add_f32_dpp v162, v162, v162 quad_perm:[2,3,0,1] row_mask:0xf bank_mask:0xf bound_ctrl:1
	v_add_f32_dpp v161, v161, v161 row_mirror row_mask:0xf bank_mask:0xf bound_ctrl:1
	v_add_f32_dpp v156, v156, v156 quad_perm:[1,0,3,2] row_mask:0xf bank_mask:0xf bound_ctrl:1
	v_add_f32_dpp v162, v162, v162 row_half_mirror row_mask:0xf bank_mask:0xf bound_ctrl:1
	v_add_f32_dpp v161, v161, v161 row_bcast:15 row_mask:0xa bank_mask:0xf
	v_add_f32_dpp v156, v156, v156 quad_perm:[2,3,0,1] row_mask:0xf bank_mask:0xf bound_ctrl:1
	v_add_f32_dpp v162, v162, v162 row_mirror row_mask:0xf bank_mask:0xf bound_ctrl:1
	s_nop 0
	v_add_f32_dpp v156, v156, v156 row_half_mirror row_mask:0xf bank_mask:0xf bound_ctrl:1
	s_add_i32 s8, s28, -8
	v_add_f32_dpp v162, v162, v162 row_bcast:15 row_mask:0xa bank_mask:0xf
	v_add_f32_dpp v156, v156, v156 row_mirror row_mask:0xf bank_mask:0xf bound_ctrl:1
	s_ashr_i32 s9, s8, 31
	s_lshl_b64 s[8:9], s[8:9], 11
	v_add_f32_dpp v156, v156, v156 row_bcast:15 row_mask:0xa bank_mask:0xf
	s_add_u32 s8, s76, s8
	s_addc_u32 s9, s77, s9
	v_add_f32_dpp v105, v105, v105 row_bcast:31 row_mask:0xc bank_mask:0xf
	s_nop 0
	v_readlane_b32 s6, v105, 63
	s_ashr_i32 s29, s28, 31
	v_add_f32_dpp v157, v157, v157 row_bcast:31 row_mask:0xc bank_mask:0xf
	v_fma_f32 v105, s6, v235, v225
	v_readlane_b32 s10, v157, 63
	v_add_f32_dpp v158, v158, v158 row_bcast:31 row_mask:0xc bank_mask:0xf
	s_nop 0
	v_readlane_b32 s11, v158, 63
	s_nop 0
	v_add_f32_dpp v159, v159, v159 row_bcast:31 row_mask:0xc bank_mask:0xf
	s_nop 0
	v_readlane_b32 s57, v159, 63
	s_nop 0
	v_add_f32_dpp v160, v160, v160 row_bcast:31 row_mask:0xc bank_mask:0xf
	s_nop 0
	v_readlane_b32 s56, v160, 63
	s_nop 0
	v_add_f32_dpp v161, v161, v161 row_bcast:31 row_mask:0xc bank_mask:0xf
	s_nop 0
	v_readlane_b32 s55, v161, 63
	s_nop 0
	v_add_f32_dpp v162, v162, v162 row_bcast:31 row_mask:0xc bank_mask:0xf
	v_mov_b32_e32 v163, v131
	v_readlane_b32 s7, v162, 63
	s_nop 0
	v_mov_b32_dpp v163, v156 row_bcast:31 row_mask:0xc bank_mask:0xf
	v_add_f32_e32 v163, v156, v163
	v_rsq_f32_e32 v156, v105
	v_readlane_b32 s6, v163, 63
	v_pk_mul_f32 v[38:39], v[38:39], v[156:157] op_sel_hi:[1,0]
	s_nop 0
	v_pk_fma_f32 v[38:39], v[2:3], v[38:39], v[6:7]
	v_pk_mul_f32 v[40:41], v[40:41], v[156:157] op_sel_hi:[1,0]
	v_mul_f32_e32 v105, 0xbfb8aa3b, v38
	v_exp_f32_e32 v105, v105
	v_mul_f32_e32 v156, 0xbfb8aa3b, v39
	v_exp_f32_e32 v157, v156
	v_pk_fma_f32 v[40:41], v[4:5], v[40:41], v[8:9]
	v_add_f32_e32 v105, 1.0, v105
	v_rcp_f32_e32 v156, v105
	v_add_f32_e32 v105, 1.0, v157
	v_mul_f32_e32 v157, 0xbfb8aa3b, v40
	v_exp_f32_e32 v158, v157
	v_mul_f32_e32 v157, 0xbfb8aa3b, v41
	v_exp_f32_e32 v159, v157
	v_rcp_f32_e32 v157, v105
	v_add_f32_e32 v105, 1.0, v158
	v_rcp_f32_e32 v158, v105
	v_add_f32_e32 v105, 1.0, v159
	v_rcp_f32_e32 v159, v105
	v_pk_mul_f32 v[38:39], v[38:39], v[156:157]
	v_lshlrev_b32_e32 v105, 3, v130
	v_cvt_pk_bf16_f32 v38, v38, v39
	v_pk_mul_f32 v[40:41], v[40:41], v[158:159]
	v_cvt_pk_bf16_f32 v39, v40, v41
	v_fma_f32 v40, s10, v235, v225
	v_rsq_f32_e32 v40, v40
	global_store_dwordx2 v105, v[38:39], s[8:9] offset:512
	s_lshl_b64 s[8:9], s[28:29], 11
	s_add_u32 s8, s76, s8
	v_pk_mul_f32 v[36:37], v[36:37], v[40:41] op_sel_hi:[1,0]
	v_pk_mul_f32 v[34:35], v[34:35], v[40:41] op_sel_hi:[1,0]
	v_pk_fma_f32 v[36:37], v[4:5], v[36:37], v[8:9]
	v_pk_fma_f32 v[34:35], v[2:3], v[34:35], v[6:7]
	v_mul_f32_e32 v130, 0xbfb8aa3b, v36
	v_pk_mul_f32 v[40:41], v[34:35], s[96:97] op_sel_hi:[1,0]
	v_exp_f32_e32 v130, v130
	v_mul_f32_e32 v156, 0xbfb8aa3b, v37
	v_exp_f32_e32 v40, v40
	v_exp_f32_e32 v41, v41
	v_exp_f32_e32 v157, v156
	v_add_f32_e32 v130, 1.0, v130
	v_pk_add_f32 v[40:41], v[40:41], 1.0 op_sel_hi:[1,0]
	v_rcp_f32_e32 v156, v130
	v_add_f32_e32 v130, 1.0, v157
	v_rcp_f32_e32 v40, v40
	v_rcp_f32_e32 v41, v41
	v_rcp_f32_e32 v157, v130
	s_addc_u32 s9, s77, s9
	v_pk_mul_f32 v[34:35], v[34:35], v[40:41]
	v_pk_mul_f32 v[36:37], v[36:37], v[156:157]
	v_cvt_pk_bf16_f32 v34, v34, v35
	v_cvt_pk_bf16_f32 v35, v36, v37
	v_fma_f32 v36, s11, v235, v225
	v_rsq_f32_e32 v36, v36
	global_store_dwordx2 v105, v[34:35], s[8:9] offset:512
	s_add_i32 s8, s28, 8
	s_ashr_i32 s9, s8, 31
	v_pk_mul_f32 v[30:31], v[30:31], v[36:37] op_sel_hi:[1,0]
	v_pk_mul_f32 v[32:33], v[32:33], v[36:37] op_sel_hi:[1,0]
	v_pk_fma_f32 v[30:31], v[2:3], v[30:31], v[6:7]
	v_pk_fma_f32 v[32:33], v[4:5], v[32:33], v[8:9]
	v_pk_mul_f32 v[36:37], v[30:31], s[96:97] op_sel_hi:[1,0]
	v_pk_mul_f32 v[38:39], v[32:33], s[96:97] op_sel_hi:[1,0]
	v_exp_f32_e32 v36, v36
	v_exp_f32_e32 v37, v37
	v_exp_f32_e32 v38, v38
	v_exp_f32_e32 v39, v39
	v_pk_add_f32 v[36:37], v[36:37], 1.0 op_sel_hi:[1,0]
	v_pk_add_f32 v[38:39], v[38:39], 1.0 op_sel_hi:[1,0]
	v_rcp_f32_e32 v36, v36
	v_rcp_f32_e32 v37, v37
	v_rcp_f32_e32 v38, v38
	v_rcp_f32_e32 v39, v39
	s_lshl_b64 s[8:9], s[8:9], 11
	v_pk_mul_f32 v[30:31], v[30:31], v[36:37]
	s_add_u32 s8, s76, s8
	v_pk_mul_f32 v[32:33], v[32:33], v[38:39]
	v_cvt_pk_bf16_f32 v30, v30, v31
	v_cvt_pk_bf16_f32 v31, v32, v33
	v_fma_f32 v32, s57, v235, v225
	v_rsq_f32_e32 v32, v32
	s_addc_u32 s9, s77, s9
	global_store_dwordx2 v105, v[30:31], s[8:9] offset:512
	s_add_i32 s8, s28, 16
	v_pk_mul_f32 v[26:27], v[26:27], v[32:33] op_sel_hi:[1,0]
	v_pk_mul_f32 v[28:29], v[28:29], v[32:33] op_sel_hi:[1,0]
	v_pk_fma_f32 v[26:27], v[2:3], v[26:27], v[6:7]
	v_pk_fma_f32 v[28:29], v[4:5], v[28:29], v[8:9]
	v_pk_mul_f32 v[32:33], v[26:27], s[96:97] op_sel_hi:[1,0]
	v_pk_mul_f32 v[34:35], v[28:29], s[96:97] op_sel_hi:[1,0]
	v_exp_f32_e32 v32, v32
	v_exp_f32_e32 v33, v33
	v_exp_f32_e32 v34, v34
	v_exp_f32_e32 v35, v35
	v_pk_add_f32 v[32:33], v[32:33], 1.0 op_sel_hi:[1,0]
	v_pk_add_f32 v[34:35], v[34:35], 1.0 op_sel_hi:[1,0]
	v_rcp_f32_e32 v32, v32
	v_rcp_f32_e32 v33, v33
	v_rcp_f32_e32 v34, v34
	v_rcp_f32_e32 v35, v35
	s_ashr_i32 s9, s8, 31
	v_pk_mul_f32 v[26:27], v[26:27], v[32:33]
	s_lshl_b64 s[8:9], s[8:9], 11
	v_pk_mul_f32 v[28:29], v[28:29], v[34:35]
	v_cvt_pk_bf16_f32 v26, v26, v27
	v_cvt_pk_bf16_f32 v27, v28, v29
	v_fma_f32 v28, s56, v235, v225
	v_rsq_f32_e32 v28, v28
	s_add_u32 s8, s76, s8
	s_addc_u32 s9, s77, s9
	global_store_dwordx2 v105, v[26:27], s[8:9] offset:512
	v_pk_mul_f32 v[22:23], v[22:23], v[28:29] op_sel_hi:[1,0]
	v_pk_mul_f32 v[24:25], v[24:25], v[28:29] op_sel_hi:[1,0]
	v_pk_fma_f32 v[22:23], v[2:3], v[22:23], v[6:7]
	v_pk_fma_f32 v[24:25], v[4:5], v[24:25], v[8:9]
	v_pk_mul_f32 v[28:29], v[22:23], s[96:97] op_sel_hi:[1,0]
	v_pk_mul_f32 v[30:31], v[24:25], s[96:97] op_sel_hi:[1,0]
	v_exp_f32_e32 v28, v28
	v_exp_f32_e32 v29, v29
	v_exp_f32_e32 v30, v30
	v_exp_f32_e32 v31, v31
	v_pk_add_f32 v[28:29], v[28:29], 1.0 op_sel_hi:[1,0]
	v_pk_add_f32 v[30:31], v[30:31], 1.0 op_sel_hi:[1,0]
	v_rcp_f32_e32 v28, v28
	v_rcp_f32_e32 v29, v29
	v_rcp_f32_e32 v30, v30
	v_rcp_f32_e32 v31, v31
	s_add_i32 s8, s28, 24
	v_pk_mul_f32 v[22:23], v[22:23], v[28:29]
	s_ashr_i32 s9, s8, 31
	v_pk_mul_f32 v[24:25], v[24:25], v[30:31]
	v_cvt_pk_bf16_f32 v22, v22, v23
	v_cvt_pk_bf16_f32 v23, v24, v25
	v_fma_f32 v24, s55, v235, v225
	v_rsq_f32_e32 v24, v24
	s_lshl_b64 s[8:9], s[8:9], 11
	s_add_u32 s8, s76, s8
	s_addc_u32 s9, s77, s9
	v_pk_mul_f32 v[18:19], v[18:19], v[24:25] op_sel_hi:[1,0]
	v_pk_mul_f32 v[20:21], v[20:21], v[24:25] op_sel_hi:[1,0]
	v_pk_fma_f32 v[18:19], v[2:3], v[18:19], v[6:7]
	v_pk_fma_f32 v[20:21], v[4:5], v[20:21], v[8:9]
	v_pk_mul_f32 v[24:25], v[18:19], s[96:97] op_sel_hi:[1,0]
	v_pk_mul_f32 v[26:27], v[20:21], s[96:97] op_sel_hi:[1,0]
	v_exp_f32_e32 v24, v24
	v_exp_f32_e32 v25, v25
	v_exp_f32_e32 v26, v26
	v_exp_f32_e32 v27, v27
	v_pk_add_f32 v[24:25], v[24:25], 1.0 op_sel_hi:[1,0]
	v_pk_add_f32 v[26:27], v[26:27], 1.0 op_sel_hi:[1,0]
	v_rcp_f32_e32 v24, v24
	v_rcp_f32_e32 v25, v25
	v_rcp_f32_e32 v26, v26
	v_rcp_f32_e32 v27, v27
	global_store_dwordx2 v105, v[22:23], s[8:9] offset:512
	v_pk_mul_f32 v[18:19], v[18:19], v[24:25]
	s_add_i32 s8, s28, 32
	v_pk_mul_f32 v[20:21], v[20:21], v[26:27]
	v_cvt_pk_bf16_f32 v18, v18, v19
	v_cvt_pk_bf16_f32 v19, v20, v21
	v_fma_f32 v20, s7, v235, v225
	v_rsq_f32_e32 v20, v20
	s_ashr_i32 s9, s8, 31
	s_lshl_b64 s[8:9], s[8:9], 11
	s_add_u32 s8, s76, s8
	v_pk_mul_f32 v[14:15], v[14:15], v[20:21] op_sel_hi:[1,0]
	v_pk_mul_f32 v[16:17], v[16:17], v[20:21] op_sel_hi:[1,0]
	v_pk_fma_f32 v[14:15], v[2:3], v[14:15], v[6:7]
	v_pk_fma_f32 v[16:17], v[4:5], v[16:17], v[8:9]
	v_pk_mul_f32 v[20:21], v[14:15], s[96:97] op_sel_hi:[1,0]
	v_pk_mul_f32 v[22:23], v[16:17], s[96:97] op_sel_hi:[1,0]
	v_exp_f32_e32 v20, v20
	v_exp_f32_e32 v21, v21
	v_exp_f32_e32 v22, v22
	v_exp_f32_e32 v23, v23
	v_pk_add_f32 v[20:21], v[20:21], 1.0 op_sel_hi:[1,0]
	v_pk_add_f32 v[22:23], v[22:23], 1.0 op_sel_hi:[1,0]
	v_rcp_f32_e32 v20, v20
	v_rcp_f32_e32 v21, v21
	v_rcp_f32_e32 v22, v22
	v_rcp_f32_e32 v23, v23
	s_addc_u32 s9, s77, s9
	v_pk_mul_f32 v[14:15], v[14:15], v[20:21]
	global_store_dwordx2 v105, v[18:19], s[8:9] offset:512
	v_pk_mul_f32 v[16:17], v[16:17], v[22:23]
	v_cvt_pk_bf16_f32 v14, v14, v15
	v_cvt_pk_bf16_f32 v15, v16, v17
	v_fma_f32 v16, s6, v235, v225
	v_rsq_f32_e32 v16, v16
	s_add_i32 s8, s28, 40
	s_ashr_i32 s9, s8, 31
	s_lshl_b64 s[6:7], s[8:9], 11
	v_pk_mul_f32 v[10:11], v[10:11], v[16:17] op_sel_hi:[1,0]
	v_pk_mul_f32 v[12:13], v[12:13], v[16:17] op_sel_hi:[1,0]
	v_pk_fma_f32 v[10:11], v[2:3], v[10:11], v[6:7]
	v_pk_fma_f32 v[12:13], v[4:5], v[12:13], v[8:9]
	v_pk_mul_f32 v[16:17], v[10:11], s[96:97] op_sel_hi:[1,0]
	v_pk_mul_f32 v[18:19], v[12:13], s[96:97] op_sel_hi:[1,0]
	v_exp_f32_e32 v16, v16
	v_exp_f32_e32 v17, v17
	v_exp_f32_e32 v18, v18
	v_exp_f32_e32 v19, v19
	s_add_u32 s6, s76, s6
	v_pk_add_f32 v[16:17], v[16:17], 1.0 op_sel_hi:[1,0]
	v_pk_add_f32 v[18:19], v[18:19], 1.0 op_sel_hi:[1,0]
	s_addc_u32 s7, s77, s7
	v_rcp_f32_e32 v16, v16
	v_rcp_f32_e32 v17, v17
	v_rcp_f32_e32 v18, v18
	v_rcp_f32_e32 v19, v19
	global_store_dwordx2 v105, v[14:15], s[6:7] offset:512
	s_add_i32 s6, s28, 48
	s_ashr_i32 s7, s6, 31
	s_lshl_b64 s[6:7], s[6:7], 11
	v_pk_mul_f32 v[10:11], v[10:11], v[16:17]
	v_pk_mul_f32 v[12:13], v[12:13], v[18:19]
	s_add_u32 s6, s76, s6
	v_cvt_pk_bf16_f32 v10, v10, v11
	v_cvt_pk_bf16_f32 v11, v12, v13
	s_addc_u32 s7, s77, s7
	s_add_i32 s54, s54, s60
	global_store_dwordx2 v105, v[10:11], s[6:7] offset:512
	s_add_i32 s6, s50, s54
	s_add_i32 s52, s52, s53
	s_cmpk_gt_i32 s6, 0x1ff
	s_barrier
	s_cbranch_scc1 .LBB0_282

.LBB0_270:
	s_waitcnt vmcnt(2)
	v_lshlrev_b32_e32 v12, 16, v154
	v_and_b32_e32 v13, 0xffff0000, v154
	v_lshlrev_b32_e32 v14, 16, v155
	v_and_b32_e32 v15, 0xffff0000, v155
	v_pk_mul_f32 v[12:13], v[12:13], s[96:97] op_sel_hi:[1,0]
	v_pk_mul_f32 v[14:15], v[14:15], s[96:97] op_sel_hi:[1,0]
	v_exp_f32_e32 v12, v12
	v_exp_f32_e32 v13, v13
	v_exp_f32_e32 v14, v14
	v_exp_f32_e32 v15, v15
	v_pk_add_f32 v[12:13], v[12:13], 1.0 op_sel_hi:[1,0]
	v_pk_add_f32 v[14:15], v[14:15], 1.0 op_sel_hi:[1,0]
	v_rcp_f32_e32 v12, v12
	v_rcp_f32_e32 v13, v13
	v_rcp_f32_e32 v14, v14
	v_rcp_f32_e32 v15, v15
	s_waitcnt vmcnt(1)
	v_and_b32_e32 v17, 0xffff0000, v152
	v_and_b32_e32 v19, 0xffff0000, v153
	v_lshlrev_b32_e32 v16, 16, v152
	v_lshlrev_b32_e32 v18, 16, v153
	s_cmp_ge_i32 s28, s7
	v_pk_mul_f32 v[14:15], v[14:15], v[18:19]
	v_pk_mul_f32 v[12:13], v[12:13], v[16:17]
	s_cselect_b64 vcc, -1, 0
	v_lshl_add_u32 v20, s28, 10, v11
	v_cndmask_b32_e32 v13, 0, v13, vcc
	v_cndmask_b32_e32 v12, 0, v12, vcc
	v_cndmask_b32_e32 v15, 0, v15, vcc
	v_cndmask_b32_e32 v14, 0, v14, vcc
	ds_write_b128 v20, v[12:15]
	s_cmpk_gt_i32 s28, 0x55
	s_cbranch_scc1 .LBB0_260
.LBB0_271:
	s_waitcnt vmcnt(4)
	v_lshlrev_b32_e32 v12, 16, v150
	v_and_b32_e32 v13, 0xffff0000, v150
	v_lshlrev_b32_e32 v14, 16, v151
	v_and_b32_e32 v15, 0xffff0000, v151
	v_pk_mul_f32 v[12:13], v[12:13], s[96:97] op_sel_hi:[1,0]
	v_pk_mul_f32 v[14:15], v[14:15], s[96:97] op_sel_hi:[1,0]
	v_exp_f32_e32 v12, v12
	v_exp_f32_e32 v13, v13
	v_exp_f32_e32 v14, v14
	v_exp_f32_e32 v15, v15
	v_pk_add_f32 v[12:13], v[12:13], 1.0 op_sel_hi:[1,0]
	v_pk_add_f32 v[14:15], v[14:15], 1.0 op_sel_hi:[1,0]
	v_rcp_f32_e32 v12, v12
	v_rcp_f32_e32 v13, v13
	v_rcp_f32_e32 v14, v14
	v_rcp_f32_e32 v15, v15
	s_add_i32 s8, s28, 8
	s_waitcnt vmcnt(3)
	v_and_b32_e32 v17, 0xffff0000, v148
	v_and_b32_e32 v19, 0xffff0000, v149
	v_lshlrev_b32_e32 v16, 16, v148
	v_lshlrev_b32_e32 v18, 16, v149
	s_cmp_ge_i32 s8, s7
	v_pk_mul_f32 v[14:15], v[14:15], v[18:19]
	v_pk_mul_f32 v[12:13], v[12:13], v[16:17]
	s_cselect_b64 vcc, -1, 0
	v_lshl_add_u32 v20, s8, 10, v11
	v_cndmask_b32_e32 v13, 0, v13, vcc
	v_cndmask_b32_e32 v12, 0, v12, vcc
	v_cndmask_b32_e32 v15, 0, v15, vcc
	v_cndmask_b32_e32 v14, 0, v14, vcc
	ds_write_b128 v20, v[12:15]
	s_cmpk_gt_i32 s28, 0x4d
	s_cbranch_scc1 .LBB0_261
.LBB0_272:
	s_waitcnt vmcnt(6)
	v_lshlrev_b32_e32 v12, 16, v146
	v_and_b32_e32 v13, 0xffff0000, v146
	v_lshlrev_b32_e32 v14, 16, v147
	v_and_b32_e32 v15, 0xffff0000, v147
	v_pk_mul_f32 v[12:13], v[12:13], s[96:97] op_sel_hi:[1,0]
	v_pk_mul_f32 v[14:15], v[14:15], s[96:97] op_sel_hi:[1,0]
	v_exp_f32_e32 v12, v12
	v_exp_f32_e32 v13, v13
	v_exp_f32_e32 v14, v14
	v_exp_f32_e32 v15, v15
	v_pk_add_f32 v[12:13], v[12:13], 1.0 op_sel_hi:[1,0]
	v_pk_add_f32 v[14:15], v[14:15], 1.0 op_sel_hi:[1,0]
	v_rcp_f32_e32 v12, v12
	v_rcp_f32_e32 v13, v13
	v_rcp_f32_e32 v14, v14
	v_rcp_f32_e32 v15, v15
	s_add_i32 s8, s28, 16
	s_waitcnt vmcnt(5)
	v_and_b32_e32 v17, 0xffff0000, v144
	v_and_b32_e32 v19, 0xffff0000, v145
	v_lshlrev_b32_e32 v16, 16, v144
	v_lshlrev_b32_e32 v18, 16, v145
	s_cmp_ge_i32 s8, s7
	v_pk_mul_f32 v[14:15], v[14:15], v[18:19]
	v_pk_mul_f32 v[12:13], v[12:13], v[16:17]
	s_cselect_b64 vcc, -1, 0
	v_lshl_add_u32 v20, s8, 10, v11
	v_cndmask_b32_e32 v13, 0, v13, vcc
	v_cndmask_b32_e32 v12, 0, v12, vcc
	v_cndmask_b32_e32 v15, 0, v15, vcc
	v_cndmask_b32_e32 v14, 0, v14, vcc
	ds_write_b128 v20, v[12:15]
	s_cmpk_gt_i32 s28, 0x45
	s_cbranch_scc1 .LBB0_262
.LBB0_273:
	s_waitcnt vmcnt(8)
	v_lshlrev_b32_e32 v12, 16, v142
	v_and_b32_e32 v13, 0xffff0000, v142
	v_lshlrev_b32_e32 v14, 16, v143
	v_and_b32_e32 v15, 0xffff0000, v143
	v_pk_mul_f32 v[12:13], v[12:13], s[96:97] op_sel_hi:[1,0]
	v_pk_mul_f32 v[14:15], v[14:15], s[96:97] op_sel_hi:[1,0]
	v_exp_f32_e32 v12, v12
	v_exp_f32_e32 v13, v13
	v_exp_f32_e32 v14, v14
	v_exp_f32_e32 v15, v15
	v_pk_add_f32 v[12:13], v[12:13], 1.0 op_sel_hi:[1,0]
	v_pk_add_f32 v[14:15], v[14:15], 1.0 op_sel_hi:[1,0]
	v_rcp_f32_e32 v12, v12
	v_rcp_f32_e32 v13, v13
	v_rcp_f32_e32 v14, v14
	v_rcp_f32_e32 v15, v15
	s_add_i32 s8, s28, 24
	s_waitcnt vmcnt(7)
	v_and_b32_e32 v17, 0xffff0000, v140
	v_and_b32_e32 v19, 0xffff0000, v141
	v_lshlrev_b32_e32 v16, 16, v140
	v_lshlrev_b32_e32 v18, 16, v141
	s_cmp_ge_i32 s8, s7
	v_pk_mul_f32 v[14:15], v[14:15], v[18:19]
	v_pk_mul_f32 v[12:13], v[12:13], v[16:17]
	s_cselect_b64 vcc, -1, 0
	v_lshl_add_u32 v20, s8, 10, v11
	v_cndmask_b32_e32 v13, 0, v13, vcc
	v_cndmask_b32_e32 v12, 0, v12, vcc
	v_cndmask_b32_e32 v15, 0, v15, vcc
	v_cndmask_b32_e32 v14, 0, v14, vcc
	ds_write_b128 v20, v[12:15]
	s_cmp_gt_i32 s28, 61
	s_cbranch_scc1 .LBB0_263
.LBB0_274:
	s_waitcnt vmcnt(10)
	v_lshlrev_b32_e32 v12, 16, v138
	v_and_b32_e32 v13, 0xffff0000, v138
	v_lshlrev_b32_e32 v14, 16, v139
	v_and_b32_e32 v15, 0xffff0000, v139
	v_pk_mul_f32 v[12:13], v[12:13], s[96:97] op_sel_hi:[1,0]
	v_pk_mul_f32 v[14:15], v[14:15], s[96:97] op_sel_hi:[1,0]
	v_exp_f32_e32 v12, v12
	v_exp_f32_e32 v13, v13
	v_exp_f32_e32 v14, v14
	v_exp_f32_e32 v15, v15
	v_pk_add_f32 v[12:13], v[12:13], 1.0 op_sel_hi:[1,0]
	v_pk_add_f32 v[14:15], v[14:15], 1.0 op_sel_hi:[1,0]
	v_rcp_f32_e32 v12, v12
	v_rcp_f32_e32 v13, v13
	v_rcp_f32_e32 v14, v14
	v_rcp_f32_e32 v15, v15
	s_add_i32 s8, s28, 32
	s_waitcnt vmcnt(9)
	v_and_b32_e32 v17, 0xffff0000, v136
	v_and_b32_e32 v19, 0xffff0000, v137
	v_lshlrev_b32_e32 v16, 16, v136
	v_lshlrev_b32_e32 v18, 16, v137
	s_cmp_ge_i32 s8, s7
	v_pk_mul_f32 v[14:15], v[14:15], v[18:19]
	v_pk_mul_f32 v[12:13], v[12:13], v[16:17]
	s_cselect_b64 vcc, -1, 0
	v_lshl_add_u32 v20, s8, 10, v11
	v_cndmask_b32_e32 v13, 0, v13, vcc
	v_cndmask_b32_e32 v12, 0, v12, vcc
	v_cndmask_b32_e32 v15, 0, v15, vcc
	v_cndmask_b32_e32 v14, 0, v14, vcc
	ds_write_b128 v20, v[12:15]
	s_cmp_gt_i32 s28, 53
	s_cbranch_scc1 .LBB0_264
.LBB0_275:
	s_waitcnt vmcnt(12)
	v_lshlrev_b32_e32 v12, 16, v134
	v_and_b32_e32 v13, 0xffff0000, v134
	v_lshlrev_b32_e32 v14, 16, v135
	v_and_b32_e32 v15, 0xffff0000, v135
	v_pk_mul_f32 v[12:13], v[12:13], s[96:97] op_sel_hi:[1,0]
	v_pk_mul_f32 v[14:15], v[14:15], s[96:97] op_sel_hi:[1,0]
	v_exp_f32_e32 v12, v12
	v_exp_f32_e32 v13, v13
	v_exp_f32_e32 v14, v14
	v_exp_f32_e32 v15, v15
	v_pk_add_f32 v[12:13], v[12:13], 1.0 op_sel_hi:[1,0]
	v_pk_add_f32 v[14:15], v[14:15], 1.0 op_sel_hi:[1,0]
	v_rcp_f32_e32 v12, v12
	v_rcp_f32_e32 v13, v13
	v_rcp_f32_e32 v14, v14
	v_rcp_f32_e32 v15, v15
	s_add_i32 s8, s28, 40
	s_waitcnt vmcnt(11)
	v_and_b32_e32 v17, 0xffff0000, v132
	v_and_b32_e32 v19, 0xffff0000, v133
	v_lshlrev_b32_e32 v16, 16, v132
	v_lshlrev_b32_e32 v18, 16, v133
	s_cmp_ge_i32 s8, s7
	v_pk_mul_f32 v[14:15], v[14:15], v[18:19]
	v_pk_mul_f32 v[12:13], v[12:13], v[16:17]
	s_cselect_b64 vcc, -1, 0
	v_lshl_add_u32 v20, s8, 10, v11
	v_cndmask_b32_e32 v13, 0, v13, vcc
	v_cndmask_b32_e32 v12, 0, v12, vcc
	v_cndmask_b32_e32 v15, 0, v15, vcc
	v_cndmask_b32_e32 v14, 0, v14, vcc
	ds_write_b128 v20, v[12:15]
	s_cmp_gt_i32 s28, 45
	s_cbranch_scc1 .LBB0_265
.LBB0_276:
	s_waitcnt vmcnt(14)
	v_lshlrev_b32_e32 v12, 16, v128
	v_and_b32_e32 v13, 0xffff0000, v128
	v_lshlrev_b32_e32 v14, 16, v129
	v_and_b32_e32 v15, 0xffff0000, v129
	v_pk_mul_f32 v[12:13], v[12:13], s[96:97] op_sel_hi:[1,0]
	v_pk_mul_f32 v[14:15], v[14:15], s[96:97] op_sel_hi:[1,0]
	v_exp_f32_e32 v12, v12
	v_exp_f32_e32 v13, v13
	v_exp_f32_e32 v14, v14
	v_exp_f32_e32 v15, v15
	v_pk_add_f32 v[12:13], v[12:13], 1.0 op_sel_hi:[1,0]
	v_pk_add_f32 v[14:15], v[14:15], 1.0 op_sel_hi:[1,0]
	v_rcp_f32_e32 v12, v12
	v_rcp_f32_e32 v13, v13
	v_rcp_f32_e32 v14, v14
	v_rcp_f32_e32 v15, v15
	s_add_i32 s8, s28, 48
	s_waitcnt vmcnt(13)
	v_and_b32_e32 v17, 0xffff0000, v126
	v_and_b32_e32 v19, 0xffff0000, v127
	v_lshlrev_b32_e32 v16, 16, v126
	v_lshlrev_b32_e32 v18, 16, v127
	s_cmp_ge_i32 s8, s7
	v_pk_mul_f32 v[14:15], v[14:15], v[18:19]
	v_pk_mul_f32 v[12:13], v[12:13], v[16:17]
	s_cselect_b64 vcc, -1, 0
	v_lshl_add_u32 v20, s8, 10, v11
	v_cndmask_b32_e32 v13, 0, v13, vcc
	v_cndmask_b32_e32 v12, 0, v12, vcc
	v_cndmask_b32_e32 v15, 0, v15, vcc
	v_cndmask_b32_e32 v14, 0, v14, vcc
	ds_write_b128 v20, v[12:15]
	s_cmp_gt_i32 s28, 37
	s_cbranch_scc1 .LBB0_266
.LBB0_277:
	s_waitcnt vmcnt(16)
	v_lshlrev_b32_e32 v12, 16, v124
	v_and_b32_e32 v13, 0xffff0000, v124
	v_lshlrev_b32_e32 v14, 16, v125
	v_and_b32_e32 v15, 0xffff0000, v125
	v_pk_mul_f32 v[12:13], v[12:13], s[96:97] op_sel_hi:[1,0]
	v_pk_mul_f32 v[14:15], v[14:15], s[96:97] op_sel_hi:[1,0]
	v_exp_f32_e32 v12, v12
	v_exp_f32_e32 v13, v13
	v_exp_f32_e32 v14, v14
	v_exp_f32_e32 v15, v15
	v_pk_add_f32 v[12:13], v[12:13], 1.0 op_sel_hi:[1,0]
	v_pk_add_f32 v[14:15], v[14:15], 1.0 op_sel_hi:[1,0]
	v_rcp_f32_e32 v12, v12
	v_rcp_f32_e32 v13, v13
	v_rcp_f32_e32 v14, v14
	v_rcp_f32_e32 v15, v15
	s_add_i32 s8, s28, 56
	s_waitcnt vmcnt(15)
	v_and_b32_e32 v17, 0xffff0000, v122
	v_and_b32_e32 v19, 0xffff0000, v123
	v_lshlrev_b32_e32 v16, 16, v122
	v_lshlrev_b32_e32 v18, 16, v123
	s_cmp_ge_i32 s8, s7
	v_pk_mul_f32 v[14:15], v[14:15], v[18:19]
	v_pk_mul_f32 v[12:13], v[12:13], v[16:17]
	s_cselect_b64 vcc, -1, 0
	v_lshl_add_u32 v20, s8, 10, v11
	v_cndmask_b32_e32 v13, 0, v13, vcc
	v_cndmask_b32_e32 v12, 0, v12, vcc
	v_cndmask_b32_e32 v15, 0, v15, vcc
	v_cndmask_b32_e32 v14, 0, v14, vcc
	ds_write_b128 v20, v[12:15]
	s_cmp_gt_i32 s28, 29
	s_cbranch_scc1 .LBB0_267
.LBB0_278:
	s_waitcnt vmcnt(14)
	v_lshlrev_b32_e32 v12, 16, v120
	v_and_b32_e32 v13, 0xffff0000, v120
	v_lshlrev_b32_e32 v14, 16, v121
	v_and_b32_e32 v15, 0xffff0000, v121
	v_pk_mul_f32 v[12:13], v[12:13], s[96:97] op_sel_hi:[1,0]
	v_pk_mul_f32 v[14:15], v[14:15], s[96:97] op_sel_hi:[1,0]
	v_exp_f32_e32 v12, v12
	v_exp_f32_e32 v13, v13
	v_exp_f32_e32 v14, v14
	v_exp_f32_e32 v15, v15
	v_pk_add_f32 v[12:13], v[12:13], 1.0 op_sel_hi:[1,0]
	v_pk_add_f32 v[14:15], v[14:15], 1.0 op_sel_hi:[1,0]
	v_rcp_f32_e32 v12, v12
	v_rcp_f32_e32 v13, v13
	v_rcp_f32_e32 v14, v14
	v_rcp_f32_e32 v15, v15
	s_add_i32 s8, s28, 64
	s_waitcnt vmcnt(17)
	v_and_b32_e32 v17, 0xffff0000, v118
	v_and_b32_e32 v19, 0xffff0000, v119
	v_lshlrev_b32_e32 v16, 16, v118
	v_lshlrev_b32_e32 v18, 16, v119
	s_cmp_ge_i32 s8, s7
	v_pk_mul_f32 v[14:15], v[14:15], v[18:19]
	v_pk_mul_f32 v[12:13], v[12:13], v[16:17]
	s_cselect_b64 vcc, -1, 0
	v_lshl_add_u32 v20, s8, 10, v11
	v_cndmask_b32_e32 v13, 0, v13, vcc
	v_cndmask_b32_e32 v12, 0, v12, vcc
	v_cndmask_b32_e32 v15, 0, v15, vcc
	v_cndmask_b32_e32 v14, 0, v14, vcc
	ds_write_b128 v20, v[12:15]
	s_cmp_gt_i32 s28, 21
	s_cbranch_scc1 .LBB0_268
.LBB0_279:
	s_waitcnt vmcnt(12)
	v_lshlrev_b32_e32 v12, 16, v116
	v_and_b32_e32 v13, 0xffff0000, v116
	v_lshlrev_b32_e32 v14, 16, v117
	v_and_b32_e32 v15, 0xffff0000, v117
	v_pk_mul_f32 v[12:13], v[12:13], s[96:97] op_sel_hi:[1,0]
	v_pk_mul_f32 v[14:15], v[14:15], s[96:97] op_sel_hi:[1,0]
	v_exp_f32_e32 v12, v12
	v_exp_f32_e32 v13, v13
	v_exp_f32_e32 v14, v14
	v_exp_f32_e32 v15, v15
	v_pk_add_f32 v[12:13], v[12:13], 1.0 op_sel_hi:[1,0]
	v_pk_add_f32 v[14:15], v[14:15], 1.0 op_sel_hi:[1,0]
	v_rcp_f32_e32 v12, v12
	v_rcp_f32_e32 v13, v13
	v_rcp_f32_e32 v14, v14
	v_rcp_f32_e32 v15, v15
	s_add_i32 s8, s28, 0x48
	s_waitcnt vmcnt(19)
	v_and_b32_e32 v17, 0xffff0000, v114
	v_and_b32_e32 v19, 0xffff0000, v115
	v_lshlrev_b32_e32 v16, 16, v114
	v_lshlrev_b32_e32 v18, 16, v115
	s_cmp_ge_i32 s8, s7
	v_pk_mul_f32 v[14:15], v[14:15], v[18:19]
	v_pk_mul_f32 v[12:13], v[12:13], v[16:17]
	s_cselect_b64 vcc, -1, 0
	v_lshl_add_u32 v20, s8, 10, v11
	v_cndmask_b32_e32 v13, 0, v13, vcc
	v_cndmask_b32_e32 v12, 0, v12, vcc
	v_cndmask_b32_e32 v15, 0, v15, vcc
	v_cndmask_b32_e32 v14, 0, v14, vcc
	ds_write_b128 v20, v[12:15]
	s_cmp_gt_i32 s28, 13
	s_cbranch_scc1 .LBB0_269
.LBB0_280:
	s_waitcnt vmcnt(10)
	v_lshlrev_b32_e32 v12, 16, v112
	v_and_b32_e32 v13, 0xffff0000, v112
	v_lshlrev_b32_e32 v14, 16, v113
	v_and_b32_e32 v15, 0xffff0000, v113
	v_pk_mul_f32 v[12:13], v[12:13], s[96:97] op_sel_hi:[1,0]
	v_pk_mul_f32 v[14:15], v[14:15], s[96:97] op_sel_hi:[1,0]
	v_exp_f32_e32 v12, v12
	v_exp_f32_e32 v13, v13
	v_exp_f32_e32 v14, v14
	v_exp_f32_e32 v15, v15
	v_pk_add_f32 v[12:13], v[12:13], 1.0 op_sel_hi:[1,0]
	v_pk_add_f32 v[14:15], v[14:15], 1.0 op_sel_hi:[1,0]
	v_rcp_f32_e32 v12, v12
	v_rcp_f32_e32 v13, v13
	v_rcp_f32_e32 v14, v14
	v_rcp_f32_e32 v15, v15
	s_add_i32 s8, s28, 0x50
	s_waitcnt vmcnt(21)
	v_and_b32_e32 v17, 0xffff0000, v110
	v_and_b32_e32 v19, 0xffff0000, v111
	v_lshlrev_b32_e32 v16, 16, v110
	v_lshlrev_b32_e32 v18, 16, v111
	s_cmp_ge_i32 s8, s7
	v_pk_mul_f32 v[14:15], v[14:15], v[18:19]
	v_pk_mul_f32 v[12:13], v[12:13], v[16:17]
	s_cselect_b64 vcc, -1, 0
	v_lshl_add_u32 v20, s8, 10, v11
	v_cndmask_b32_e32 v13, 0, v13, vcc
	v_cndmask_b32_e32 v12, 0, v12, vcc
	v_cndmask_b32_e32 v15, 0, v15, vcc
	v_cndmask_b32_e32 v14, 0, v14, vcc
	ds_write_b128 v20, v[12:15]
	s_cmp_gt_i32 s28, 5
	s_cbranch_scc1 .LBB0_257
.LBB0_281:
	s_waitcnt vmcnt(8)
	v_lshlrev_b32_e32 v12, 16, v108
	v_and_b32_e32 v13, 0xffff0000, v108
	v_lshlrev_b32_e32 v14, 16, v109
	v_and_b32_e32 v15, 0xffff0000, v109
	v_pk_mul_f32 v[12:13], v[12:13], s[96:97] op_sel_hi:[1,0]
	v_pk_mul_f32 v[14:15], v[14:15], s[96:97] op_sel_hi:[1,0]
	v_exp_f32_e32 v12, v12
	v_exp_f32_e32 v13, v13
	v_exp_f32_e32 v14, v14
	v_exp_f32_e32 v15, v15
	v_pk_add_f32 v[12:13], v[12:13], 1.0 op_sel_hi:[1,0]
	v_pk_add_f32 v[14:15], v[14:15], 1.0 op_sel_hi:[1,0]
	v_rcp_f32_e32 v12, v12
	v_rcp_f32_e32 v13, v13
	v_rcp_f32_e32 v14, v14
	v_rcp_f32_e32 v15, v15
	s_add_i32 s8, s28, 0x58
	s_waitcnt vmcnt(23)
	v_and_b32_e32 v17, 0xffff0000, v106
	v_and_b32_e32 v19, 0xffff0000, v107
	v_lshlrev_b32_e32 v16, 16, v106
	v_lshlrev_b32_e32 v18, 16, v107
	s_cmp_ge_i32 s8, s7
	v_pk_mul_f32 v[14:15], v[14:15], v[18:19]
	v_pk_mul_f32 v[12:13], v[12:13], v[16:17]
	s_cselect_b64 vcc, -1, 0
	v_lshl_add_u32 v11, s8, 10, v11
	v_cndmask_b32_e32 v13, 0, v13, vcc
	v_cndmask_b32_e32 v12, 0, v12, vcc
	v_cndmask_b32_e32 v15, 0, v15, vcc
	v_cndmask_b32_e32 v14, 0, v14, vcc
	ds_write_b128 v11, v[12:15]
	s_branch .LBB0_257

.LBB0_288:
	s_add_i32 s59, s58, 0xffffff80
	s_cmpk_lt_i32 s59, 0x100
	s_cselect_b32 s7, s58, s59
	s_lshl_b32 s7, s7, 6
	s_and_b32 s8, s7, 0xfc0
	s_sub_i32 s10, s8, 30
	s_add_i32 s8, s10, s56
	s_and_b32 s7, s7, 0xfffff000
	s_max_i32 s8, s8, 0
	s_add_i32 s8, s8, s7
	v_and_b32_e32 v14, 0xff, v10
	v_mad_i64_i32 v[10:11], s[8:9], s8, v238, v[102:103]
	s_add_i32 s8, s10, s51
	s_max_i32 s8, s8, 0
	s_add_i32 s8, s8, s7
	v_mad_i64_i32 v[12:13], s[8:9], s8, v238, v[102:103]
	s_add_i32 s8, s10, s50
	s_max_i32 s8, s8, 0
	s_add_i32 s8, s8, s7
	s_waitcnt lgkmcnt(0)
	s_barrier
	global_load_dwordx2 v[152:153], v[10:11], off offset:1024
	global_load_dwordx2 v[154:155], v[10:11], off offset:1536
	global_load_dwordx2 v[148:149], v[12:13], off offset:1024
	global_load_dwordx2 v[150:151], v[12:13], off offset:1536
	v_mad_i64_i32 v[10:11], s[8:9], s8, v238, v[102:103]
	s_add_i32 s8, s10, s49
	s_max_i32 s8, s8, 0
	s_add_i32 s8, s8, s7
	v_mad_i64_i32 v[12:13], s[8:9], s8, v238, v[102:103]
	s_add_i32 s8, s10, s48
	s_max_i32 s8, s8, 0
	s_add_i32 s8, s8, s7
	global_load_dwordx2 v[144:145], v[10:11], off offset:1024
	global_load_dwordx2 v[146:147], v[10:11], off offset:1536
	global_load_dwordx2 v[140:141], v[12:13], off offset:1024
	global_load_dwordx2 v[142:143], v[12:13], off offset:1536
	v_mad_i64_i32 v[10:11], s[8:9], s8, v238, v[102:103]
	s_add_i32 s8, s10, s47
	s_max_i32 s8, s8, 0
	s_add_i32 s8, s8, s7
	v_mad_i64_i32 v[12:13], s[8:9], s8, v238, v[102:103]
	s_add_i32 s8, s10, s46
	s_max_i32 s8, s8, 0
	s_add_i32 s8, s8, s7
	global_load_dwordx2 v[136:137], v[10:11], off offset:1024
	global_load_dwordx2 v[138:139], v[10:11], off offset:1536
	global_load_dwordx2 v[132:133], v[12:13], off offset:1024
	global_load_dwordx2 v[134:135], v[12:13], off offset:1536
	v_mad_i64_i32 v[10:11], s[8:9], s8, v238, v[102:103]
	s_add_i32 s8, s10, s45
	s_max_i32 s8, s8, 0
	s_add_i32 s8, s8, s7
	v_mad_i64_i32 v[12:13], s[8:9], s8, v238, v[102:103]
	s_add_i32 s8, s10, s44
	s_max_i32 s8, s8, 0
	s_add_i32 s8, s8, s7
	global_load_dwordx2 v[126:127], v[10:11], off offset:1024
	global_load_dwordx2 v[128:129], v[10:11], off offset:1536
	global_load_dwordx2 v[122:123], v[12:13], off offset:1024
	global_load_dwordx2 v[124:125], v[12:13], off offset:1536
	v_mad_i64_i32 v[10:11], s[8:9], s8, v238, v[102:103]
	s_add_i32 s8, s10, s41
	s_max_i32 s8, s8, 0
	s_add_i32 s8, s8, s7
	v_mad_i64_i32 v[12:13], s[8:9], s8, v238, v[102:103]
	s_add_i32 s8, s10, s40
	s_max_i32 s8, s8, 0
	s_add_i32 s8, s8, s7
	global_load_dwordx2 v[118:119], v[10:11], off offset:1024
	global_load_dwordx2 v[120:121], v[10:11], off offset:1536
	global_load_dwordx2 v[114:115], v[12:13], off offset:1024
	global_load_dwordx2 v[116:117], v[12:13], off offset:1536
	v_mad_i64_i32 v[10:11], s[8:9], s8, v238, v[102:103]
	s_add_i32 s10, s10, s5
	s_lshl_b32 s6, s6, 7
	s_max_i32 s8, s10, 0
	s_and_b32 s6, s6, 0xffff8000
	s_add_i32 s8, s8, s7
	s_add_i32 s6, s6, 0
	v_mad_i64_i32 v[12:13], s[8:9], s8, v238, v[102:103]
	v_lshl_add_u32 v163, v14, 2, s6
	global_load_dwordx2 v[110:111], v[10:11], off offset:1024
	global_load_dwordx2 v[112:113], v[10:11], off offset:1536
	global_load_dwordx2 v[104:105], v[12:13], off offset:1024
	global_load_dwordx2 v[106:107], v[12:13], off offset:1536
	ds_read2st64_b32 v[26:27], v163 offset1:4
	ds_read2st64_b32 v[28:29], v163 offset0:8 offset1:12
	ds_read2st64_b32 v[30:31], v163 offset0:16 offset1:20
	ds_read2st64_b32 v[32:33], v163 offset0:24 offset1:28
	ds_read2st64_b32 v[160:161], v163 offset0:32 offset1:36
	ds_read2st64_b32 v[158:159], v163 offset0:40 offset1:44
	ds_read2st64_b32 v[156:157], v163 offset0:48 offset1:52
	ds_read2st64_b32 v[40:41], v163 offset0:56 offset1:60
	ds_read2st64_b32 v[38:39], v163 offset0:64 offset1:68
	ds_read2st64_b32 v[36:37], v163 offset0:72 offset1:76
	ds_read2st64_b32 v[34:35], v163 offset0:80 offset1:84
	ds_read2st64_b32 v[24:25], v163 offset0:88 offset1:92
	ds_read2st64_b32 v[22:23], v163 offset0:96 offset1:100
	ds_read2st64_b32 v[20:21], v163 offset0:104 offset1:108
	ds_read2st64_b32 v[10:11], v163 offset0:120 offset1:124
	ds_read2st64_b32 v[18:19], v163 offset0:112 offset1:116
	ds_read2st64_b32 v[12:13], v163 offset0:128 offset1:132
	ds_read2st64_b32 v[14:15], v163 offset0:136 offset1:140
	ds_read2st64_b32 v[16:17], v163 offset0:144 offset1:148
	s_waitcnt vmcnt(51) lgkmcnt(4)
	v_mul_f32_e32 v109, v101, v10
	v_mul_f32_e32 v165, v42, v27
	s_waitcnt vmcnt(24)
	v_mov_b32_e32 v164, v108
	v_pk_fma_f32 v[26:27], v[42:43], v[26:27], v[108:109]
	v_pk_fma_f32 v[164:165], v[44:45], v[28:29], v[164:165]
	v_pk_fma_f32 v[26:27], v[46:47], v[28:29], v[26:27]
	v_pk_fma_f32 v[164:165], v[48:49], v[30:31], v[164:165]
	v_pk_fma_f32 v[26:27], v[50:51], v[30:31], v[26:27]
	v_pk_fma_f32 v[164:165], v[52:53], v[32:33], v[164:165]
	v_pk_fma_f32 v[26:27], v[54:55], v[32:33], v[26:27]
	v_pk_fma_f32 v[164:165], v[56:57], v[160:161], v[164:165]
	v_pk_fma_f32 v[26:27], v[58:59], v[160:161], v[26:27]
	v_pk_fma_f32 v[164:165], v[60:61], v[158:159], v[164:165]
	v_pk_fma_f32 v[26:27], v[62:63], v[158:159], v[26:27]
	v_pk_fma_f32 v[164:165], v[64:65], v[156:157], v[164:165]
	v_pk_fma_f32 v[26:27], v[66:67], v[156:157], v[26:27]
	v_pk_fma_f32 v[164:165], v[68:69], v[40:41], v[164:165]
	v_pk_fma_f32 v[26:27], v[70:71], v[40:41], v[26:27]
	v_pk_fma_f32 v[164:165], v[72:73], v[38:39], v[164:165]
	v_pk_fma_f32 v[26:27], v[74:75], v[38:39], v[26:27]
	v_pk_fma_f32 v[164:165], v[76:77], v[36:37], v[164:165]
	v_pk_fma_f32 v[26:27], v[78:79], v[36:37], v[26:27]
	v_pk_fma_f32 v[164:165], v[80:81], v[34:35], v[164:165]
	v_pk_fma_f32 v[26:27], v[82:83], v[34:35], v[26:27]
	v_pk_fma_f32 v[164:165], v[84:85], v[24:25], v[164:165]
	v_pk_fma_f32 v[26:27], v[86:87], v[24:25], v[26:27]
	v_pk_fma_f32 v[164:165], v[88:89], v[22:23], v[164:165]
	v_pk_fma_f32 v[26:27], v[90:91], v[22:23], v[26:27]
	v_pk_fma_f32 v[164:165], v[92:93], v[20:21], v[164:165]
	v_pk_fma_f32 v[26:27], v[94:95], v[20:21], v[26:27]
	s_waitcnt lgkmcnt(3)
	v_pk_fma_f32 v[164:165], v[96:97], v[18:19], v[164:165]
	v_pk_fma_f32 v[26:27], v[98:99], v[18:19], v[26:27]
	v_pk_fma_f32 v[166:167], v[100:101], v[10:11], v[164:165]
	v_add_f32_e32 v164, v26, v27
	v_mul_f32_e32 v27, v42, v29
	v_mov_b32_e32 v26, v108
	v_pk_fma_f32 v[26:27], v[44:45], v[30:31], v[26:27]
	v_add_f32_e32 v165, v166, v167
	v_pk_fma_f32 v[26:27], v[48:49], v[32:33], v[26:27]
	s_waitcnt lgkmcnt(2)
	v_mul_f32_e32 v109, v101, v12
	v_pk_fma_f32 v[26:27], v[52:53], v[160:161], v[26:27]
	v_pk_fma_f32 v[28:29], v[42:43], v[28:29], v[108:109]
	v_pk_fma_f32 v[26:27], v[56:57], v[158:159], v[26:27]
	v_pk_fma_f32 v[28:29], v[46:47], v[30:31], v[28:29]
	v_pk_fma_f32 v[26:27], v[60:61], v[156:157], v[26:27]
	v_pk_fma_f32 v[28:29], v[50:51], v[32:33], v[28:29]
	v_pk_fma_f32 v[26:27], v[64:65], v[40:41], v[26:27]
	v_pk_fma_f32 v[28:29], v[54:55], v[160:161], v[28:29]
	v_pk_fma_f32 v[26:27], v[68:69], v[38:39], v[26:27]
	v_pk_fma_f32 v[28:29], v[58:59], v[158:159], v[28:29]
	v_pk_fma_f32 v[26:27], v[72:73], v[36:37], v[26:27]
	v_pk_fma_f32 v[28:29], v[62:63], v[156:157], v[28:29]
	v_pk_fma_f32 v[26:27], v[76:77], v[34:35], v[26:27]
	v_pk_fma_f32 v[28:29], v[66:67], v[40:41], v[28:29]
	v_pk_fma_f32 v[26:27], v[80:81], v[24:25], v[26:27]
	v_pk_fma_f32 v[28:29], v[70:71], v[38:39], v[28:29]
	v_pk_fma_f32 v[26:27], v[84:85], v[22:23], v[26:27]
	v_pk_fma_f32 v[28:29], v[74:75], v[36:37], v[28:29]
	v_pk_fma_f32 v[26:27], v[88:89], v[20:21], v[26:27]
	v_pk_fma_f32 v[28:29], v[78:79], v[34:35], v[28:29]
	v_pk_fma_f32 v[26:27], v[92:93], v[18:19], v[26:27]
	v_pk_fma_f32 v[28:29], v[82:83], v[24:25], v[28:29]
	v_pk_fma_f32 v[26:27], v[96:97], v[10:11], v[26:27]
	v_pk_fma_f32 v[28:29], v[86:87], v[22:23], v[28:29]
	v_pk_fma_f32 v[26:27], v[100:101], v[12:13], v[26:27]
	v_pk_fma_f32 v[28:29], v[90:91], v[20:21], v[28:29]
	v_add_f32_e32 v167, v26, v27
	v_mul_f32_e32 v27, v42, v31
	v_mov_b32_e32 v26, v108
	v_pk_fma_f32 v[26:27], v[44:45], v[32:33], v[26:27]
	v_pk_fma_f32 v[28:29], v[94:95], v[18:19], v[28:29]
	v_pk_fma_f32 v[26:27], v[48:49], v[160:161], v[26:27]
	v_pk_fma_f32 v[28:29], v[98:99], v[10:11], v[28:29]
	v_pk_fma_f32 v[26:27], v[52:53], v[158:159], v[26:27]
	s_waitcnt lgkmcnt(1)
	v_mul_f32_e32 v109, v101, v14
	v_pk_fma_f32 v[26:27], v[56:57], v[156:157], v[26:27]
	v_add_f32_e32 v166, v28, v29
	v_pk_fma_f32 v[26:27], v[60:61], v[40:41], v[26:27]
	v_pk_fma_f32 v[28:29], v[42:43], v[30:31], v[108:109]
	v_pk_fma_f32 v[26:27], v[64:65], v[38:39], v[26:27]
	v_pk_fma_f32 v[28:29], v[46:47], v[32:33], v[28:29]
	v_pk_fma_f32 v[26:27], v[68:69], v[36:37], v[26:27]
	v_pk_fma_f32 v[28:29], v[50:51], v[160:161], v[28:29]
	v_pk_fma_f32 v[26:27], v[72:73], v[34:35], v[26:27]
	v_pk_fma_f32 v[28:29], v[54:55], v[158:159], v[28:29]
	v_pk_fma_f32 v[26:27], v[76:77], v[24:25], v[26:27]
	v_pk_fma_f32 v[28:29], v[58:59], v[156:157], v[28:29]
	v_pk_fma_f32 v[26:27], v[80:81], v[22:23], v[26:27]
	v_pk_fma_f32 v[28:29], v[62:63], v[40:41], v[28:29]
	v_pk_fma_f32 v[26:27], v[84:85], v[20:21], v[26:27]
	v_pk_fma_f32 v[28:29], v[66:67], v[38:39], v[28:29]
	v_pk_fma_f32 v[26:27], v[88:89], v[18:19], v[26:27]
	v_pk_fma_f32 v[28:29], v[70:71], v[36:37], v[28:29]
	v_pk_fma_f32 v[26:27], v[92:93], v[10:11], v[26:27]
	v_pk_fma_f32 v[28:29], v[74:75], v[34:35], v[28:29]
	v_pk_fma_f32 v[26:27], v[96:97], v[12:13], v[26:27]
	v_pk_fma_f32 v[28:29], v[78:79], v[24:25], v[28:29]
	v_pk_fma_f32 v[26:27], v[100:101], v[14:15], v[26:27]
	v_pk_fma_f32 v[28:29], v[82:83], v[22:23], v[28:29]
	v_add_f32_e32 v169, v26, v27
	v_mul_f32_e32 v27, v42, v33
	v_mov_b32_e32 v26, v108
	v_pk_fma_f32 v[26:27], v[44:45], v[160:161], v[26:27]
	v_pk_fma_f32 v[28:29], v[86:87], v[20:21], v[28:29]
	v_pk_fma_f32 v[26:27], v[48:49], v[158:159], v[26:27]
	v_pk_fma_f32 v[28:29], v[90:91], v[18:19], v[28:29]
	v_pk_fma_f32 v[26:27], v[52:53], v[156:157], v[26:27]
	v_pk_fma_f32 v[28:29], v[94:95], v[10:11], v[28:29]
	v_pk_fma_f32 v[26:27], v[56:57], v[40:41], v[26:27]
	v_pk_fma_f32 v[28:29], v[98:99], v[12:13], v[28:29]
	v_pk_fma_f32 v[26:27], v[60:61], v[38:39], v[26:27]
	s_waitcnt lgkmcnt(0)
	v_mul_f32_e32 v109, v101, v16
	v_pk_fma_f32 v[26:27], v[64:65], v[36:37], v[26:27]
	v_add_f32_e32 v168, v28, v29
	v_pk_fma_f32 v[26:27], v[68:69], v[34:35], v[26:27]
	v_pk_fma_f32 v[28:29], v[42:43], v[32:33], v[108:109]
	v_pk_fma_f32 v[26:27], v[72:73], v[24:25], v[26:27]
	v_pk_fma_f32 v[28:29], v[46:47], v[160:161], v[28:29]
	v_pk_fma_f32 v[26:27], v[76:77], v[22:23], v[26:27]
	v_pk_fma_f32 v[28:29], v[50:51], v[158:159], v[28:29]
	v_pk_fma_f32 v[26:27], v[80:81], v[20:21], v[26:27]
	v_pk_fma_f32 v[28:29], v[54:55], v[156:157], v[28:29]
	v_pk_fma_f32 v[26:27], v[84:85], v[18:19], v[26:27]
	v_pk_fma_f32 v[28:29], v[58:59], v[40:41], v[28:29]
	v_pk_fma_f32 v[26:27], v[88:89], v[10:11], v[26:27]
	v_mul_f32_e32 v173, v42, v161
	v_pk_fma_f32 v[26:27], v[92:93], v[12:13], v[26:27]
	v_pk_fma_f32 v[28:29], v[62:63], v[38:39], v[28:29]
	v_pk_fma_f32 v[26:27], v[96:97], v[14:15], v[26:27]
	v_pk_fma_f32 v[28:29], v[66:67], v[36:37], v[28:29]
	v_pk_fma_f32 v[30:31], v[100:101], v[16:17], v[26:27]
	ds_read2st64_b32 v[26:27], v163 offset0:152 offset1:156
	v_pk_fma_f32 v[28:29], v[70:71], v[34:35], v[28:29]
	v_add_f32_e32 v171, v30, v31
	v_pk_fma_f32 v[28:29], v[74:75], v[24:25], v[28:29]
	v_mov_b32_e32 v172, v108
	s_waitcnt lgkmcnt(0)
	v_mul_f32_e32 v109, v101, v26
	v_pk_fma_f32 v[160:161], v[42:43], v[160:161], v[108:109]
	v_pk_fma_f32 v[28:29], v[78:79], v[22:23], v[28:29]
	v_pk_fma_f32 v[160:161], v[46:47], v[158:159], v[160:161]
	v_pk_fma_f32 v[28:29], v[82:83], v[20:21], v[28:29]
	v_pk_fma_f32 v[160:161], v[50:51], v[156:157], v[160:161]
	v_pk_fma_f32 v[28:29], v[86:87], v[18:19], v[28:29]
	v_pk_fma_f32 v[160:161], v[54:55], v[40:41], v[160:161]
	v_pk_fma_f32 v[28:29], v[90:91], v[10:11], v[28:29]
	v_pk_fma_f32 v[160:161], v[58:59], v[38:39], v[160:161]
	v_pk_fma_f32 v[28:29], v[94:95], v[12:13], v[28:29]
	v_pk_fma_f32 v[160:161], v[62:63], v[36:37], v[160:161]
	v_pk_fma_f32 v[28:29], v[98:99], v[14:15], v[28:29]
	v_pk_fma_f32 v[160:161], v[66:67], v[34:35], v[160:161]
	v_add_f32_e32 v170, v28, v29
	v_pk_fma_f32 v[160:161], v[70:71], v[24:25], v[160:161]
	ds_read2st64_b32 v[28:29], v163 offset0:160 offset1:164
	ds_read2st64_b32 v[30:31], v163 offset0:168 offset1:172
	ds_read2st64_b32 v[32:33], v163 offset0:176 offset1:180
	v_pk_fma_f32 v[160:161], v[74:75], v[22:23], v[160:161]
	v_pk_fma_f32 v[172:173], v[44:45], v[158:159], v[172:173]
	v_pk_fma_f32 v[160:161], v[78:79], v[20:21], v[160:161]
	s_waitcnt lgkmcnt(2)
	v_mul_f32_e32 v109, v101, v28
	v_pk_fma_f32 v[160:161], v[82:83], v[18:19], v[160:161]
	v_pk_fma_f32 v[172:173], v[48:49], v[156:157], v[172:173]
	v_pk_fma_f32 v[160:161], v[86:87], v[10:11], v[160:161]
	v_pk_fma_f32 v[172:173], v[52:53], v[40:41], v[172:173]
	v_pk_fma_f32 v[160:161], v[90:91], v[12:13], v[160:161]
	v_pk_fma_f32 v[172:173], v[56:57], v[38:39], v[172:173]
	v_pk_fma_f32 v[160:161], v[94:95], v[14:15], v[160:161]
	v_pk_fma_f32 v[172:173], v[60:61], v[36:37], v[172:173]
	v_pk_fma_f32 v[160:161], v[98:99], v[16:17], v[160:161]
	v_pk_fma_f32 v[172:173], v[64:65], v[34:35], v[172:173]
	v_add_f32_e32 v174, v160, v161
	v_mul_f32_e32 v161, v42, v159
	v_pk_fma_f32 v[158:159], v[42:43], v[158:159], v[108:109]
	v_mov_b32_e32 v160, v108
	v_pk_fma_f32 v[158:159], v[46:47], v[156:157], v[158:159]
	s_waitcnt lgkmcnt(1)
	v_mul_f32_e32 v109, v101, v30
	v_pk_fma_f32 v[158:159], v[50:51], v[40:41], v[158:159]
	v_pk_fma_f32 v[160:161], v[44:45], v[156:157], v[160:161]
	v_pk_fma_f32 v[158:159], v[54:55], v[38:39], v[158:159]
	v_pk_fma_f32 v[160:161], v[48:49], v[40:41], v[160:161]
	v_pk_fma_f32 v[158:159], v[58:59], v[36:37], v[158:159]
	v_pk_fma_f32 v[172:173], v[68:69], v[24:25], v[172:173]
	v_pk_fma_f32 v[158:159], v[62:63], v[34:35], v[158:159]
	v_pk_fma_f32 v[172:173], v[72:73], v[22:23], v[172:173]
	v_pk_fma_f32 v[158:159], v[66:67], v[24:25], v[158:159]
	v_pk_fma_f32 v[172:173], v[76:77], v[20:21], v[172:173]
	v_pk_fma_f32 v[158:159], v[70:71], v[22:23], v[158:159]
	v_pk_fma_f32 v[172:173], v[80:81], v[18:19], v[172:173]
	v_pk_fma_f32 v[158:159], v[74:75], v[20:21], v[158:159]
	v_pk_fma_f32 v[172:173], v[84:85], v[10:11], v[172:173]
	v_pk_fma_f32 v[158:159], v[78:79], v[18:19], v[158:159]
	v_pk_fma_f32 v[172:173], v[88:89], v[12:13], v[172:173]
	v_pk_fma_f32 v[158:159], v[82:83], v[10:11], v[158:159]
	v_pk_fma_f32 v[172:173], v[92:93], v[14:15], v[172:173]
	v_pk_fma_f32 v[158:159], v[86:87], v[12:13], v[158:159]
	v_pk_fma_f32 v[172:173], v[96:97], v[16:17], v[172:173]
	v_pk_fma_f32 v[158:159], v[90:91], v[14:15], v[158:159]
	v_pk_fma_f32 v[160:161], v[52:53], v[38:39], v[160:161]
	v_pk_fma_f32 v[158:159], v[94:95], v[16:17], v[158:159]
	v_pk_fma_f32 v[172:173], v[100:101], v[26:27], v[172:173]
	v_pk_fma_f32 v[158:159], v[98:99], v[26:27], v[158:159]
	v_pk_fma_f32 v[160:161], v[56:57], v[36:37], v[160:161]
	v_add_f32_e32 v176, v158, v159
	v_mul_f32_e32 v159, v42, v157
	v_pk_fma_f32 v[156:157], v[42:43], v[156:157], v[108:109]
	v_mov_b32_e32 v158, v108
	v_pk_fma_f32 v[156:157], v[46:47], v[40:41], v[156:157]
	s_waitcnt lgkmcnt(0)
	v_mul_f32_e32 v109, v101, v32
	v_pk_fma_f32 v[156:157], v[50:51], v[38:39], v[156:157]
	v_pk_fma_f32 v[158:159], v[44:45], v[40:41], v[158:159]
	v_pk_fma_f32 v[156:157], v[54:55], v[36:37], v[156:157]
	v_pk_fma_f32 v[158:159], v[48:49], v[38:39], v[158:159]
	v_pk_fma_f32 v[156:157], v[58:59], v[34:35], v[156:157]
	v_pk_fma_f32 v[158:159], v[52:53], v[36:37], v[158:159]
	v_pk_fma_f32 v[156:157], v[62:63], v[24:25], v[156:157]
	v_pk_fma_f32 v[158:159], v[56:57], v[34:35], v[158:159]
	v_pk_fma_f32 v[156:157], v[66:67], v[22:23], v[156:157]
	v_add_f32_e32 v175, v172, v173
	v_pk_fma_f32 v[156:157], v[70:71], v[20:21], v[156:157]
	v_pk_fma_f32 v[160:161], v[60:61], v[34:35], v[160:161]
	v_pk_fma_f32 v[156:157], v[74:75], v[18:19], v[156:157]
	v_pk_fma_f32 v[158:159], v[60:61], v[24:25], v[158:159]
	v_pk_fma_f32 v[156:157], v[78:79], v[10:11], v[156:157]
	v_mul_f32_e32 v173, v42, v39
	v_pk_fma_f32 v[156:157], v[82:83], v[12:13], v[156:157]
	v_pk_fma_f32 v[160:161], v[64:65], v[24:25], v[160:161]
	v_pk_fma_f32 v[156:157], v[86:87], v[14:15], v[156:157]
	v_pk_fma_f32 v[158:159], v[64:65], v[22:23], v[158:159]
	v_pk_fma_f32 v[156:157], v[90:91], v[16:17], v[156:157]
	v_pk_fma_f32 v[160:161], v[68:69], v[22:23], v[160:161]
	v_pk_fma_f32 v[156:157], v[94:95], v[26:27], v[156:157]
	v_pk_fma_f32 v[158:159], v[68:69], v[20:21], v[158:159]
	v_pk_fma_f32 v[156:157], v[98:99], v[28:29], v[156:157]
	v_pk_fma_f32 v[160:161], v[72:73], v[20:21], v[160:161]
	v_add_f32_e32 v178, v156, v157
	v_mul_f32_e32 v157, v42, v41
	v_pk_fma_f32 v[40:41], v[42:43], v[40:41], v[108:109]
	v_mov_b32_e32 v156, v108
	v_pk_fma_f32 v[40:41], v[46:47], v[38:39], v[40:41]
	v_pk_fma_f32 v[156:157], v[44:45], v[38:39], v[156:157]
	v_pk_fma_f32 v[40:41], v[50:51], v[36:37], v[40:41]
	v_pk_fma_f32 v[156:157], v[48:49], v[36:37], v[156:157]
	v_pk_fma_f32 v[40:41], v[54:55], v[34:35], v[40:41]
	v_pk_fma_f32 v[156:157], v[52:53], v[34:35], v[156:157]
	v_pk_fma_f32 v[40:41], v[58:59], v[24:25], v[40:41]
	v_pk_fma_f32 v[156:157], v[56:57], v[24:25], v[156:157]
	v_pk_fma_f32 v[40:41], v[62:63], v[22:23], v[40:41]
	v_pk_fma_f32 v[156:157], v[60:61], v[22:23], v[156:157]
	v_pk_fma_f32 v[40:41], v[66:67], v[20:21], v[40:41]
	v_pk_fma_f32 v[156:157], v[64:65], v[20:21], v[156:157]
	v_pk_fma_f32 v[40:41], v[70:71], v[18:19], v[40:41]
	v_pk_fma_f32 v[156:157], v[68:69], v[18:19], v[156:157]
	v_pk_fma_f32 v[40:41], v[74:75], v[10:11], v[40:41]
	v_pk_fma_f32 v[158:159], v[72:73], v[18:19], v[158:159]
	v_pk_fma_f32 v[40:41], v[78:79], v[12:13], v[40:41]
	v_pk_fma_f32 v[156:157], v[72:73], v[10:11], v[156:157]
	v_pk_fma_f32 v[40:41], v[82:83], v[14:15], v[40:41]
	v_pk_fma_f32 v[160:161], v[76:77], v[18:19], v[160:161]
	v_pk_fma_f32 v[40:41], v[86:87], v[16:17], v[40:41]
	v_pk_fma_f32 v[158:159], v[76:77], v[10:11], v[158:159]
	v_pk_fma_f32 v[40:41], v[90:91], v[26:27], v[40:41]
	v_pk_fma_f32 v[156:157], v[76:77], v[12:13], v[156:157]
	v_pk_fma_f32 v[40:41], v[94:95], v[28:29], v[40:41]
	v_pk_fma_f32 v[160:161], v[80:81], v[10:11], v[160:161]
	v_pk_fma_f32 v[40:41], v[98:99], v[30:31], v[40:41]
	v_pk_fma_f32 v[158:159], v[80:81], v[12:13], v[158:159]
	v_add_f32_e32 v180, v40, v41
	ds_read2st64_b32 v[40:41], v163 offset0:184 offset1:188
	v_pk_fma_f32 v[156:157], v[80:81], v[14:15], v[156:157]
	v_pk_fma_f32 v[160:161], v[84:85], v[12:13], v[160:161]
	v_pk_fma_f32 v[158:159], v[84:85], v[14:15], v[158:159]
	v_pk_fma_f32 v[156:157], v[84:85], v[16:17], v[156:157]
	s_waitcnt lgkmcnt(0)
	v_mul_f32_e32 v109, v101, v40
	v_pk_fma_f32 v[38:39], v[42:43], v[38:39], v[108:109]
	v_pk_fma_f32 v[160:161], v[88:89], v[14:15], v[160:161]
	v_pk_fma_f32 v[38:39], v[46:47], v[36:37], v[38:39]
	v_pk_fma_f32 v[158:159], v[88:89], v[16:17], v[158:159]
	v_pk_fma_f32 v[38:39], v[50:51], v[34:35], v[38:39]
	v_pk_fma_f32 v[156:157], v[88:89], v[26:27], v[156:157]
	v_pk_fma_f32 v[38:39], v[54:55], v[24:25], v[38:39]
	v_pk_fma_f32 v[160:161], v[92:93], v[16:17], v[160:161]
	v_pk_fma_f32 v[38:39], v[58:59], v[22:23], v[38:39]
	v_pk_fma_f32 v[158:159], v[92:93], v[26:27], v[158:159]
	v_pk_fma_f32 v[38:39], v[62:63], v[20:21], v[38:39]
	v_pk_fma_f32 v[156:157], v[92:93], v[28:29], v[156:157]
	v_pk_fma_f32 v[38:39], v[66:67], v[18:19], v[38:39]
	v_pk_fma_f32 v[160:161], v[96:97], v[26:27], v[160:161]
	v_pk_fma_f32 v[38:39], v[70:71], v[10:11], v[38:39]
	v_pk_fma_f32 v[158:159], v[96:97], v[28:29], v[158:159]
	v_pk_fma_f32 v[38:39], v[74:75], v[12:13], v[38:39]
	v_pk_fma_f32 v[156:157], v[96:97], v[30:31], v[156:157]
	v_pk_fma_f32 v[38:39], v[78:79], v[14:15], v[38:39]
	v_pk_fma_f32 v[160:161], v[100:101], v[28:29], v[160:161]
	v_pk_fma_f32 v[158:159], v[100:101], v[30:31], v[158:159]
	v_pk_fma_f32 v[156:157], v[100:101], v[32:33], v[156:157]
	v_pk_fma_f32 v[38:39], v[82:83], v[16:17], v[38:39]
	v_add_f32_e32 v177, v160, v161
	v_add_f32_e32 v179, v158, v159
	v_add_f32_e32 v181, v156, v157
	ds_read2st64_b32 v[156:157], v163 offset0:192 offset1:196
	ds_read2st64_b32 v[158:159], v163 offset0:200 offset1:204
	ds_read2st64_b32 v[160:161], v163 offset0:208 offset1:212
	v_pk_fma_f32 v[38:39], v[86:87], v[26:27], v[38:39]
	v_mov_b32_e32 v172, v108
	v_pk_fma_f32 v[38:39], v[90:91], v[28:29], v[38:39]
	s_waitcnt lgkmcnt(2)
	v_mul_f32_e32 v109, v101, v156
	v_pk_fma_f32 v[38:39], v[94:95], v[30:31], v[38:39]
	v_pk_fma_f32 v[172:173], v[44:45], v[36:37], v[172:173]
	v_pk_fma_f32 v[38:39], v[98:99], v[32:33], v[38:39]
	v_pk_fma_f32 v[172:173], v[48:49], v[34:35], v[172:173]
	v_add_f32_e32 v182, v38, v39
	v_mul_f32_e32 v39, v42, v37
	v_pk_fma_f32 v[36:37], v[42:43], v[36:37], v[108:109]
	v_mov_b32_e32 v38, v108
	v_pk_fma_f32 v[36:37], v[46:47], v[34:35], v[36:37]
	s_waitcnt lgkmcnt(1)
	v_mul_f32_e32 v109, v101, v158
	v_pk_fma_f32 v[36:37], v[50:51], v[24:25], v[36:37]
	v_pk_fma_f32 v[38:39], v[44:45], v[34:35], v[38:39]
	v_pk_fma_f32 v[36:37], v[54:55], v[22:23], v[36:37]
	v_pk_fma_f32 v[172:173], v[52:53], v[24:25], v[172:173]
	v_pk_fma_f32 v[36:37], v[58:59], v[20:21], v[36:37]
	v_pk_fma_f32 v[38:39], v[48:49], v[24:25], v[38:39]
	v_pk_fma_f32 v[36:37], v[62:63], v[18:19], v[36:37]
	v_pk_fma_f32 v[172:173], v[56:57], v[22:23], v[172:173]
	v_pk_fma_f32 v[36:37], v[66:67], v[10:11], v[36:37]
	v_pk_fma_f32 v[172:173], v[60:61], v[20:21], v[172:173]
	v_pk_fma_f32 v[36:37], v[70:71], v[12:13], v[36:37]
	v_pk_fma_f32 v[172:173], v[64:65], v[18:19], v[172:173]
	v_pk_fma_f32 v[36:37], v[74:75], v[14:15], v[36:37]
	v_pk_fma_f32 v[172:173], v[68:69], v[10:11], v[172:173]
	v_pk_fma_f32 v[36:37], v[78:79], v[16:17], v[36:37]
	v_pk_fma_f32 v[172:173], v[72:73], v[12:13], v[172:173]
	v_pk_fma_f32 v[36:37], v[82:83], v[26:27], v[36:37]
	v_pk_fma_f32 v[172:173], v[76:77], v[14:15], v[172:173]
	v_pk_fma_f32 v[36:37], v[86:87], v[28:29], v[36:37]
	v_pk_fma_f32 v[172:173], v[80:81], v[16:17], v[172:173]
	v_pk_fma_f32 v[36:37], v[90:91], v[30:31], v[36:37]
	v_pk_fma_f32 v[172:173], v[84:85], v[26:27], v[172:173]
	v_pk_fma_f32 v[36:37], v[94:95], v[32:33], v[36:37]
	v_pk_fma_f32 v[172:173], v[88:89], v[28:29], v[172:173]
	v_pk_fma_f32 v[36:37], v[98:99], v[40:41], v[36:37]
	v_pk_fma_f32 v[172:173], v[92:93], v[30:31], v[172:173]
	v_add_f32_e32 v184, v36, v37
	v_mul_f32_e32 v37, v42, v35
	v_pk_fma_f32 v[34:35], v[42:43], v[34:35], v[108:109]
	v_mov_b32_e32 v36, v108
	v_pk_fma_f32 v[34:35], v[46:47], v[24:25], v[34:35]
	s_waitcnt lgkmcnt(0)
	v_mul_f32_e32 v109, v101, v160
	v_pk_fma_f32 v[34:35], v[50:51], v[22:23], v[34:35]
	v_pk_fma_f32 v[36:37], v[44:45], v[24:25], v[36:37]
	v_pk_fma_f32 v[34:35], v[54:55], v[20:21], v[34:35]
	v_pk_fma_f32 v[36:37], v[48:49], v[22:23], v[36:37]
	v_pk_fma_f32 v[34:35], v[58:59], v[18:19], v[34:35]
	v_pk_fma_f32 v[172:173], v[96:97], v[32:33], v[172:173]
	v_pk_fma_f32 v[34:35], v[62:63], v[10:11], v[34:35]
	v_pk_fma_f32 v[38:39], v[52:53], v[22:23], v[38:39]
	v_pk_fma_f32 v[34:35], v[66:67], v[12:13], v[34:35]
	v_pk_fma_f32 v[36:37], v[52:53], v[20:21], v[36:37]
	v_pk_fma_f32 v[34:35], v[70:71], v[14:15], v[34:35]
	v_pk_fma_f32 v[172:173], v[100:101], v[40:41], v[172:173]
	v_pk_fma_f32 v[34:35], v[74:75], v[16:17], v[34:35]
	v_pk_fma_f32 v[38:39], v[56:57], v[20:21], v[38:39]
	v_pk_fma_f32 v[34:35], v[78:79], v[26:27], v[34:35]
	v_pk_fma_f32 v[36:37], v[56:57], v[18:19], v[36:37]
	v_pk_fma_f32 v[34:35], v[82:83], v[28:29], v[34:35]
	v_add_f32_e32 v183, v172, v173
	v_pk_fma_f32 v[34:35], v[86:87], v[30:31], v[34:35]
	v_pk_fma_f32 v[38:39], v[60:61], v[18:19], v[38:39]
	v_pk_fma_f32 v[34:35], v[90:91], v[32:33], v[34:35]
	v_pk_fma_f32 v[36:37], v[60:61], v[10:11], v[36:37]
	v_pk_fma_f32 v[34:35], v[94:95], v[40:41], v[34:35]
	v_mul_f32_e32 v173, v42, v23
	v_pk_fma_f32 v[34:35], v[98:99], v[156:157], v[34:35]
	v_pk_fma_f32 v[38:39], v[64:65], v[10:11], v[38:39]
	v_add_f32_e32 v186, v34, v35
	v_mul_f32_e32 v35, v42, v25
	v_pk_fma_f32 v[24:25], v[42:43], v[24:25], v[108:109]
	v_mov_b32_e32 v34, v108
	v_pk_fma_f32 v[24:25], v[46:47], v[22:23], v[24:25]
	v_pk_fma_f32 v[34:35], v[44:45], v[22:23], v[34:35]
	v_pk_fma_f32 v[24:25], v[50:51], v[20:21], v[24:25]
	v_pk_fma_f32 v[34:35], v[48:49], v[20:21], v[34:35]
	v_pk_fma_f32 v[24:25], v[54:55], v[18:19], v[24:25]
	v_pk_fma_f32 v[34:35], v[52:53], v[18:19], v[34:35]
	v_pk_fma_f32 v[24:25], v[58:59], v[10:11], v[24:25]
	v_pk_fma_f32 v[34:35], v[56:57], v[10:11], v[34:35]
	v_pk_fma_f32 v[24:25], v[62:63], v[12:13], v[24:25]
	v_pk_fma_f32 v[34:35], v[60:61], v[12:13], v[34:35]
	v_pk_fma_f32 v[24:25], v[66:67], v[14:15], v[24:25]
	v_pk_fma_f32 v[36:37], v[64:65], v[12:13], v[36:37]
	v_pk_fma_f32 v[24:25], v[70:71], v[16:17], v[24:25]
	v_pk_fma_f32 v[34:35], v[64:65], v[14:15], v[34:35]
	v_pk_fma_f32 v[24:25], v[74:75], v[26:27], v[24:25]
	v_pk_fma_f32 v[38:39], v[68:69], v[12:13], v[38:39]
	v_pk_fma_f32 v[24:25], v[78:79], v[28:29], v[24:25]
	v_pk_fma_f32 v[36:37], v[68:69], v[14:15], v[36:37]
	v_pk_fma_f32 v[24:25], v[82:83], v[30:31], v[24:25]
	v_pk_fma_f32 v[34:35], v[68:69], v[16:17], v[34:35]
	v_pk_fma_f32 v[24:25], v[86:87], v[32:33], v[24:25]
	v_pk_fma_f32 v[38:39], v[72:73], v[14:15], v[38:39]
	v_pk_fma_f32 v[24:25], v[90:91], v[40:41], v[24:25]
	v_pk_fma_f32 v[36:37], v[72:73], v[16:17], v[36:37]
	v_pk_fma_f32 v[24:25], v[94:95], v[156:157], v[24:25]
	v_pk_fma_f32 v[34:35], v[72:73], v[26:27], v[34:35]
	v_pk_fma_f32 v[24:25], v[98:99], v[158:159], v[24:25]
	v_pk_fma_f32 v[38:39], v[76:77], v[16:17], v[38:39]
	v_add_f32_e32 v188, v24, v25
	ds_read2st64_b32 v[24:25], v163 offset0:216 offset1:220
	v_pk_fma_f32 v[36:37], v[76:77], v[26:27], v[36:37]
	v_pk_fma_f32 v[34:35], v[76:77], v[28:29], v[34:35]
	v_pk_fma_f32 v[38:39], v[80:81], v[26:27], v[38:39]
	v_pk_fma_f32 v[36:37], v[80:81], v[28:29], v[36:37]
	s_waitcnt lgkmcnt(0)
	v_mul_f32_e32 v109, v101, v24
	v_pk_fma_f32 v[22:23], v[42:43], v[22:23], v[108:109]
	v_pk_fma_f32 v[34:35], v[80:81], v[30:31], v[34:35]
	v_pk_fma_f32 v[22:23], v[46:47], v[20:21], v[22:23]
	v_pk_fma_f32 v[38:39], v[84:85], v[28:29], v[38:39]
	v_pk_fma_f32 v[22:23], v[50:51], v[18:19], v[22:23]
	v_pk_fma_f32 v[36:37], v[84:85], v[30:31], v[36:37]
	v_pk_fma_f32 v[22:23], v[54:55], v[10:11], v[22:23]
	v_pk_fma_f32 v[34:35], v[84:85], v[32:33], v[34:35]
	v_pk_fma_f32 v[22:23], v[58:59], v[12:13], v[22:23]
	v_pk_fma_f32 v[38:39], v[88:89], v[30:31], v[38:39]
	v_pk_fma_f32 v[22:23], v[62:63], v[14:15], v[22:23]
	v_pk_fma_f32 v[36:37], v[88:89], v[32:33], v[36:37]
	v_pk_fma_f32 v[22:23], v[66:67], v[16:17], v[22:23]
	v_pk_fma_f32 v[34:35], v[88:89], v[40:41], v[34:35]
	v_pk_fma_f32 v[22:23], v[70:71], v[26:27], v[22:23]
	v_pk_fma_f32 v[38:39], v[92:93], v[32:33], v[38:39]
	v_pk_fma_f32 v[36:37], v[92:93], v[40:41], v[36:37]
	v_pk_fma_f32 v[34:35], v[92:93], v[156:157], v[34:35]
	v_pk_fma_f32 v[22:23], v[74:75], v[28:29], v[22:23]
	v_pk_fma_f32 v[38:39], v[96:97], v[40:41], v[38:39]
	v_pk_fma_f32 v[36:37], v[96:97], v[156:157], v[36:37]
	v_pk_fma_f32 v[34:35], v[96:97], v[158:159], v[34:35]
	v_pk_fma_f32 v[22:23], v[78:79], v[30:31], v[22:23]
	v_pk_fma_f32 v[38:39], v[100:101], v[156:157], v[38:39]
	v_pk_fma_f32 v[36:37], v[100:101], v[158:159], v[36:37]
	v_pk_fma_f32 v[34:35], v[100:101], v[160:161], v[34:35]
	v_pk_fma_f32 v[22:23], v[82:83], v[32:33], v[22:23]
	v_add_f32_e32 v185, v38, v39
	v_add_f32_e32 v187, v36, v37
	v_add_f32_e32 v189, v34, v35
	ds_read2st64_b32 v[34:35], v163 offset0:224 offset1:228
	ds_read2st64_b32 v[36:37], v163 offset0:232 offset1:236
	ds_read2st64_b32 v[38:39], v163 offset0:240 offset1:244
	v_pk_fma_f32 v[22:23], v[86:87], v[40:41], v[22:23]
	v_mov_b32_e32 v172, v108
	v_pk_fma_f32 v[22:23], v[90:91], v[156:157], v[22:23]
	s_waitcnt lgkmcnt(2)
	v_mul_f32_e32 v109, v101, v34
	v_pk_fma_f32 v[22:23], v[94:95], v[158:159], v[22:23]
	v_pk_fma_f32 v[172:173], v[44:45], v[20:21], v[172:173]
	v_pk_fma_f32 v[22:23], v[98:99], v[160:161], v[22:23]
	v_pk_fma_f32 v[172:173], v[48:49], v[18:19], v[172:173]
	v_add_f32_e32 v190, v22, v23
	v_mul_f32_e32 v23, v42, v21
	v_pk_fma_f32 v[20:21], v[42:43], v[20:21], v[108:109]
	v_pk_fma_f32 v[172:173], v[52:53], v[10:11], v[172:173]
	v_pk_fma_f32 v[20:21], v[46:47], v[18:19], v[20:21]
	v_pk_fma_f32 v[172:173], v[56:57], v[12:13], v[172:173]
	v_pk_fma_f32 v[20:21], v[50:51], v[10:11], v[20:21]
	v_pk_fma_f32 v[172:173], v[60:61], v[14:15], v[172:173]
	v_pk_fma_f32 v[20:21], v[54:55], v[12:13], v[20:21]
	v_pk_fma_f32 v[172:173], v[64:65], v[16:17], v[172:173]
	v_pk_fma_f32 v[20:21], v[58:59], v[14:15], v[20:21]
	v_pk_fma_f32 v[172:173], v[68:69], v[26:27], v[172:173]
	v_pk_fma_f32 v[20:21], v[62:63], v[16:17], v[20:21]
	v_pk_fma_f32 v[172:173], v[72:73], v[28:29], v[172:173]
	v_pk_fma_f32 v[20:21], v[66:67], v[26:27], v[20:21]
	v_pk_fma_f32 v[172:173], v[76:77], v[30:31], v[172:173]
	v_pk_fma_f32 v[20:21], v[70:71], v[28:29], v[20:21]
	v_pk_fma_f32 v[172:173], v[80:81], v[32:33], v[172:173]
	v_pk_fma_f32 v[20:21], v[74:75], v[30:31], v[20:21]
	v_pk_fma_f32 v[172:173], v[84:85], v[40:41], v[172:173]
	v_pk_fma_f32 v[20:21], v[78:79], v[32:33], v[20:21]
	v_pk_fma_f32 v[172:173], v[88:89], v[156:157], v[172:173]
	v_pk_fma_f32 v[20:21], v[82:83], v[40:41], v[20:21]
	v_pk_fma_f32 v[172:173], v[92:93], v[158:159], v[172:173]
	v_pk_fma_f32 v[20:21], v[86:87], v[156:157], v[20:21]
	v_pk_fma_f32 v[172:173], v[96:97], v[160:161], v[172:173]
	v_pk_fma_f32 v[20:21], v[90:91], v[158:159], v[20:21]
	v_pk_fma_f32 v[172:173], v[100:101], v[24:25], v[172:173]
	v_pk_fma_f32 v[20:21], v[94:95], v[160:161], v[20:21]
	v_mov_b32_e32 v22, v108
	v_pk_fma_f32 v[20:21], v[98:99], v[24:25], v[20:21]
	s_waitcnt lgkmcnt(1)
	v_mul_f32_e32 v109, v101, v36
	v_add_f32_e32 v172, v172, v173
	v_pk_fma_f32 v[22:23], v[44:45], v[18:19], v[22:23]
	v_add_f32_e32 v173, v20, v21
	v_mul_f32_e32 v21, v42, v19
	v_pk_fma_f32 v[18:19], v[42:43], v[18:19], v[108:109]
	v_pk_fma_f32 v[22:23], v[48:49], v[10:11], v[22:23]
	v_pk_fma_f32 v[18:19], v[46:47], v[10:11], v[18:19]
	v_pk_fma_f32 v[22:23], v[52:53], v[12:13], v[22:23]
	v_pk_fma_f32 v[18:19], v[50:51], v[12:13], v[18:19]
	v_pk_fma_f32 v[22:23], v[56:57], v[14:15], v[22:23]
	v_pk_fma_f32 v[18:19], v[54:55], v[14:15], v[18:19]
	v_pk_fma_f32 v[22:23], v[60:61], v[16:17], v[22:23]
	v_pk_fma_f32 v[18:19], v[58:59], v[16:17], v[18:19]
	v_pk_fma_f32 v[22:23], v[64:65], v[26:27], v[22:23]
	v_pk_fma_f32 v[18:19], v[62:63], v[26:27], v[18:19]
	v_pk_fma_f32 v[22:23], v[68:69], v[28:29], v[22:23]
	v_pk_fma_f32 v[18:19], v[66:67], v[28:29], v[18:19]
	v_pk_fma_f32 v[22:23], v[72:73], v[30:31], v[22:23]
	v_pk_fma_f32 v[18:19], v[70:71], v[30:31], v[18:19]
	v_pk_fma_f32 v[22:23], v[76:77], v[32:33], v[22:23]
	v_pk_fma_f32 v[18:19], v[74:75], v[32:33], v[18:19]
	v_pk_fma_f32 v[22:23], v[80:81], v[40:41], v[22:23]
	v_pk_fma_f32 v[18:19], v[78:79], v[40:41], v[18:19]
	v_pk_fma_f32 v[22:23], v[84:85], v[156:157], v[22:23]
	v_pk_fma_f32 v[18:19], v[82:83], v[156:157], v[18:19]
	v_pk_fma_f32 v[22:23], v[88:89], v[158:159], v[22:23]
	v_pk_fma_f32 v[18:19], v[86:87], v[158:159], v[18:19]
	v_pk_fma_f32 v[22:23], v[92:93], v[160:161], v[22:23]
	v_pk_fma_f32 v[18:19], v[90:91], v[160:161], v[18:19]
	v_pk_fma_f32 v[22:23], v[96:97], v[24:25], v[22:23]
	v_pk_fma_f32 v[18:19], v[94:95], v[24:25], v[18:19]
	v_pk_fma_f32 v[22:23], v[100:101], v[34:35], v[22:23]
	v_pk_fma_f32 v[18:19], v[98:99], v[34:35], v[18:19]
	v_add_f32_e32 v22, v22, v23
	v_mov_b32_e32 v20, v108
	v_add_f32_e32 v23, v18, v19
	s_waitcnt lgkmcnt(0)
	v_mul_f32_e32 v109, v101, v38
	v_mul_f32_e32 v19, v42, v11
	v_mov_b32_e32 v18, v108
	v_pk_fma_f32 v[20:21], v[44:45], v[10:11], v[20:21]
	v_pk_fma_f32 v[10:11], v[42:43], v[10:11], v[108:109]
	v_pk_fma_f32 v[18:19], v[44:45], v[12:13], v[18:19]
	v_pk_fma_f32 v[20:21], v[48:49], v[12:13], v[20:21]
	v_pk_fma_f32 v[10:11], v[46:47], v[12:13], v[10:11]
	v_pk_fma_f32 v[12:13], v[48:49], v[14:15], v[18:19]
	v_pk_fma_f32 v[20:21], v[52:53], v[14:15], v[20:21]
	v_pk_fma_f32 v[10:11], v[50:51], v[14:15], v[10:11]
	v_pk_fma_f32 v[12:13], v[52:53], v[16:17], v[12:13]
	v_pk_fma_f32 v[20:21], v[56:57], v[16:17], v[20:21]
	v_pk_fma_f32 v[10:11], v[54:55], v[16:17], v[10:11]
	v_pk_fma_f32 v[12:13], v[56:57], v[26:27], v[12:13]
	v_pk_fma_f32 v[20:21], v[60:61], v[26:27], v[20:21]
	v_pk_fma_f32 v[10:11], v[58:59], v[26:27], v[10:11]
	v_pk_fma_f32 v[12:13], v[60:61], v[28:29], v[12:13]
	v_pk_fma_f32 v[20:21], v[64:65], v[28:29], v[20:21]
	v_pk_fma_f32 v[10:11], v[62:63], v[28:29], v[10:11]
	v_pk_fma_f32 v[12:13], v[64:65], v[30:31], v[12:13]
	v_pk_fma_f32 v[20:21], v[68:69], v[30:31], v[20:21]
	v_pk_fma_f32 v[10:11], v[66:67], v[30:31], v[10:11]
	v_pk_fma_f32 v[12:13], v[68:69], v[32:33], v[12:13]
	v_pk_fma_f32 v[20:21], v[72:73], v[32:33], v[20:21]
	v_pk_fma_f32 v[10:11], v[70:71], v[32:33], v[10:11]
	v_pk_fma_f32 v[12:13], v[72:73], v[40:41], v[12:13]
	v_pk_fma_f32 v[20:21], v[76:77], v[40:41], v[20:21]
	v_pk_fma_f32 v[10:11], v[74:75], v[40:41], v[10:11]
	v_pk_fma_f32 v[12:13], v[76:77], v[156:157], v[12:13]
	v_pk_fma_f32 v[20:21], v[80:81], v[156:157], v[20:21]
	v_pk_fma_f32 v[10:11], v[78:79], v[156:157], v[10:11]
	v_pk_fma_f32 v[12:13], v[80:81], v[158:159], v[12:13]
	v_pk_fma_f32 v[20:21], v[84:85], v[158:159], v[20:21]
	v_pk_fma_f32 v[10:11], v[82:83], v[158:159], v[10:11]
	v_pk_fma_f32 v[12:13], v[84:85], v[160:161], v[12:13]
	v_pk_fma_f32 v[20:21], v[88:89], v[160:161], v[20:21]
	v_pk_fma_f32 v[10:11], v[86:87], v[160:161], v[10:11]
	v_pk_fma_f32 v[12:13], v[88:89], v[24:25], v[12:13]
	v_pk_fma_f32 v[20:21], v[92:93], v[24:25], v[20:21]
	v_pk_fma_f32 v[10:11], v[90:91], v[24:25], v[10:11]
	v_pk_fma_f32 v[12:13], v[92:93], v[34:35], v[12:13]
	s_lshl_b32 s6, s28, 10
	v_pk_fma_f32 v[20:21], v[96:97], v[34:35], v[20:21]
	v_pk_fma_f32 v[10:11], v[94:95], v[34:35], v[10:11]
	v_pk_fma_f32 v[12:13], v[96:97], v[36:37], v[12:13]
	s_add_i32 s6, s6, 0
	v_pk_fma_f32 v[20:21], v[100:101], v[36:37], v[20:21]
	v_pk_fma_f32 v[10:11], v[98:99], v[36:37], v[10:11]
	v_pk_fma_f32 v[12:13], v[100:101], v[38:39], v[12:13]
	v_add_u32_e32 v109, s6, v162
	v_add_f32_e32 v20, v20, v21
	v_add_f32_e32 v10, v10, v11
	v_add_f32_e32 v11, v12, v13
	s_barrier
	ds_write2st64_b32 v163, v164, v165 offset1:4
	ds_write2st64_b32 v163, v166, v167 offset0:8 offset1:12
	ds_write2st64_b32 v163, v168, v169 offset0:16 offset1:20
	ds_write2st64_b32 v163, v170, v171 offset0:24 offset1:28
	ds_write2st64_b32 v163, v174, v175 offset0:32 offset1:36
	ds_write2st64_b32 v163, v176, v177 offset0:40 offset1:44
	ds_write2st64_b32 v163, v178, v179 offset0:48 offset1:52
	ds_write2st64_b32 v163, v180, v181 offset0:56 offset1:60
	ds_write2st64_b32 v163, v182, v183 offset0:64 offset1:68
	ds_write2st64_b32 v163, v184, v185 offset0:72 offset1:76
	ds_write2st64_b32 v163, v186, v187 offset0:80 offset1:84
	ds_write2st64_b32 v163, v188, v189 offset0:88 offset1:92
	ds_write2st64_b32 v163, v190, v172 offset0:96 offset1:100
	ds_write2st64_b32 v163, v173, v22 offset0:104 offset1:108
	ds_write2st64_b32 v163, v23, v20 offset0:112 offset1:116
	ds_write2st64_b32 v163, v10, v11 offset0:120 offset1:124
	s_waitcnt lgkmcnt(0)
	s_barrier
	ds_read_b128 v[38:41], v109
	ds_read_b128 v[34:37], v109 offset:8192
	ds_read_b128 v[30:33], v109 offset:16384
	ds_read_b128 v[26:29], v109 offset:24576
	ds_read_b128 v[22:25], v109 offset:32768
	ds_read_b128 v[18:21], v109 offset:40960
	s_waitcnt lgkmcnt(5)
	v_mov_b32_e32 v10, v39
	v_mov_b32_e32 v11, v40
	v_mov_b32_e32 v12, v38
	v_mov_b32_e32 v13, v41
	v_pk_add_f32 v[10:11], v[10:11], v[12:13]
	s_waitcnt lgkmcnt(4)
	v_mov_b32_e32 v12, v34
	v_add_f32_e32 v160, v10, v11
	v_mov_b32_e32 v10, v35
	v_mov_b32_e32 v11, v36
	v_mov_b32_e32 v13, v37
	v_pk_add_f32 v[10:11], v[10:11], v[12:13]
	s_waitcnt lgkmcnt(3)
	v_mov_b32_e32 v12, v30
	v_add_f32_e32 v161, v10, v11
	v_mov_b32_e32 v10, v31
	v_mov_b32_e32 v11, v32
	v_mov_b32_e32 v13, v33
	v_pk_add_f32 v[10:11], v[10:11], v[12:13]
	s_waitcnt lgkmcnt(2)
	v_mov_b32_e32 v12, v26
	v_add_f32_e32 v162, v10, v11
	v_mov_b32_e32 v10, v27
	v_mov_b32_e32 v11, v28
	v_mov_b32_e32 v13, v29
	v_pk_add_f32 v[10:11], v[10:11], v[12:13]
	s_waitcnt lgkmcnt(1)
	v_mov_b32_e32 v12, v22
	v_add_f32_e32 v163, v10, v11
	v_mov_b32_e32 v10, v23
	v_mov_b32_e32 v11, v24
	v_mov_b32_e32 v13, v25
	v_pk_add_f32 v[10:11], v[10:11], v[12:13]
	s_waitcnt lgkmcnt(0)
	v_mov_b32_e32 v12, v18
	v_add_f32_e32 v164, v10, v11
	v_mov_b32_e32 v10, v19
	v_mov_b32_e32 v11, v20
	ds_read_b128 v[14:17], v109 offset:49152
	v_mov_b32_e32 v13, v21
	v_pk_add_f32 v[10:11], v[10:11], v[12:13]
	s_add_i32 s28, s57, s28
	v_add_f32_e32 v165, v10, v11
	ds_read_b128 v[10:13], v109 offset:57344
	s_waitcnt lgkmcnt(1)
	v_mov_b32_e32 v156, v15
	v_mov_b32_e32 v157, v16
	v_mov_b32_e32 v158, v14
	v_mov_b32_e32 v159, v17
	v_pk_add_f32 v[156:157], v[156:157], v[158:159]
	s_waitcnt lgkmcnt(0)
	v_mov_b32_e32 v158, v10
	v_add_f32_e32 v109, v156, v157
	v_mov_b32_e32 v156, v11
	v_mov_b32_e32 v157, v12
	v_mov_b32_e32 v159, v13
	v_pk_add_f32 v[156:157], v[156:157], v[158:159]
	v_add_f32_dpp v158, v161, v161 quad_perm:[1,0,3,2] row_mask:0xf bank_mask:0xf bound_ctrl:1
	v_add_f32_e32 v156, v156, v157
	v_add_f32_dpp v157, v160, v160 quad_perm:[1,0,3,2] row_mask:0xf bank_mask:0xf bound_ctrl:1
	v_add_f32_dpp v160, v163, v163 quad_perm:[1,0,3,2] row_mask:0xf bank_mask:0xf bound_ctrl:1
	v_add_f32_dpp v158, v158, v158 quad_perm:[2,3,0,1] row_mask:0xf bank_mask:0xf bound_ctrl:1
	v_add_f32_dpp v157, v157, v157 quad_perm:[2,3,0,1] row_mask:0xf bank_mask:0xf bound_ctrl:1
	v_add_f32_dpp v159, v162, v162 quad_perm:[1,0,3,2] row_mask:0xf bank_mask:0xf bound_ctrl:1
	s_nop 0
	v_add_f32_dpp v157, v157, v157 row_half_mirror row_mask:0xf bank_mask:0xf bound_ctrl:1
	v_add_f32_dpp v158, v158, v158 row_half_mirror row_mask:0xf bank_mask:0xf bound_ctrl:1
	v_add_f32_dpp v159, v159, v159 quad_perm:[2,3,0,1] row_mask:0xf bank_mask:0xf bound_ctrl:1
	v_add_f32_dpp v157, v157, v157 row_mirror row_mask:0xf bank_mask:0xf bound_ctrl:1
	v_add_f32_dpp v158, v158, v158 row_mirror row_mask:0xf bank_mask:0xf bound_ctrl:1
	v_add_f32_dpp v159, v159, v159 row_half_mirror row_mask:0xf bank_mask:0xf bound_ctrl:1
	v_add_f32_dpp v157, v157, v157 row_bcast:15 row_mask:0xa bank_mask:0xf
	v_add_f32_dpp v160, v160, v160 quad_perm:[2,3,0,1] row_mask:0xf bank_mask:0xf bound_ctrl:1
	v_add_f32_dpp v159, v159, v159 row_mirror row_mask:0xf bank_mask:0xf bound_ctrl:1
	v_add_f32_dpp v158, v158, v158 row_bcast:15 row_mask:0xa bank_mask:0xf
	v_add_f32_dpp v161, v164, v164 quad_perm:[1,0,3,2] row_mask:0xf bank_mask:0xf bound_ctrl:1
	v_add_f32_dpp v160, v160, v160 row_half_mirror row_mask:0xf bank_mask:0xf bound_ctrl:1
	v_add_f32_dpp v159, v159, v159 row_bcast:15 row_mask:0xa bank_mask:0xf
	v_add_f32_dpp v161, v161, v161 quad_perm:[2,3,0,1] row_mask:0xf bank_mask:0xf bound_ctrl:1
	v_add_f32_dpp v160, v160, v160 row_mirror row_mask:0xf bank_mask:0xf bound_ctrl:1
	v_add_f32_dpp v162, v165, v165 quad_perm:[1,0,3,2] row_mask:0xf bank_mask:0xf bound_ctrl:1
	v_add_f32_dpp v161, v161, v161 row_half_mirror row_mask:0xf bank_mask:0xf bound_ctrl:1
	v_add_f32_dpp v160, v160, v160 row_bcast:15 row_mask:0xa bank_mask:0xf
	v_add_f32_dpp v162, v162, v162 quad_perm:[2,3,0,1] row_mask:0xf bank_mask:0xf bound_ctrl:1
	v_add_f32_dpp v161, v161, v161 row_mirror row_mask:0xf bank_mask:0xf bound_ctrl:1
	v_add_f32_dpp v109, v109, v109 quad_perm:[1,0,3,2] row_mask:0xf bank_mask:0xf bound_ctrl:1
	v_add_f32_dpp v162, v162, v162 row_half_mirror row_mask:0xf bank_mask:0xf bound_ctrl:1
	v_add_f32_dpp v161, v161, v161 row_bcast:15 row_mask:0xa bank_mask:0xf
	v_add_f32_dpp v109, v109, v109 quad_perm:[2,3,0,1] row_mask:0xf bank_mask:0xf bound_ctrl:1
	v_add_f32_dpp v162, v162, v162 row_mirror row_mask:0xf bank_mask:0xf bound_ctrl:1
	v_add_f32_dpp v156, v156, v156 quad_perm:[1,0,3,2] row_mask:0xf bank_mask:0xf bound_ctrl:1
	v_add_f32_dpp v109, v109, v109 row_half_mirror row_mask:0xf bank_mask:0xf bound_ctrl:1
	v_add_f32_dpp v162, v162, v162 row_bcast:15 row_mask:0xa bank_mask:0xf
	v_add_f32_dpp v156, v156, v156 quad_perm:[2,3,0,1] row_mask:0xf bank_mask:0xf bound_ctrl:1
	v_add_f32_dpp v109, v109, v109 row_mirror row_mask:0xf bank_mask:0xf bound_ctrl:1
	s_nop 0
	v_add_f32_dpp v156, v156, v156 row_half_mirror row_mask:0xf bank_mask:0xf bound_ctrl:1
	s_nop 0
	v_add_f32_dpp v109, v109, v109 row_bcast:15 row_mask:0xa bank_mask:0xf
	v_add_f32_dpp v156, v156, v156 row_mirror row_mask:0xf bank_mask:0xf bound_ctrl:1
	s_nop 1
	v_add_f32_dpp v156, v156, v156 row_bcast:15 row_mask:0xa bank_mask:0xf
	s_nop 1
	v_add_f32_dpp v157, v157, v157 row_bcast:31 row_mask:0xc bank_mask:0xf
	s_nop 0
	v_readlane_b32 s6, v157, 63
	s_nop 0
	v_add_f32_dpp v158, v158, v158 row_bcast:31 row_mask:0xc bank_mask:0xf
	v_fma_f32 v39, s6, v239, v39
	v_fma_f32 v38, s6, v239, v38
	v_add_f32_dpp v159, v159, v159 row_bcast:31 row_mask:0xc bank_mask:0xf
	v_fma_f32 v41, s6, v239, v41
	v_fmac_f32_e32 v40, s6, v239
	v_add_f32_dpp v160, v160, v160 row_bcast:31 row_mask:0xc bank_mask:0xf
	v_readlane_b32 s7, v158, 63
	v_readlane_b32 s8, v159, 63
	v_add_f32_dpp v161, v161, v161 row_bcast:31 row_mask:0xc bank_mask:0xf
	v_pk_mul_f32 v[158:159], v[38:39], v[38:39]
	v_readlane_b32 s9, v160, 63
	v_add_f32_dpp v162, v162, v162 row_bcast:31 row_mask:0xc bank_mask:0xf
	v_readlane_b32 s10, v161, 63
	v_fma_f32 v35, s7, v239, v35
	v_add_f32_dpp v109, v109, v109 row_bcast:31 row_mask:0xc bank_mask:0xf
	v_fma_f32 v34, s7, v239, v34
	v_fma_f32 v37, s7, v239, v37
	v_add_f32_dpp v156, v156, v156 row_bcast:31 row_mask:0xc bank_mask:0xf
	v_fmac_f32_e32 v36, s7, v239
	v_readlane_b32 s60, v156, 63
	v_pk_mul_f32 v[156:157], v[40:41], v[40:41]
	v_readlane_b32 s29, v109, 63
	v_pk_mov_b32 v[160:161], v[158:159], v[156:157] op_sel:[1,0]
	v_mov_b32_e32 v159, v157
	v_pk_add_f32 v[156:157], v[160:161], v[158:159]
	v_pk_mul_f32 v[158:159], v[34:35], v[34:35]
	v_add_f32_e32 v109, v156, v157
	v_pk_mul_f32 v[156:157], v[36:37], v[36:37]
	v_fma_f32 v31, s8, v239, v31
	v_pk_mov_b32 v[160:161], v[158:159], v[156:157] op_sel:[1,0]
	v_mov_b32_e32 v159, v157
	v_pk_add_f32 v[156:157], v[160:161], v[158:159]
	v_fma_f32 v30, s8, v239, v30
	v_fma_f32 v33, s8, v239, v33
	v_fmac_f32_e32 v32, s8, v239
	v_readlane_b32 s11, v162, 63
	v_add_f32_e32 v162, v156, v157
	v_pk_mul_f32 v[156:157], v[32:33], v[32:33]
	v_pk_mul_f32 v[158:159], v[30:31], v[30:31]
	v_fma_f32 v27, s9, v239, v27
	v_pk_mov_b32 v[160:161], v[158:159], v[156:157] op_sel:[1,0]
	v_mov_b32_e32 v159, v157
	v_pk_add_f32 v[156:157], v[160:161], v[158:159]
	v_fma_f32 v26, s9, v239, v26
	v_fma_f32 v29, s9, v239, v29
	v_fmac_f32_e32 v28, s9, v239
	v_add_f32_e32 v163, v156, v157
	v_pk_mul_f32 v[156:157], v[28:29], v[28:29]
	v_pk_mul_f32 v[158:159], v[26:27], v[26:27]
	v_fma_f32 v23, s10, v239, v23
	v_pk_mov_b32 v[160:161], v[158:159], v[156:157] op_sel:[1,0]
	v_mov_b32_e32 v159, v157
	v_pk_add_f32 v[156:157], v[160:161], v[158:159]
	v_fma_f32 v22, s10, v239, v22
	v_fma_f32 v25, s10, v239, v25
	v_fmac_f32_e32 v24, s10, v239
	v_add_f32_e32 v164, v156, v157
	v_pk_mul_f32 v[156:157], v[24:25], v[24:25]
	v_pk_mul_f32 v[158:159], v[22:23], v[22:23]
	v_fma_f32 v19, s11, v239, v19
	v_pk_mov_b32 v[160:161], v[158:159], v[156:157] op_sel:[1,0]
	v_mov_b32_e32 v159, v157
	v_pk_add_f32 v[156:157], v[160:161], v[158:159]
	v_fma_f32 v18, s11, v239, v18
	v_fma_f32 v21, s11, v239, v21
	v_fmac_f32_e32 v20, s11, v239
	v_add_f32_e32 v165, v156, v157
	v_pk_mul_f32 v[156:157], v[20:21], v[20:21]
	v_pk_mul_f32 v[158:159], v[18:19], v[18:19]
	v_fma_f32 v15, s29, v239, v15
	v_pk_mov_b32 v[160:161], v[158:159], v[156:157] op_sel:[1,0]
	v_mov_b32_e32 v159, v157
	v_pk_add_f32 v[156:157], v[160:161], v[158:159]
	v_fma_f32 v14, s29, v239, v14
	v_fma_f32 v17, s29, v239, v17
	v_fmac_f32_e32 v16, s29, v239
	v_add_f32_e32 v166, v156, v157
	v_pk_mul_f32 v[156:157], v[16:17], v[16:17]
	v_pk_mul_f32 v[158:159], v[14:15], v[14:15]
	v_fma_f32 v11, s60, v239, v11
	v_pk_mov_b32 v[160:161], v[158:159], v[156:157] op_sel:[1,0]
	v_mov_b32_e32 v159, v157
	v_pk_add_f32 v[156:157], v[160:161], v[158:159]
	v_fma_f32 v10, s60, v239, v10
	v_fma_f32 v13, s60, v239, v13
	v_fmac_f32_e32 v12, s60, v239
	v_add_f32_e32 v167, v156, v157
	v_pk_mul_f32 v[156:157], v[12:13], v[12:13]
	v_pk_mul_f32 v[158:159], v[10:11], v[10:11]
	v_add_f32_dpp v109, v109, v109 quad_perm:[1,0,3,2] row_mask:0xf bank_mask:0xf bound_ctrl:1
	v_pk_mov_b32 v[160:161], v[158:159], v[156:157] op_sel:[1,0]
	v_mov_b32_e32 v159, v157
	v_pk_add_f32 v[156:157], v[160:161], v[158:159]
	v_add_f32_dpp v109, v109, v109 quad_perm:[2,3,0,1] row_mask:0xf bank_mask:0xf bound_ctrl:1
	v_add_f32_e32 v156, v156, v157
	v_add_f32_dpp v157, v162, v162 quad_perm:[1,0,3,2] row_mask:0xf bank_mask:0xf bound_ctrl:1
	v_add_f32_dpp v109, v109, v109 row_half_mirror row_mask:0xf bank_mask:0xf bound_ctrl:1
	v_add_f32_dpp v158, v163, v163 quad_perm:[1,0,3,2] row_mask:0xf bank_mask:0xf bound_ctrl:1
	v_add_f32_dpp v157, v157, v157 quad_perm:[2,3,0,1] row_mask:0xf bank_mask:0xf bound_ctrl:1
	v_add_f32_dpp v109, v109, v109 row_mirror row_mask:0xf bank_mask:0xf bound_ctrl:1
	s_nop 0
	v_add_f32_dpp v157, v157, v157 row_half_mirror row_mask:0xf bank_mask:0xf bound_ctrl:1
	v_add_f32_dpp v158, v158, v158 quad_perm:[2,3,0,1] row_mask:0xf bank_mask:0xf bound_ctrl:1
	v_add_f32_dpp v109, v109, v109 row_bcast:15 row_mask:0xa bank_mask:0xf
	v_add_f32_dpp v157, v157, v157 row_mirror row_mask:0xf bank_mask:0xf bound_ctrl:1
	v_add_f32_dpp v159, v164, v164 quad_perm:[1,0,3,2] row_mask:0xf bank_mask:0xf bound_ctrl:1
	v_add_f32_dpp v158, v158, v158 row_half_mirror row_mask:0xf bank_mask:0xf bound_ctrl:1
	v_add_f32_dpp v157, v157, v157 row_bcast:15 row_mask:0xa bank_mask:0xf
	v_add_f32_dpp v159, v159, v159 quad_perm:[2,3,0,1] row_mask:0xf bank_mask:0xf bound_ctrl:1
	v_add_f32_dpp v158, v158, v158 row_mirror row_mask:0xf bank_mask:0xf bound_ctrl:1
	v_add_f32_dpp v160, v165, v165 quad_perm:[1,0,3,2] row_mask:0xf bank_mask:0xf bound_ctrl:1
	v_add_f32_dpp v159, v159, v159 row_half_mirror row_mask:0xf bank_mask:0xf bound_ctrl:1
	v_add_f32_dpp v158, v158, v158 row_bcast:15 row_mask:0xa bank_mask:0xf
	v_add_f32_dpp v160, v160, v160 quad_perm:[2,3,0,1] row_mask:0xf bank_mask:0xf bound_ctrl:1
	v_add_f32_dpp v159, v159, v159 row_mirror row_mask:0xf bank_mask:0xf bound_ctrl:1
	v_add_f32_dpp v161, v166, v166 quad_perm:[1,0,3,2] row_mask:0xf bank_mask:0xf bound_ctrl:1
	v_add_f32_dpp v160, v160, v160 row_half_mirror row_mask:0xf bank_mask:0xf bound_ctrl:1
	v_add_f32_dpp v159, v159, v159 row_bcast:15 row_mask:0xa bank_mask:0xf
	v_add_f32_dpp v161, v161, v161 quad_perm:[2,3,0,1] row_mask:0xf bank_mask:0xf bound_ctrl:1
	v_add_f32_dpp v160, v160, v160 row_mirror row_mask:0xf bank_mask:0xf bound_ctrl:1
	v_add_f32_dpp v162, v167, v167 quad_perm:[1,0,3,2] row_mask:0xf bank_mask:0xf bound_ctrl:1
	v_add_f32_dpp v161, v161, v161 row_half_mirror row_mask:0xf bank_mask:0xf bound_ctrl:1
	v_add_f32_dpp v160, v160, v160 row_bcast:15 row_mask:0xa bank_mask:0xf
	v_add_f32_dpp v162, v162, v162 quad_perm:[2,3,0,1] row_mask:0xf bank_mask:0xf bound_ctrl:1
	v_add_f32_dpp v161, v161, v161 row_mirror row_mask:0xf bank_mask:0xf bound_ctrl:1
	v_add_f32_dpp v156, v156, v156 quad_perm:[1,0,3,2] row_mask:0xf bank_mask:0xf bound_ctrl:1
	v_add_f32_dpp v162, v162, v162 row_half_mirror row_mask:0xf bank_mask:0xf bound_ctrl:1
	v_add_f32_dpp v161, v161, v161 row_bcast:15 row_mask:0xa bank_mask:0xf
	v_add_f32_dpp v156, v156, v156 quad_perm:[2,3,0,1] row_mask:0xf bank_mask:0xf bound_ctrl:1
	v_add_f32_dpp v162, v162, v162 row_mirror row_mask:0xf bank_mask:0xf bound_ctrl:1
	s_nop 0
	v_add_f32_dpp v156, v156, v156 row_half_mirror row_mask:0xf bank_mask:0xf bound_ctrl:1
	s_ashr_i32 s29, s28, 31
	v_add_f32_dpp v162, v162, v162 row_bcast:15 row_mask:0xa bank_mask:0xf
	v_add_f32_dpp v156, v156, v156 row_mirror row_mask:0xf bank_mask:0xf bound_ctrl:1
	s_lshl_b64 s[8:9], s[28:29], 11
	s_add_u32 s8, s76, s8
	v_add_f32_dpp v156, v156, v156 row_bcast:15 row_mask:0xa bank_mask:0xf
	s_addc_u32 s9, s77, s9
	s_nop 0
	v_add_f32_dpp v109, v109, v109 row_bcast:31 row_mask:0xc bank_mask:0xf
	s_nop 0
	v_readlane_b32 s6, v109, 63
	s_nop 0
	v_add_f32_dpp v157, v157, v157 row_bcast:31 row_mask:0xc bank_mask:0xf
	v_fma_f32 v109, s6, v235, v225
	v_readlane_b32 s10, v157, 63
	v_add_f32_dpp v158, v158, v158 row_bcast:31 row_mask:0xc bank_mask:0xf
	s_nop 0
	v_readlane_b32 s11, v158, 63
	s_nop 0
	v_add_f32_dpp v159, v159, v159 row_bcast:31 row_mask:0xc bank_mask:0xf
	s_nop 0
	v_readlane_b32 s65, v159, 63
	s_nop 0
	v_add_f32_dpp v160, v160, v160 row_bcast:31 row_mask:0xc bank_mask:0xf
	s_nop 0
	v_readlane_b32 s61, v160, 63
	s_nop 0
	v_add_f32_dpp v161, v161, v161 row_bcast:31 row_mask:0xc bank_mask:0xf
	s_nop 0
	v_readlane_b32 s60, v161, 63
	s_nop 0
	v_add_f32_dpp v162, v162, v162 row_bcast:31 row_mask:0xc bank_mask:0xf
	v_mov_b32_e32 v163, v131
	v_readlane_b32 s7, v162, 63
	s_nop 0
	v_mov_b32_dpp v163, v156 row_bcast:31 row_mask:0xc bank_mask:0xf
	v_add_f32_e32 v163, v156, v163
	v_rsq_f32_e32 v156, v109
	v_readlane_b32 s6, v163, 63
	v_pk_mul_f32 v[38:39], v[38:39], v[156:157] op_sel_hi:[1,0]
	s_nop 0
	v_pk_fma_f32 v[38:39], v[2:3], v[38:39], v[6:7]
	v_pk_mul_f32 v[40:41], v[40:41], v[156:157] op_sel_hi:[1,0]
	v_mul_f32_e32 v109, 0xbfb8aa3b, v38
	v_exp_f32_e32 v109, v109
	v_mul_f32_e32 v156, 0xbfb8aa3b, v39
	v_exp_f32_e32 v157, v156
	v_pk_fma_f32 v[40:41], v[4:5], v[40:41], v[8:9]
	v_add_f32_e32 v109, 1.0, v109
	v_rcp_f32_e32 v156, v109
	v_add_f32_e32 v109, 1.0, v157
	v_mul_f32_e32 v157, 0xbfb8aa3b, v40
	v_exp_f32_e32 v158, v157
	v_mul_f32_e32 v157, 0xbfb8aa3b, v41
	v_exp_f32_e32 v159, v157
	v_rcp_f32_e32 v157, v109
	v_add_f32_e32 v109, 1.0, v158
	v_rcp_f32_e32 v158, v109
	v_add_f32_e32 v109, 1.0, v159
	v_rcp_f32_e32 v159, v109
	v_pk_mul_f32 v[38:39], v[38:39], v[156:157]
	v_lshlrev_b32_e32 v109, 3, v130
	v_cvt_pk_bf16_f32 v38, v38, v39
	v_pk_mul_f32 v[40:41], v[40:41], v[158:159]
	v_cvt_pk_bf16_f32 v39, v40, v41
	v_fma_f32 v40, s10, v235, v225
	v_rsq_f32_e32 v40, v40
	global_store_dwordx2 v109, v[38:39], s[8:9] offset:512
	s_add_i32 s8, s28, 8
	s_ashr_i32 s9, s8, 31
	v_pk_mul_f32 v[36:37], v[36:37], v[40:41] op_sel_hi:[1,0]
	v_pk_mul_f32 v[34:35], v[34:35], v[40:41] op_sel_hi:[1,0]
	v_pk_fma_f32 v[36:37], v[4:5], v[36:37], v[8:9]
	v_pk_fma_f32 v[34:35], v[2:3], v[34:35], v[6:7]
	v_mul_f32_e32 v130, 0xbfb8aa3b, v36
	v_pk_mul_f32 v[40:41], v[34:35], s[96:97] op_sel_hi:[1,0]
	v_exp_f32_e32 v130, v130
	v_mul_f32_e32 v156, 0xbfb8aa3b, v37
	v_exp_f32_e32 v40, v40
	v_exp_f32_e32 v41, v41
	v_exp_f32_e32 v157, v156
	v_add_f32_e32 v130, 1.0, v130
	v_pk_add_f32 v[40:41], v[40:41], 1.0 op_sel_hi:[1,0]
	v_rcp_f32_e32 v156, v130
	v_add_f32_e32 v130, 1.0, v157
	v_rcp_f32_e32 v40, v40
	v_rcp_f32_e32 v41, v41
	v_rcp_f32_e32 v157, v130
	s_lshl_b64 s[8:9], s[8:9], 11
	s_add_u32 s8, s76, s8
	v_pk_mul_f32 v[34:35], v[34:35], v[40:41]
	v_pk_mul_f32 v[36:37], v[36:37], v[156:157]
	v_cvt_pk_bf16_f32 v34, v34, v35
	v_cvt_pk_bf16_f32 v35, v36, v37
	v_fma_f32 v36, s11, v235, v225
	v_rsq_f32_e32 v36, v36
	s_addc_u32 s9, s77, s9
	global_store_dwordx2 v109, v[34:35], s[8:9] offset:512
	s_add_i32 s8, s28, 16
	v_pk_mul_f32 v[30:31], v[30:31], v[36:37] op_sel_hi:[1,0]
	v_pk_mul_f32 v[32:33], v[32:33], v[36:37] op_sel_hi:[1,0]
	v_pk_fma_f32 v[30:31], v[2:3], v[30:31], v[6:7]
	v_pk_fma_f32 v[32:33], v[4:5], v[32:33], v[8:9]
	v_pk_mul_f32 v[36:37], v[30:31], s[96:97] op_sel_hi:[1,0]
	v_pk_mul_f32 v[38:39], v[32:33], s[96:97] op_sel_hi:[1,0]
	v_exp_f32_e32 v36, v36
	v_exp_f32_e32 v37, v37
	v_exp_f32_e32 v38, v38
	v_exp_f32_e32 v39, v39
	v_pk_add_f32 v[36:37], v[36:37], 1.0 op_sel_hi:[1,0]
	v_pk_add_f32 v[38:39], v[38:39], 1.0 op_sel_hi:[1,0]
	v_rcp_f32_e32 v36, v36
	v_rcp_f32_e32 v37, v37
	v_rcp_f32_e32 v38, v38
	v_rcp_f32_e32 v39, v39
	s_ashr_i32 s9, s8, 31
	v_pk_mul_f32 v[30:31], v[30:31], v[36:37]
	s_lshl_b64 s[8:9], s[8:9], 11
	v_pk_mul_f32 v[32:33], v[32:33], v[38:39]
	v_cvt_pk_bf16_f32 v30, v30, v31
	v_cvt_pk_bf16_f32 v31, v32, v33
	v_fma_f32 v32, s65, v235, v225
	v_rsq_f32_e32 v32, v32
	s_add_u32 s8, s76, s8
	s_addc_u32 s9, s77, s9
	global_store_dwordx2 v109, v[30:31], s[8:9] offset:512
	v_pk_mul_f32 v[26:27], v[26:27], v[32:33] op_sel_hi:[1,0]
	v_pk_mul_f32 v[28:29], v[28:29], v[32:33] op_sel_hi:[1,0]
	v_pk_fma_f32 v[26:27], v[2:3], v[26:27], v[6:7]
	v_pk_fma_f32 v[28:29], v[4:5], v[28:29], v[8:9]
	v_pk_mul_f32 v[32:33], v[26:27], s[96:97] op_sel_hi:[1,0]
	v_pk_mul_f32 v[34:35], v[28:29], s[96:97] op_sel_hi:[1,0]
	v_exp_f32_e32 v32, v32
	v_exp_f32_e32 v33, v33
	v_exp_f32_e32 v34, v34
	v_exp_f32_e32 v35, v35
	v_pk_add_f32 v[32:33], v[32:33], 1.0 op_sel_hi:[1,0]
	v_pk_add_f32 v[34:35], v[34:35], 1.0 op_sel_hi:[1,0]
	v_rcp_f32_e32 v32, v32
	v_rcp_f32_e32 v33, v33
	v_rcp_f32_e32 v34, v34
	v_rcp_f32_e32 v35, v35
	s_add_i32 s8, s28, 24
	v_pk_mul_f32 v[26:27], v[26:27], v[32:33]
	s_ashr_i32 s9, s8, 31
	v_pk_mul_f32 v[28:29], v[28:29], v[34:35]
	v_cvt_pk_bf16_f32 v26, v26, v27
	v_cvt_pk_bf16_f32 v27, v28, v29
	v_fma_f32 v28, s61, v235, v225
	v_rsq_f32_e32 v28, v28
	s_lshl_b64 s[8:9], s[8:9], 11
	s_add_u32 s8, s76, s8
	s_addc_u32 s9, s77, s9
	v_pk_mul_f32 v[22:23], v[22:23], v[28:29] op_sel_hi:[1,0]
	v_pk_mul_f32 v[24:25], v[24:25], v[28:29] op_sel_hi:[1,0]
	v_pk_fma_f32 v[22:23], v[2:3], v[22:23], v[6:7]
	v_pk_fma_f32 v[24:25], v[4:5], v[24:25], v[8:9]
	v_pk_mul_f32 v[28:29], v[22:23], s[96:97] op_sel_hi:[1,0]
	v_pk_mul_f32 v[30:31], v[24:25], s[96:97] op_sel_hi:[1,0]
	v_exp_f32_e32 v28, v28
	v_exp_f32_e32 v29, v29
	v_exp_f32_e32 v30, v30
	v_exp_f32_e32 v31, v31
	v_pk_add_f32 v[28:29], v[28:29], 1.0 op_sel_hi:[1,0]
	v_pk_add_f32 v[30:31], v[30:31], 1.0 op_sel_hi:[1,0]
	v_rcp_f32_e32 v28, v28
	v_rcp_f32_e32 v29, v29
	v_rcp_f32_e32 v30, v30
	v_rcp_f32_e32 v31, v31
	global_store_dwordx2 v109, v[26:27], s[8:9] offset:512
	v_pk_mul_f32 v[22:23], v[22:23], v[28:29]
	s_add_i32 s8, s28, 32
	v_pk_mul_f32 v[24:25], v[24:25], v[30:31]
	v_cvt_pk_bf16_f32 v22, v22, v23
	v_cvt_pk_bf16_f32 v23, v24, v25
	v_fma_f32 v24, s60, v235, v225
	v_rsq_f32_e32 v24, v24
	s_ashr_i32 s9, s8, 31
	s_lshl_b64 s[8:9], s[8:9], 11
	s_add_u32 s8, s76, s8
	v_pk_mul_f32 v[18:19], v[18:19], v[24:25] op_sel_hi:[1,0]
	v_pk_mul_f32 v[20:21], v[20:21], v[24:25] op_sel_hi:[1,0]
	v_pk_fma_f32 v[18:19], v[2:3], v[18:19], v[6:7]
	v_pk_fma_f32 v[20:21], v[4:5], v[20:21], v[8:9]
	v_pk_mul_f32 v[24:25], v[18:19], s[96:97] op_sel_hi:[1,0]
	v_pk_mul_f32 v[26:27], v[20:21], s[96:97] op_sel_hi:[1,0]
	v_exp_f32_e32 v24, v24
	v_exp_f32_e32 v25, v25
	v_exp_f32_e32 v26, v26
	v_exp_f32_e32 v27, v27
	v_pk_add_f32 v[24:25], v[24:25], 1.0 op_sel_hi:[1,0]
	v_pk_add_f32 v[26:27], v[26:27], 1.0 op_sel_hi:[1,0]
	v_rcp_f32_e32 v24, v24
	v_rcp_f32_e32 v25, v25
	v_rcp_f32_e32 v26, v26
	v_rcp_f32_e32 v27, v27
	s_addc_u32 s9, s77, s9
	v_pk_mul_f32 v[18:19], v[18:19], v[24:25]
	global_store_dwordx2 v109, v[22:23], s[8:9] offset:512
	v_pk_mul_f32 v[20:21], v[20:21], v[26:27]
	v_cvt_pk_bf16_f32 v18, v18, v19
	v_cvt_pk_bf16_f32 v19, v20, v21
	v_fma_f32 v20, s7, v235, v225
	v_rsq_f32_e32 v20, v20
	s_add_i32 s8, s28, 40
	s_ashr_i32 s9, s8, 31
	s_lshl_b64 s[8:9], s[8:9], 11
	v_pk_mul_f32 v[14:15], v[14:15], v[20:21] op_sel_hi:[1,0]
	v_pk_mul_f32 v[16:17], v[16:17], v[20:21] op_sel_hi:[1,0]
	v_pk_fma_f32 v[14:15], v[2:3], v[14:15], v[6:7]
	v_pk_fma_f32 v[16:17], v[4:5], v[16:17], v[8:9]
	v_pk_mul_f32 v[20:21], v[14:15], s[96:97] op_sel_hi:[1,0]
	v_pk_mul_f32 v[22:23], v[16:17], s[96:97] op_sel_hi:[1,0]
	v_exp_f32_e32 v20, v20
	v_exp_f32_e32 v21, v21
	v_exp_f32_e32 v22, v22
	v_exp_f32_e32 v23, v23
	v_pk_add_f32 v[20:21], v[20:21], 1.0 op_sel_hi:[1,0]
	v_pk_add_f32 v[22:23], v[22:23], 1.0 op_sel_hi:[1,0]
	v_rcp_f32_e32 v20, v20
	v_rcp_f32_e32 v21, v21
	v_rcp_f32_e32 v22, v22
	v_rcp_f32_e32 v23, v23
	s_add_u32 s8, s76, s8
	v_pk_mul_f32 v[14:15], v[14:15], v[20:21]
	s_addc_u32 s9, s77, s9
	v_pk_mul_f32 v[16:17], v[16:17], v[22:23]
	v_cvt_pk_bf16_f32 v14, v14, v15
	v_cvt_pk_bf16_f32 v15, v16, v17
	v_fma_f32 v16, s6, v235, v225
	v_rsq_f32_e32 v16, v16
	global_store_dwordx2 v109, v[18:19], s[8:9] offset:512
	s_add_i32 s8, s28, 48
	s_ashr_i32 s9, s8, 31
	v_pk_mul_f32 v[10:11], v[10:11], v[16:17] op_sel_hi:[1,0]
	v_pk_mul_f32 v[12:13], v[12:13], v[16:17] op_sel_hi:[1,0]
	v_pk_fma_f32 v[10:11], v[2:3], v[10:11], v[6:7]
	v_pk_fma_f32 v[12:13], v[4:5], v[12:13], v[8:9]
	v_pk_mul_f32 v[16:17], v[10:11], s[96:97] op_sel_hi:[1,0]
	v_pk_mul_f32 v[18:19], v[12:13], s[96:97] op_sel_hi:[1,0]
	v_exp_f32_e32 v16, v16
	v_exp_f32_e32 v17, v17
	v_exp_f32_e32 v18, v18
	v_exp_f32_e32 v19, v19
	s_lshl_b64 s[6:7], s[8:9], 11
	s_add_u32 s6, s76, s6
	s_addc_u32 s7, s77, s7
	v_pk_add_f32 v[16:17], v[16:17], 1.0 op_sel_hi:[1,0]
	v_pk_add_f32 v[18:19], v[18:19], 1.0 op_sel_hi:[1,0]
	v_rcp_f32_e32 v16, v16
	v_rcp_f32_e32 v17, v17
	v_rcp_f32_e32 v18, v18
	v_rcp_f32_e32 v19, v19
	global_store_dwordx2 v109, v[14:15], s[6:7] offset:512
	s_add_i32 s6, s28, 56
	s_ashr_i32 s7, s6, 31
	s_lshl_b64 s[6:7], s[6:7], 11
	s_add_u32 s6, s76, s6
	v_pk_mul_f32 v[10:11], v[10:11], v[16:17]
	v_pk_mul_f32 v[12:13], v[12:13], v[18:19]
	s_addc_u32 s7, s77, s7
	s_addk_i32 s58, 0x80
	s_addk_i32 s57, 0x2000
	v_cvt_pk_bf16_f32 v10, v10, v11
	v_cvt_pk_bf16_f32 v11, v12, v13
	s_cmpk_gt_i32 s59, 0xff
	global_store_dwordx2 v109, v[10:11], s[6:7] offset:512
	s_barrier
	s_cbranch_scc1 .LBB0_313

.LBB0_312:
	s_waitcnt vmcnt(8)
	v_lshlrev_b32_e32 v12, 16, v106
	v_and_b32_e32 v13, 0xffff0000, v106
	v_lshlrev_b32_e32 v14, 16, v107
	v_and_b32_e32 v15, 0xffff0000, v107
	v_pk_mul_f32 v[12:13], v[12:13], s[96:97] op_sel_hi:[1,0]
	v_pk_mul_f32 v[14:15], v[14:15], s[96:97] op_sel_hi:[1,0]
	v_exp_f32_e32 v12, v12
	v_exp_f32_e32 v13, v13
	v_exp_f32_e32 v14, v14
	v_exp_f32_e32 v15, v15
	v_pk_add_f32 v[12:13], v[12:13], 1.0 op_sel_hi:[1,0]
	v_pk_add_f32 v[14:15], v[14:15], 1.0 op_sel_hi:[1,0]
	v_rcp_f32_e32 v12, v12
	v_rcp_f32_e32 v13, v13
	v_rcp_f32_e32 v14, v14
	v_rcp_f32_e32 v15, v15
	s_add_i32 s8, s28, 0x58
	s_waitcnt vmcnt(23)
	v_and_b32_e32 v17, 0xffff0000, v104
	v_and_b32_e32 v19, 0xffff0000, v105
	v_lshlrev_b32_e32 v16, 16, v104
	v_lshlrev_b32_e32 v18, 16, v105
	s_cmp_ge_i32 s8, s7
	v_pk_mul_f32 v[14:15], v[14:15], v[18:19]
	v_pk_mul_f32 v[12:13], v[12:13], v[16:17]
	s_cselect_b64 vcc, -1, 0
	v_lshl_add_u32 v11, s8, 10, v11
	v_cndmask_b32_e32 v13, 0, v13, vcc
	v_cndmask_b32_e32 v12, 0, v12, vcc
	v_cndmask_b32_e32 v15, 0, v15, vcc
	v_cndmask_b32_e32 v14, 0, v14, vcc
	ds_write_b128 v11, v[12:15]
	s_branch .LBB0_288

.LBB0_319:
	s_add_i32 s65, s6, 32
	s_add_i32 s6, s6, 64
	s_cmpk_lt_i32 s65, 0x1e0
	s_cselect_b32 s6, s6, s65
	s_lshl_b32 s6, s6, 6
	s_and_b32 s8, s6, 0xfc0
	s_sub_i32 s8, s8, 30
	s_add_i32 s9, s8, s63
	s_and_b32 s6, s6, 0xfffff000
	s_max_i32 s9, s9, 0
	s_add_i32 s66, s9, s6
	s_add_i32 s9, s8, s62
	s_max_i32 s9, s9, 0
	s_add_i32 s67, s9, s6
	s_add_i32 s9, s8, s61
	s_max_i32 s9, s9, 0
	s_add_i32 s68, s9, s6
	s_add_i32 s9, s8, s60
	s_max_i32 s9, s9, 0
	s_add_i32 s69, s9, s6
	s_add_i32 s9, s8, s59
	s_max_i32 s9, s9, 0
	s_add_i32 s72, s9, s6
	s_add_i32 s9, s8, s58
	s_max_i32 s9, s9, 0
	s_add_i32 s73, s9, s6
	s_add_i32 s9, s8, s41
	s_max_i32 s9, s9, 0
	s_add_i32 s84, s9, s6
	s_add_i32 s9, s8, s40
	s_max_i32 s9, s9, 0
	s_add_i32 s85, s9, s6
	s_add_i32 s9, s8, s34
	s_max_i32 s9, s9, 0
	s_add_i32 s88, s9, s6
	s_add_i32 s9, s8, s29
	s_max_i32 s9, s9, 0
	s_add_i32 s89, s9, s6
	s_add_i32 s9, s8, s28
	s_add_i32 s8, s8, s5
	s_max_i32 s9, s9, 0
	s_max_i32 s8, s8, 0
	s_add_i32 s94, s9, s6
	s_add_i32 s95, s8, s6
	s_lshl_b32 s6, s42, 7
	s_add_i32 s8, s64, s7
	s_and_b32 s6, s6, 0xffff8000
	s_sub_i32 s10, s8, 56
	s_add_i32 vcc_lo, s6, 0
	s_lshl_b32 s6, s7, 10
	s_ashr_i32 s11, s10, 31
	s_add_i32 s6, s6, 0
	s_lshl_b64 s[10:11], s[10:11], 11
	s_add_u32 s56, s76, s10
	s_addc_u32 s57, s77, s11
	s_sub_i32 s10, s8, 48
	s_ashr_i32 s11, s10, 31
	s_lshl_b64 s[10:11], s[10:11], 11
	s_add_u32 s54, s76, s10
	s_addc_u32 s55, s77, s11
	s_sub_i32 s10, s8, 40
	s_ashr_i32 s11, s10, 31
	s_lshl_b64 s[10:11], s[10:11], 11
	s_add_u32 s52, s76, s10
	s_addc_u32 s53, s77, s11
	s_sub_i32 s10, s8, 32
	s_ashr_i32 s11, s10, 31
	s_lshl_b64 s[10:11], s[10:11], 11
	s_add_u32 s50, s76, s10
	s_addc_u32 s51, s77, s11
	s_sub_i32 s10, s8, 24
	s_ashr_i32 s11, s10, 31
	s_lshl_b64 s[10:11], s[10:11], 11
	s_add_u32 s48, s76, s10
	s_addc_u32 s49, s77, s11
	s_add_i32 s10, s8, -16
	s_ashr_i32 s11, s10, 31
	s_lshl_b64 s[10:11], s[10:11], 11
	s_add_u32 s46, s76, s10
	s_addc_u32 s47, s77, s11
	s_add_i32 s10, s8, -8
	s_ashr_i32 s11, s10, 31
	s_lshl_b64 s[10:11], s[10:11], 11
	s_add_u32 s44, s76, s10
	s_addc_u32 s45, s77, s11
	s_ashr_i32 s9, s8, 31
	s_lshl_b64 s[8:9], s[8:9], 11
	s_add_u32 s42, s76, s8
	v_and_b32_e32 v12, 0xff, v10
	s_addc_u32 s43, s77, s9
	v_mad_i64_i32 v[10:11], s[8:9], s66, v238, v[102:103]
	s_waitcnt lgkmcnt(0)
	s_barrier
	global_load_dwordx2 v[152:153], v[10:11], off offset:1024
	global_load_dwordx2 v[154:155], v[10:11], off offset:1536
	v_mad_i64_i32 v[10:11], s[8:9], s67, v238, v[102:103]
	global_load_dwordx2 v[148:149], v[10:11], off offset:1024
	global_load_dwordx2 v[150:151], v[10:11], off offset:1536
	v_mad_i64_i32 v[10:11], s[8:9], s68, v238, v[102:103]
	global_load_dwordx2 v[144:145], v[10:11], off offset:1024
	global_load_dwordx2 v[146:147], v[10:11], off offset:1536
	v_mad_i64_i32 v[10:11], s[8:9], s69, v238, v[102:103]
	global_load_dwordx2 v[140:141], v[10:11], off offset:1024
	global_load_dwordx2 v[142:143], v[10:11], off offset:1536
	v_mad_i64_i32 v[10:11], s[8:9], s72, v238, v[102:103]
	global_load_dwordx2 v[136:137], v[10:11], off offset:1024
	global_load_dwordx2 v[138:139], v[10:11], off offset:1536
	v_mad_i64_i32 v[10:11], s[8:9], s73, v238, v[102:103]
	global_load_dwordx2 v[132:133], v[10:11], off offset:1024
	global_load_dwordx2 v[134:135], v[10:11], off offset:1536
	v_mad_i64_i32 v[10:11], s[8:9], s84, v238, v[102:103]
	global_load_dwordx2 v[126:127], v[10:11], off offset:1024
	global_load_dwordx2 v[128:129], v[10:11], off offset:1536
	v_mad_i64_i32 v[10:11], s[8:9], s85, v238, v[102:103]
	global_load_dwordx2 v[122:123], v[10:11], off offset:1024
	global_load_dwordx2 v[124:125], v[10:11], off offset:1536
	v_mad_i64_i32 v[10:11], s[8:9], s88, v238, v[102:103]
	global_load_dwordx2 v[118:119], v[10:11], off offset:1024
	global_load_dwordx2 v[120:121], v[10:11], off offset:1536
	v_mad_i64_i32 v[10:11], s[8:9], s89, v238, v[102:103]
	global_load_dwordx2 v[114:115], v[10:11], off offset:1024
	global_load_dwordx2 v[116:117], v[10:11], off offset:1536
	v_mad_i64_i32 v[10:11], s[8:9], s94, v238, v[102:103]
	global_load_dwordx2 v[110:111], v[10:11], off offset:1024
	global_load_dwordx2 v[112:113], v[10:11], off offset:1536
	v_mad_i64_i32 v[10:11], s[8:9], s95, v238, v[102:103]
	v_lshl_add_u32 v163, v12, 2, vcc_lo
	global_load_dwordx2 v[106:107], v[10:11], off offset:1024
	global_load_dwordx2 v[108:109], v[10:11], off offset:1536
	ds_read2st64_b32 v[26:27], v163 offset1:4
	ds_read2st64_b32 v[28:29], v163 offset0:8 offset1:12
	ds_read2st64_b32 v[30:31], v163 offset0:16 offset1:20
	ds_read2st64_b32 v[32:33], v163 offset0:24 offset1:28
	ds_read2st64_b32 v[160:161], v163 offset0:32 offset1:36
	ds_read2st64_b32 v[158:159], v163 offset0:40 offset1:44
	ds_read2st64_b32 v[156:157], v163 offset0:48 offset1:52
	ds_read2st64_b32 v[40:41], v163 offset0:56 offset1:60
	ds_read2st64_b32 v[38:39], v163 offset0:64 offset1:68
	ds_read2st64_b32 v[36:37], v163 offset0:72 offset1:76
	ds_read2st64_b32 v[34:35], v163 offset0:80 offset1:84
	ds_read2st64_b32 v[24:25], v163 offset0:88 offset1:92
	ds_read2st64_b32 v[22:23], v163 offset0:96 offset1:100
	ds_read2st64_b32 v[20:21], v163 offset0:104 offset1:108
	ds_read2st64_b32 v[18:19], v163 offset0:112 offset1:116
	ds_read2st64_b32 v[10:11], v163 offset0:120 offset1:124
	ds_read2st64_b32 v[12:13], v163 offset0:128 offset1:132
	ds_read2st64_b32 v[14:15], v163 offset0:136 offset1:140
	ds_read2st64_b32 v[16:17], v163 offset0:144 offset1:148
	s_waitcnt lgkmcnt(14)
	v_mul_f32_e32 v165, v42, v27
	s_waitcnt vmcnt(51) lgkmcnt(3)
	v_mul_f32_e32 v105, v101, v10
	s_waitcnt vmcnt(24)
	v_mov_b32_e32 v164, v104
	v_pk_fma_f32 v[26:27], v[42:43], v[26:27], v[104:105]
	v_pk_fma_f32 v[164:165], v[44:45], v[28:29], v[164:165]
	v_pk_fma_f32 v[26:27], v[46:47], v[28:29], v[26:27]
	v_pk_fma_f32 v[164:165], v[48:49], v[30:31], v[164:165]
	v_pk_fma_f32 v[26:27], v[50:51], v[30:31], v[26:27]
	v_pk_fma_f32 v[164:165], v[52:53], v[32:33], v[164:165]
	v_pk_fma_f32 v[26:27], v[54:55], v[32:33], v[26:27]
	v_pk_fma_f32 v[164:165], v[56:57], v[160:161], v[164:165]
	v_pk_fma_f32 v[26:27], v[58:59], v[160:161], v[26:27]
	v_pk_fma_f32 v[164:165], v[60:61], v[158:159], v[164:165]
	v_pk_fma_f32 v[26:27], v[62:63], v[158:159], v[26:27]
	v_pk_fma_f32 v[164:165], v[64:65], v[156:157], v[164:165]
	v_pk_fma_f32 v[26:27], v[66:67], v[156:157], v[26:27]
	v_pk_fma_f32 v[164:165], v[68:69], v[40:41], v[164:165]
	v_pk_fma_f32 v[26:27], v[70:71], v[40:41], v[26:27]
	v_pk_fma_f32 v[164:165], v[72:73], v[38:39], v[164:165]
	v_pk_fma_f32 v[26:27], v[74:75], v[38:39], v[26:27]
	v_pk_fma_f32 v[164:165], v[76:77], v[36:37], v[164:165]
	v_pk_fma_f32 v[26:27], v[78:79], v[36:37], v[26:27]
	v_pk_fma_f32 v[164:165], v[80:81], v[34:35], v[164:165]
	v_pk_fma_f32 v[26:27], v[82:83], v[34:35], v[26:27]
	v_pk_fma_f32 v[164:165], v[84:85], v[24:25], v[164:165]
	v_pk_fma_f32 v[26:27], v[86:87], v[24:25], v[26:27]
	v_pk_fma_f32 v[164:165], v[88:89], v[22:23], v[164:165]
	v_pk_fma_f32 v[26:27], v[90:91], v[22:23], v[26:27]
	v_pk_fma_f32 v[164:165], v[92:93], v[20:21], v[164:165]
	v_pk_fma_f32 v[26:27], v[94:95], v[20:21], v[26:27]
	v_pk_fma_f32 v[164:165], v[96:97], v[18:19], v[164:165]
	v_pk_fma_f32 v[26:27], v[98:99], v[18:19], v[26:27]
	v_pk_fma_f32 v[166:167], v[100:101], v[10:11], v[164:165]
	v_add_f32_e32 v164, v26, v27
	v_mul_f32_e32 v27, v42, v29
	v_mov_b32_e32 v26, v104
	v_pk_fma_f32 v[26:27], v[44:45], v[30:31], v[26:27]
	s_waitcnt lgkmcnt(2)
	v_mul_f32_e32 v105, v101, v12
	v_pk_fma_f32 v[26:27], v[48:49], v[32:33], v[26:27]
	v_pk_fma_f32 v[28:29], v[42:43], v[28:29], v[104:105]
	v_pk_fma_f32 v[26:27], v[52:53], v[160:161], v[26:27]
	v_pk_fma_f32 v[28:29], v[46:47], v[30:31], v[28:29]
	v_pk_fma_f32 v[26:27], v[56:57], v[158:159], v[26:27]
	v_pk_fma_f32 v[28:29], v[50:51], v[32:33], v[28:29]
	v_pk_fma_f32 v[26:27], v[60:61], v[156:157], v[26:27]
	v_pk_fma_f32 v[28:29], v[54:55], v[160:161], v[28:29]
	v_pk_fma_f32 v[26:27], v[64:65], v[40:41], v[26:27]
	v_pk_fma_f32 v[28:29], v[58:59], v[158:159], v[28:29]
	v_pk_fma_f32 v[26:27], v[68:69], v[38:39], v[26:27]
	v_pk_fma_f32 v[28:29], v[62:63], v[156:157], v[28:29]
	v_pk_fma_f32 v[26:27], v[72:73], v[36:37], v[26:27]
	v_pk_fma_f32 v[28:29], v[66:67], v[40:41], v[28:29]
	v_pk_fma_f32 v[26:27], v[76:77], v[34:35], v[26:27]
	v_pk_fma_f32 v[28:29], v[70:71], v[38:39], v[28:29]
	v_pk_fma_f32 v[26:27], v[80:81], v[24:25], v[26:27]
	v_pk_fma_f32 v[28:29], v[74:75], v[36:37], v[28:29]
	v_pk_fma_f32 v[26:27], v[84:85], v[22:23], v[26:27]
	v_pk_fma_f32 v[28:29], v[78:79], v[34:35], v[28:29]
	v_pk_fma_f32 v[26:27], v[88:89], v[20:21], v[26:27]
	v_pk_fma_f32 v[28:29], v[82:83], v[24:25], v[28:29]
	v_pk_fma_f32 v[26:27], v[92:93], v[18:19], v[26:27]
	v_pk_fma_f32 v[28:29], v[86:87], v[22:23], v[28:29]
	v_pk_fma_f32 v[26:27], v[96:97], v[10:11], v[26:27]
	v_pk_fma_f32 v[28:29], v[90:91], v[20:21], v[28:29]
	v_pk_fma_f32 v[26:27], v[100:101], v[12:13], v[26:27]
	v_add_f32_e32 v165, v166, v167
	v_pk_fma_f32 v[28:29], v[94:95], v[18:19], v[28:29]
	v_add_f32_e32 v167, v26, v27
	v_mul_f32_e32 v27, v42, v31
	v_mov_b32_e32 v26, v104
	v_pk_fma_f32 v[28:29], v[98:99], v[10:11], v[28:29]
	s_waitcnt lgkmcnt(1)
	v_mul_f32_e32 v105, v101, v14
	v_pk_fma_f32 v[26:27], v[44:45], v[32:33], v[26:27]
	v_add_f32_e32 v166, v28, v29
	v_pk_fma_f32 v[28:29], v[42:43], v[30:31], v[104:105]
	v_pk_fma_f32 v[26:27], v[48:49], v[160:161], v[26:27]
	v_pk_fma_f32 v[28:29], v[46:47], v[32:33], v[28:29]
	v_pk_fma_f32 v[26:27], v[52:53], v[158:159], v[26:27]
	v_pk_fma_f32 v[28:29], v[50:51], v[160:161], v[28:29]
	v_pk_fma_f32 v[26:27], v[56:57], v[156:157], v[26:27]
	v_pk_fma_f32 v[28:29], v[54:55], v[158:159], v[28:29]
	v_pk_fma_f32 v[26:27], v[60:61], v[40:41], v[26:27]
	v_pk_fma_f32 v[28:29], v[58:59], v[156:157], v[28:29]
	v_pk_fma_f32 v[26:27], v[64:65], v[38:39], v[26:27]
	v_pk_fma_f32 v[28:29], v[62:63], v[40:41], v[28:29]
	v_pk_fma_f32 v[26:27], v[68:69], v[36:37], v[26:27]
	v_pk_fma_f32 v[28:29], v[66:67], v[38:39], v[28:29]
	v_pk_fma_f32 v[26:27], v[72:73], v[34:35], v[26:27]
	v_pk_fma_f32 v[28:29], v[70:71], v[36:37], v[28:29]
	v_pk_fma_f32 v[26:27], v[76:77], v[24:25], v[26:27]
	v_pk_fma_f32 v[28:29], v[74:75], v[34:35], v[28:29]
	v_pk_fma_f32 v[26:27], v[80:81], v[22:23], v[26:27]
	v_pk_fma_f32 v[28:29], v[78:79], v[24:25], v[28:29]
	v_pk_fma_f32 v[26:27], v[84:85], v[20:21], v[26:27]
	v_pk_fma_f32 v[28:29], v[82:83], v[22:23], v[28:29]
	v_pk_fma_f32 v[26:27], v[88:89], v[18:19], v[26:27]
	v_pk_fma_f32 v[28:29], v[86:87], v[20:21], v[28:29]
	v_pk_fma_f32 v[26:27], v[92:93], v[10:11], v[26:27]
	v_pk_fma_f32 v[28:29], v[90:91], v[18:19], v[28:29]
	v_pk_fma_f32 v[26:27], v[96:97], v[12:13], v[26:27]
	v_pk_fma_f32 v[28:29], v[94:95], v[10:11], v[28:29]
	v_pk_fma_f32 v[26:27], v[100:101], v[14:15], v[26:27]
	v_pk_fma_f32 v[28:29], v[98:99], v[12:13], v[28:29]
	v_add_f32_e32 v169, v26, v27
	s_waitcnt lgkmcnt(0)
	v_mul_f32_e32 v105, v101, v16
	v_mul_f32_e32 v27, v42, v33
	v_mov_b32_e32 v26, v104
	v_add_f32_e32 v168, v28, v29
	v_pk_fma_f32 v[28:29], v[42:43], v[32:33], v[104:105]
	v_pk_fma_f32 v[26:27], v[44:45], v[160:161], v[26:27]
	v_pk_fma_f32 v[28:29], v[46:47], v[160:161], v[28:29]
	v_pk_fma_f32 v[26:27], v[48:49], v[158:159], v[26:27]
	v_pk_fma_f32 v[28:29], v[50:51], v[158:159], v[28:29]
	v_pk_fma_f32 v[26:27], v[52:53], v[156:157], v[26:27]
	v_pk_fma_f32 v[28:29], v[54:55], v[156:157], v[28:29]
	v_pk_fma_f32 v[26:27], v[56:57], v[40:41], v[26:27]
	v_pk_fma_f32 v[28:29], v[58:59], v[40:41], v[28:29]
	v_pk_fma_f32 v[26:27], v[60:61], v[38:39], v[26:27]
	v_pk_fma_f32 v[28:29], v[62:63], v[38:39], v[28:29]
	v_pk_fma_f32 v[26:27], v[64:65], v[36:37], v[26:27]
	v_pk_fma_f32 v[28:29], v[66:67], v[36:37], v[28:29]
	v_pk_fma_f32 v[26:27], v[68:69], v[34:35], v[26:27]
	v_pk_fma_f32 v[28:29], v[70:71], v[34:35], v[28:29]
	v_pk_fma_f32 v[26:27], v[72:73], v[24:25], v[26:27]
	v_pk_fma_f32 v[28:29], v[74:75], v[24:25], v[28:29]
	v_pk_fma_f32 v[26:27], v[76:77], v[22:23], v[26:27]
	v_pk_fma_f32 v[28:29], v[78:79], v[22:23], v[28:29]
	v_pk_fma_f32 v[26:27], v[80:81], v[20:21], v[26:27]
	v_pk_fma_f32 v[28:29], v[82:83], v[20:21], v[28:29]
	v_pk_fma_f32 v[26:27], v[84:85], v[18:19], v[26:27]
	v_pk_fma_f32 v[28:29], v[86:87], v[18:19], v[28:29]
	v_pk_fma_f32 v[26:27], v[88:89], v[10:11], v[26:27]
	v_pk_fma_f32 v[28:29], v[90:91], v[10:11], v[28:29]
	v_pk_fma_f32 v[26:27], v[92:93], v[12:13], v[26:27]
	v_pk_fma_f32 v[28:29], v[94:95], v[12:13], v[28:29]
	v_pk_fma_f32 v[26:27], v[96:97], v[14:15], v[26:27]
	v_pk_fma_f32 v[28:29], v[98:99], v[14:15], v[28:29]
	v_pk_fma_f32 v[26:27], v[100:101], v[16:17], v[26:27]
	v_add_f32_e32 v170, v28, v29
	v_add_f32_e32 v171, v26, v27
	ds_read2st64_b32 v[26:27], v163 offset0:152 offset1:156
	ds_read2st64_b32 v[28:29], v163 offset0:160 offset1:164
	ds_read2st64_b32 v[30:31], v163 offset0:168 offset1:172
	ds_read2st64_b32 v[32:33], v163 offset0:176 offset1:180
	v_mul_f32_e32 v173, v42, v161
	s_waitcnt lgkmcnt(3)
	v_mul_f32_e32 v105, v101, v26
	v_pk_fma_f32 v[160:161], v[42:43], v[160:161], v[104:105]
	v_mov_b32_e32 v172, v104
	v_pk_fma_f32 v[160:161], v[46:47], v[158:159], v[160:161]
	s_waitcnt lgkmcnt(2)
	v_mul_f32_e32 v105, v101, v28
	v_pk_fma_f32 v[160:161], v[50:51], v[156:157], v[160:161]
	v_pk_fma_f32 v[172:173], v[44:45], v[158:159], v[172:173]
	v_pk_fma_f32 v[160:161], v[54:55], v[40:41], v[160:161]
	v_pk_fma_f32 v[172:173], v[48:49], v[156:157], v[172:173]
	v_pk_fma_f32 v[160:161], v[58:59], v[38:39], v[160:161]
	v_pk_fma_f32 v[172:173], v[52:53], v[40:41], v[172:173]
	v_pk_fma_f32 v[160:161], v[62:63], v[36:37], v[160:161]
	v_pk_fma_f32 v[172:173], v[56:57], v[38:39], v[172:173]
	v_pk_fma_f32 v[160:161], v[66:67], v[34:35], v[160:161]
	v_pk_fma_f32 v[172:173], v[60:61], v[36:37], v[172:173]
	v_pk_fma_f32 v[160:161], v[70:71], v[24:25], v[160:161]
	v_pk_fma_f32 v[172:173], v[64:65], v[34:35], v[172:173]
	v_pk_fma_f32 v[160:161], v[74:75], v[22:23], v[160:161]
	v_pk_fma_f32 v[172:173], v[68:69], v[24:25], v[172:173]
	v_pk_fma_f32 v[160:161], v[78:79], v[20:21], v[160:161]
	v_pk_fma_f32 v[172:173], v[72:73], v[22:23], v[172:173]
	v_pk_fma_f32 v[160:161], v[82:83], v[18:19], v[160:161]
	v_pk_fma_f32 v[172:173], v[76:77], v[20:21], v[172:173]
	v_pk_fma_f32 v[160:161], v[86:87], v[10:11], v[160:161]
	v_pk_fma_f32 v[172:173], v[80:81], v[18:19], v[172:173]
	v_pk_fma_f32 v[160:161], v[90:91], v[12:13], v[160:161]
	v_pk_fma_f32 v[172:173], v[84:85], v[10:11], v[172:173]
	v_pk_fma_f32 v[160:161], v[94:95], v[14:15], v[160:161]
	v_pk_fma_f32 v[172:173], v[88:89], v[12:13], v[172:173]
	v_pk_fma_f32 v[160:161], v[98:99], v[16:17], v[160:161]
	v_pk_fma_f32 v[172:173], v[92:93], v[14:15], v[172:173]
	v_add_f32_e32 v174, v160, v161
	v_mul_f32_e32 v161, v42, v159
	v_pk_fma_f32 v[158:159], v[42:43], v[158:159], v[104:105]
	v_mov_b32_e32 v160, v104
	v_pk_fma_f32 v[158:159], v[46:47], v[156:157], v[158:159]
	s_waitcnt lgkmcnt(1)
	v_mul_f32_e32 v105, v101, v30
	v_pk_fma_f32 v[158:159], v[50:51], v[40:41], v[158:159]
	v_pk_fma_f32 v[160:161], v[44:45], v[156:157], v[160:161]
	v_pk_fma_f32 v[158:159], v[54:55], v[38:39], v[158:159]
	v_pk_fma_f32 v[160:161], v[48:49], v[40:41], v[160:161]
	v_pk_fma_f32 v[158:159], v[58:59], v[36:37], v[158:159]
	v_pk_fma_f32 v[160:161], v[52:53], v[38:39], v[160:161]
	v_pk_fma_f32 v[158:159], v[62:63], v[34:35], v[158:159]
	v_pk_fma_f32 v[160:161], v[56:57], v[36:37], v[160:161]
	v_pk_fma_f32 v[158:159], v[66:67], v[24:25], v[158:159]
	v_pk_fma_f32 v[160:161], v[60:61], v[34:35], v[160:161]
	v_pk_fma_f32 v[158:159], v[70:71], v[22:23], v[158:159]
	v_pk_fma_f32 v[160:161], v[64:65], v[24:25], v[160:161]
	v_pk_fma_f32 v[158:159], v[74:75], v[20:21], v[158:159]
	v_pk_fma_f32 v[160:161], v[68:69], v[22:23], v[160:161]
	v_pk_fma_f32 v[158:159], v[78:79], v[18:19], v[158:159]
	v_pk_fma_f32 v[160:161], v[72:73], v[20:21], v[160:161]
	v_pk_fma_f32 v[158:159], v[82:83], v[10:11], v[158:159]
	v_pk_fma_f32 v[160:161], v[76:77], v[18:19], v[160:161]
	v_pk_fma_f32 v[158:159], v[86:87], v[12:13], v[158:159]
	v_pk_fma_f32 v[160:161], v[80:81], v[10:11], v[160:161]
	v_pk_fma_f32 v[158:159], v[90:91], v[14:15], v[158:159]
	v_pk_fma_f32 v[160:161], v[84:85], v[12:13], v[160:161]
	v_pk_fma_f32 v[158:159], v[94:95], v[16:17], v[158:159]
	v_pk_fma_f32 v[160:161], v[88:89], v[14:15], v[160:161]
	v_pk_fma_f32 v[158:159], v[98:99], v[26:27], v[158:159]
	v_pk_fma_f32 v[160:161], v[92:93], v[16:17], v[160:161]
	v_add_f32_e32 v176, v158, v159
	v_mul_f32_e32 v159, v42, v157
	v_pk_fma_f32 v[156:157], v[42:43], v[156:157], v[104:105]
	v_mov_b32_e32 v158, v104
	v_pk_fma_f32 v[156:157], v[46:47], v[40:41], v[156:157]
	s_waitcnt lgkmcnt(0)
	v_mul_f32_e32 v105, v101, v32
	v_pk_fma_f32 v[156:157], v[50:51], v[38:39], v[156:157]
	v_pk_fma_f32 v[158:159], v[44:45], v[40:41], v[158:159]
	v_pk_fma_f32 v[156:157], v[54:55], v[36:37], v[156:157]
	v_pk_fma_f32 v[158:159], v[48:49], v[38:39], v[158:159]
	v_pk_fma_f32 v[156:157], v[58:59], v[34:35], v[156:157]
	v_pk_fma_f32 v[158:159], v[52:53], v[36:37], v[158:159]
	v_pk_fma_f32 v[156:157], v[62:63], v[24:25], v[156:157]
	v_pk_fma_f32 v[158:159], v[56:57], v[34:35], v[158:159]
	v_pk_fma_f32 v[156:157], v[66:67], v[22:23], v[156:157]
	v_pk_fma_f32 v[158:159], v[60:61], v[24:25], v[158:159]
	v_pk_fma_f32 v[156:157], v[70:71], v[20:21], v[156:157]
	v_pk_fma_f32 v[158:159], v[64:65], v[22:23], v[158:159]
	v_pk_fma_f32 v[156:157], v[74:75], v[18:19], v[156:157]
	v_pk_fma_f32 v[158:159], v[68:69], v[20:21], v[158:159]
	v_pk_fma_f32 v[156:157], v[78:79], v[10:11], v[156:157]
	v_pk_fma_f32 v[158:159], v[72:73], v[18:19], v[158:159]
	v_pk_fma_f32 v[156:157], v[82:83], v[12:13], v[156:157]
	v_pk_fma_f32 v[158:159], v[76:77], v[10:11], v[158:159]
	v_pk_fma_f32 v[156:157], v[86:87], v[14:15], v[156:157]
	v_pk_fma_f32 v[158:159], v[80:81], v[12:13], v[158:159]
	v_pk_fma_f32 v[156:157], v[90:91], v[16:17], v[156:157]
	v_pk_fma_f32 v[158:159], v[84:85], v[14:15], v[158:159]
	v_pk_fma_f32 v[156:157], v[94:95], v[26:27], v[156:157]
	v_pk_fma_f32 v[158:159], v[88:89], v[16:17], v[158:159]
	v_pk_fma_f32 v[156:157], v[98:99], v[28:29], v[156:157]
	v_pk_fma_f32 v[158:159], v[92:93], v[26:27], v[158:159]
	v_add_f32_e32 v178, v156, v157
	v_mul_f32_e32 v157, v42, v41
	v_mov_b32_e32 v156, v104
	v_pk_fma_f32 v[40:41], v[42:43], v[40:41], v[104:105]
	v_pk_fma_f32 v[156:157], v[44:45], v[38:39], v[156:157]
	v_pk_fma_f32 v[40:41], v[46:47], v[38:39], v[40:41]
	v_pk_fma_f32 v[156:157], v[48:49], v[36:37], v[156:157]
	v_pk_fma_f32 v[40:41], v[50:51], v[36:37], v[40:41]
	v_pk_fma_f32 v[156:157], v[52:53], v[34:35], v[156:157]
	v_pk_fma_f32 v[40:41], v[54:55], v[34:35], v[40:41]
	v_pk_fma_f32 v[156:157], v[56:57], v[24:25], v[156:157]
	v_pk_fma_f32 v[40:41], v[58:59], v[24:25], v[40:41]
	v_pk_fma_f32 v[156:157], v[60:61], v[22:23], v[156:157]
	v_pk_fma_f32 v[40:41], v[62:63], v[22:23], v[40:41]
	v_pk_fma_f32 v[156:157], v[64:65], v[20:21], v[156:157]
	v_pk_fma_f32 v[40:41], v[66:67], v[20:21], v[40:41]
	v_pk_fma_f32 v[156:157], v[68:69], v[18:19], v[156:157]
	v_pk_fma_f32 v[40:41], v[70:71], v[18:19], v[40:41]
	v_pk_fma_f32 v[156:157], v[72:73], v[10:11], v[156:157]
	v_pk_fma_f32 v[40:41], v[74:75], v[10:11], v[40:41]
	v_pk_fma_f32 v[156:157], v[76:77], v[12:13], v[156:157]
	v_pk_fma_f32 v[40:41], v[78:79], v[12:13], v[40:41]
	v_pk_fma_f32 v[156:157], v[80:81], v[14:15], v[156:157]
	v_pk_fma_f32 v[40:41], v[82:83], v[14:15], v[40:41]
	v_pk_fma_f32 v[156:157], v[84:85], v[16:17], v[156:157]
	v_pk_fma_f32 v[40:41], v[86:87], v[16:17], v[40:41]
	v_pk_fma_f32 v[156:157], v[88:89], v[26:27], v[156:157]
	v_pk_fma_f32 v[40:41], v[90:91], v[26:27], v[40:41]
	v_pk_fma_f32 v[156:157], v[92:93], v[28:29], v[156:157]
	v_pk_fma_f32 v[160:161], v[96:97], v[26:27], v[160:161]
	v_pk_fma_f32 v[158:159], v[96:97], v[28:29], v[158:159]
	v_pk_fma_f32 v[40:41], v[94:95], v[28:29], v[40:41]
	v_pk_fma_f32 v[156:157], v[96:97], v[30:31], v[156:157]
	v_pk_fma_f32 v[160:161], v[100:101], v[28:29], v[160:161]
	v_pk_fma_f32 v[158:159], v[100:101], v[30:31], v[158:159]
	v_pk_fma_f32 v[40:41], v[98:99], v[30:31], v[40:41]
	v_pk_fma_f32 v[156:157], v[100:101], v[32:33], v[156:157]
	v_add_f32_e32 v177, v160, v161
	v_add_f32_e32 v179, v158, v159
	v_add_f32_e32 v180, v40, v41
	v_add_f32_e32 v181, v156, v157
	ds_read2st64_b32 v[40:41], v163 offset0:184 offset1:188
	ds_read2st64_b32 v[156:157], v163 offset0:192 offset1:196
	ds_read2st64_b32 v[158:159], v163 offset0:200 offset1:204
	ds_read2st64_b32 v[160:161], v163 offset0:208 offset1:212
	v_pk_fma_f32 v[172:173], v[96:97], v[16:17], v[172:173]
	s_waitcnt lgkmcnt(3)
	v_mul_f32_e32 v105, v101, v40
	v_pk_fma_f32 v[172:173], v[100:101], v[26:27], v[172:173]
	s_addk_i32 s64, 0x800
	v_add_f32_e32 v175, v172, v173
	v_mul_f32_e32 v173, v42, v39
	v_pk_fma_f32 v[38:39], v[42:43], v[38:39], v[104:105]
	v_mov_b32_e32 v172, v104
	v_pk_fma_f32 v[38:39], v[46:47], v[36:37], v[38:39]
	s_waitcnt lgkmcnt(2)
	v_mul_f32_e32 v105, v101, v156
	v_pk_fma_f32 v[38:39], v[50:51], v[34:35], v[38:39]
	v_pk_fma_f32 v[172:173], v[44:45], v[36:37], v[172:173]
	v_pk_fma_f32 v[38:39], v[54:55], v[24:25], v[38:39]
	v_pk_fma_f32 v[172:173], v[48:49], v[34:35], v[172:173]
	v_pk_fma_f32 v[38:39], v[58:59], v[22:23], v[38:39]
	v_pk_fma_f32 v[172:173], v[52:53], v[24:25], v[172:173]
	v_pk_fma_f32 v[38:39], v[62:63], v[20:21], v[38:39]
	v_pk_fma_f32 v[172:173], v[56:57], v[22:23], v[172:173]
	v_pk_fma_f32 v[38:39], v[66:67], v[18:19], v[38:39]
	v_pk_fma_f32 v[172:173], v[60:61], v[20:21], v[172:173]
	v_pk_fma_f32 v[38:39], v[70:71], v[10:11], v[38:39]
	v_pk_fma_f32 v[172:173], v[64:65], v[18:19], v[172:173]
	v_pk_fma_f32 v[38:39], v[74:75], v[12:13], v[38:39]
	v_pk_fma_f32 v[172:173], v[68:69], v[10:11], v[172:173]
	v_pk_fma_f32 v[38:39], v[78:79], v[14:15], v[38:39]
	v_pk_fma_f32 v[172:173], v[72:73], v[12:13], v[172:173]
	v_pk_fma_f32 v[38:39], v[82:83], v[16:17], v[38:39]
	v_pk_fma_f32 v[172:173], v[76:77], v[14:15], v[172:173]
	v_pk_fma_f32 v[38:39], v[86:87], v[26:27], v[38:39]
	v_pk_fma_f32 v[172:173], v[80:81], v[16:17], v[172:173]
	v_pk_fma_f32 v[38:39], v[90:91], v[28:29], v[38:39]
	v_pk_fma_f32 v[172:173], v[84:85], v[26:27], v[172:173]
	v_pk_fma_f32 v[38:39], v[94:95], v[30:31], v[38:39]
	v_pk_fma_f32 v[172:173], v[88:89], v[28:29], v[172:173]
	v_pk_fma_f32 v[38:39], v[98:99], v[32:33], v[38:39]
	v_pk_fma_f32 v[172:173], v[92:93], v[30:31], v[172:173]
	v_add_f32_e32 v182, v38, v39
	v_mul_f32_e32 v39, v42, v37
	v_pk_fma_f32 v[36:37], v[42:43], v[36:37], v[104:105]
	v_mov_b32_e32 v38, v104
	v_pk_fma_f32 v[36:37], v[46:47], v[34:35], v[36:37]
	s_waitcnt lgkmcnt(1)
	v_mul_f32_e32 v105, v101, v158
	v_pk_fma_f32 v[36:37], v[50:51], v[24:25], v[36:37]
	v_pk_fma_f32 v[38:39], v[44:45], v[34:35], v[38:39]
	v_pk_fma_f32 v[36:37], v[54:55], v[22:23], v[36:37]
	v_pk_fma_f32 v[38:39], v[48:49], v[24:25], v[38:39]
	v_pk_fma_f32 v[36:37], v[58:59], v[20:21], v[36:37]
	v_pk_fma_f32 v[38:39], v[52:53], v[22:23], v[38:39]
	v_pk_fma_f32 v[36:37], v[62:63], v[18:19], v[36:37]
	v_pk_fma_f32 v[38:39], v[56:57], v[20:21], v[38:39]
	v_pk_fma_f32 v[36:37], v[66:67], v[10:11], v[36:37]
	v_pk_fma_f32 v[38:39], v[60:61], v[18:19], v[38:39]
	v_pk_fma_f32 v[36:37], v[70:71], v[12:13], v[36:37]
	v_pk_fma_f32 v[38:39], v[64:65], v[10:11], v[38:39]
	v_pk_fma_f32 v[36:37], v[74:75], v[14:15], v[36:37]
	v_pk_fma_f32 v[38:39], v[68:69], v[12:13], v[38:39]
	v_pk_fma_f32 v[36:37], v[78:79], v[16:17], v[36:37]
	v_pk_fma_f32 v[38:39], v[72:73], v[14:15], v[38:39]
	v_pk_fma_f32 v[36:37], v[82:83], v[26:27], v[36:37]
	v_pk_fma_f32 v[38:39], v[76:77], v[16:17], v[38:39]
	v_pk_fma_f32 v[36:37], v[86:87], v[28:29], v[36:37]
	v_pk_fma_f32 v[38:39], v[80:81], v[26:27], v[38:39]
	v_pk_fma_f32 v[36:37], v[90:91], v[30:31], v[36:37]
	v_pk_fma_f32 v[38:39], v[84:85], v[28:29], v[38:39]
	v_pk_fma_f32 v[36:37], v[94:95], v[32:33], v[36:37]
	v_pk_fma_f32 v[38:39], v[88:89], v[30:31], v[38:39]
	v_pk_fma_f32 v[36:37], v[98:99], v[40:41], v[36:37]
	v_pk_fma_f32 v[38:39], v[92:93], v[32:33], v[38:39]
	v_add_f32_e32 v184, v36, v37
	v_mul_f32_e32 v37, v42, v35
	v_pk_fma_f32 v[34:35], v[42:43], v[34:35], v[104:105]
	v_mov_b32_e32 v36, v104
	v_pk_fma_f32 v[34:35], v[46:47], v[24:25], v[34:35]
	s_waitcnt lgkmcnt(0)
	v_mul_f32_e32 v105, v101, v160
	v_pk_fma_f32 v[34:35], v[50:51], v[22:23], v[34:35]
	v_pk_fma_f32 v[36:37], v[44:45], v[24:25], v[36:37]
	v_pk_fma_f32 v[34:35], v[54:55], v[20:21], v[34:35]
	v_pk_fma_f32 v[36:37], v[48:49], v[22:23], v[36:37]
	v_pk_fma_f32 v[34:35], v[58:59], v[18:19], v[34:35]
	v_pk_fma_f32 v[36:37], v[52:53], v[20:21], v[36:37]
	v_pk_fma_f32 v[34:35], v[62:63], v[10:11], v[34:35]
	v_pk_fma_f32 v[36:37], v[56:57], v[18:19], v[36:37]
	v_pk_fma_f32 v[34:35], v[66:67], v[12:13], v[34:35]
	v_pk_fma_f32 v[36:37], v[60:61], v[10:11], v[36:37]
	v_pk_fma_f32 v[34:35], v[70:71], v[14:15], v[34:35]
	v_pk_fma_f32 v[36:37], v[64:65], v[12:13], v[36:37]
	v_pk_fma_f32 v[34:35], v[74:75], v[16:17], v[34:35]
	v_pk_fma_f32 v[36:37], v[68:69], v[14:15], v[36:37]
	v_pk_fma_f32 v[34:35], v[78:79], v[26:27], v[34:35]
	v_pk_fma_f32 v[36:37], v[72:73], v[16:17], v[36:37]
	v_pk_fma_f32 v[34:35], v[82:83], v[28:29], v[34:35]
	v_pk_fma_f32 v[36:37], v[76:77], v[26:27], v[36:37]
	v_pk_fma_f32 v[34:35], v[86:87], v[30:31], v[34:35]
	v_pk_fma_f32 v[36:37], v[80:81], v[28:29], v[36:37]
	v_pk_fma_f32 v[34:35], v[90:91], v[32:33], v[34:35]
	v_pk_fma_f32 v[36:37], v[84:85], v[30:31], v[36:37]
	v_pk_fma_f32 v[34:35], v[94:95], v[40:41], v[34:35]
	v_pk_fma_f32 v[36:37], v[88:89], v[32:33], v[36:37]
	v_pk_fma_f32 v[34:35], v[98:99], v[156:157], v[34:35]
	v_pk_fma_f32 v[36:37], v[92:93], v[40:41], v[36:37]
	v_add_f32_e32 v186, v34, v35
	v_mul_f32_e32 v35, v42, v25
	v_mov_b32_e32 v34, v104
	v_pk_fma_f32 v[24:25], v[42:43], v[24:25], v[104:105]
	v_pk_fma_f32 v[34:35], v[44:45], v[22:23], v[34:35]
	v_pk_fma_f32 v[24:25], v[46:47], v[22:23], v[24:25]
	v_pk_fma_f32 v[34:35], v[48:49], v[20:21], v[34:35]
	v_pk_fma_f32 v[24:25], v[50:51], v[20:21], v[24:25]
	v_pk_fma_f32 v[34:35], v[52:53], v[18:19], v[34:35]
	v_pk_fma_f32 v[24:25], v[54:55], v[18:19], v[24:25]
	v_pk_fma_f32 v[34:35], v[56:57], v[10:11], v[34:35]
	v_pk_fma_f32 v[24:25], v[58:59], v[10:11], v[24:25]
	v_pk_fma_f32 v[34:35], v[60:61], v[12:13], v[34:35]
	v_pk_fma_f32 v[24:25], v[62:63], v[12:13], v[24:25]
	v_pk_fma_f32 v[34:35], v[64:65], v[14:15], v[34:35]
	v_pk_fma_f32 v[24:25], v[66:67], v[14:15], v[24:25]
	v_pk_fma_f32 v[34:35], v[68:69], v[16:17], v[34:35]
	v_pk_fma_f32 v[24:25], v[70:71], v[16:17], v[24:25]
	v_pk_fma_f32 v[34:35], v[72:73], v[26:27], v[34:35]
	v_pk_fma_f32 v[24:25], v[74:75], v[26:27], v[24:25]
	v_pk_fma_f32 v[34:35], v[76:77], v[28:29], v[34:35]
	v_pk_fma_f32 v[24:25], v[78:79], v[28:29], v[24:25]
	v_pk_fma_f32 v[34:35], v[80:81], v[30:31], v[34:35]
	v_pk_fma_f32 v[24:25], v[82:83], v[30:31], v[24:25]
	v_pk_fma_f32 v[34:35], v[84:85], v[32:33], v[34:35]
	v_pk_fma_f32 v[24:25], v[86:87], v[32:33], v[24:25]
	v_pk_fma_f32 v[34:35], v[88:89], v[40:41], v[34:35]
	v_pk_fma_f32 v[24:25], v[90:91], v[40:41], v[24:25]
	v_pk_fma_f32 v[34:35], v[92:93], v[156:157], v[34:35]
	v_pk_fma_f32 v[38:39], v[96:97], v[40:41], v[38:39]
	v_pk_fma_f32 v[36:37], v[96:97], v[156:157], v[36:37]
	v_pk_fma_f32 v[24:25], v[94:95], v[156:157], v[24:25]
	v_pk_fma_f32 v[34:35], v[96:97], v[158:159], v[34:35]
	v_pk_fma_f32 v[38:39], v[100:101], v[156:157], v[38:39]
	v_pk_fma_f32 v[36:37], v[100:101], v[158:159], v[36:37]
	v_pk_fma_f32 v[24:25], v[98:99], v[158:159], v[24:25]
	v_pk_fma_f32 v[34:35], v[100:101], v[160:161], v[34:35]
	v_add_f32_e32 v185, v38, v39
	v_add_f32_e32 v187, v36, v37
	v_add_f32_e32 v188, v24, v25
	v_add_f32_e32 v189, v34, v35
	ds_read2st64_b32 v[24:25], v163 offset0:216 offset1:220
	ds_read2st64_b32 v[34:35], v163 offset0:224 offset1:228
	ds_read2st64_b32 v[36:37], v163 offset0:232 offset1:236
	ds_read2st64_b32 v[38:39], v163 offset0:240 offset1:244
	v_pk_fma_f32 v[172:173], v[96:97], v[32:33], v[172:173]
	s_waitcnt lgkmcnt(3)
	v_mul_f32_e32 v105, v101, v24
	v_pk_fma_f32 v[172:173], v[100:101], v[40:41], v[172:173]
	s_waitcnt lgkmcnt(0)
	v_add_f32_e32 v183, v172, v173
	v_mul_f32_e32 v173, v42, v23
	v_pk_fma_f32 v[22:23], v[42:43], v[22:23], v[104:105]
	v_mov_b32_e32 v172, v104
	v_pk_fma_f32 v[22:23], v[46:47], v[20:21], v[22:23]
	v_mul_f32_e32 v105, v101, v34
	v_pk_fma_f32 v[22:23], v[50:51], v[18:19], v[22:23]
	v_pk_fma_f32 v[172:173], v[44:45], v[20:21], v[172:173]
	v_pk_fma_f32 v[22:23], v[54:55], v[10:11], v[22:23]
	v_pk_fma_f32 v[172:173], v[48:49], v[18:19], v[172:173]
	v_pk_fma_f32 v[22:23], v[58:59], v[12:13], v[22:23]
	v_pk_fma_f32 v[172:173], v[52:53], v[10:11], v[172:173]
	v_pk_fma_f32 v[22:23], v[62:63], v[14:15], v[22:23]
	v_pk_fma_f32 v[172:173], v[56:57], v[12:13], v[172:173]
	v_pk_fma_f32 v[22:23], v[66:67], v[16:17], v[22:23]
	v_pk_fma_f32 v[172:173], v[60:61], v[14:15], v[172:173]
	v_pk_fma_f32 v[22:23], v[70:71], v[26:27], v[22:23]
	v_pk_fma_f32 v[172:173], v[64:65], v[16:17], v[172:173]
	v_pk_fma_f32 v[22:23], v[74:75], v[28:29], v[22:23]
	v_pk_fma_f32 v[172:173], v[68:69], v[26:27], v[172:173]
	v_pk_fma_f32 v[22:23], v[78:79], v[30:31], v[22:23]
	v_pk_fma_f32 v[172:173], v[72:73], v[28:29], v[172:173]
	v_pk_fma_f32 v[22:23], v[82:83], v[32:33], v[22:23]
	v_pk_fma_f32 v[172:173], v[76:77], v[30:31], v[172:173]
	v_pk_fma_f32 v[22:23], v[86:87], v[40:41], v[22:23]
	v_pk_fma_f32 v[172:173], v[80:81], v[32:33], v[172:173]
	v_pk_fma_f32 v[22:23], v[90:91], v[156:157], v[22:23]
	v_pk_fma_f32 v[172:173], v[84:85], v[40:41], v[172:173]
	v_pk_fma_f32 v[22:23], v[94:95], v[158:159], v[22:23]
	v_pk_fma_f32 v[172:173], v[88:89], v[156:157], v[172:173]
	v_pk_fma_f32 v[22:23], v[98:99], v[160:161], v[22:23]
	v_pk_fma_f32 v[172:173], v[92:93], v[158:159], v[172:173]
	v_add_f32_e32 v190, v22, v23
	v_mul_f32_e32 v23, v42, v21
	v_pk_fma_f32 v[20:21], v[42:43], v[20:21], v[104:105]
	v_pk_fma_f32 v[172:173], v[96:97], v[160:161], v[172:173]
	v_pk_fma_f32 v[20:21], v[46:47], v[18:19], v[20:21]
	v_pk_fma_f32 v[172:173], v[100:101], v[24:25], v[172:173]
	v_pk_fma_f32 v[20:21], v[50:51], v[10:11], v[20:21]
	v_mov_b32_e32 v22, v104
	v_pk_fma_f32 v[20:21], v[54:55], v[12:13], v[20:21]
	v_mul_f32_e32 v105, v101, v36
	v_pk_fma_f32 v[20:21], v[58:59], v[14:15], v[20:21]
	v_add_f32_e32 v172, v172, v173
	v_pk_fma_f32 v[20:21], v[62:63], v[16:17], v[20:21]
	v_pk_fma_f32 v[22:23], v[44:45], v[18:19], v[22:23]
	v_pk_fma_f32 v[20:21], v[66:67], v[26:27], v[20:21]
	v_pk_fma_f32 v[22:23], v[48:49], v[10:11], v[22:23]
	v_pk_fma_f32 v[20:21], v[70:71], v[28:29], v[20:21]
	v_pk_fma_f32 v[22:23], v[52:53], v[12:13], v[22:23]
	v_pk_fma_f32 v[20:21], v[74:75], v[30:31], v[20:21]
	v_pk_fma_f32 v[22:23], v[56:57], v[14:15], v[22:23]
	v_pk_fma_f32 v[20:21], v[78:79], v[32:33], v[20:21]
	v_pk_fma_f32 v[22:23], v[60:61], v[16:17], v[22:23]
	v_pk_fma_f32 v[20:21], v[82:83], v[40:41], v[20:21]
	v_pk_fma_f32 v[22:23], v[64:65], v[26:27], v[22:23]
	v_pk_fma_f32 v[20:21], v[86:87], v[156:157], v[20:21]
	v_pk_fma_f32 v[22:23], v[68:69], v[28:29], v[22:23]
	v_pk_fma_f32 v[20:21], v[90:91], v[158:159], v[20:21]
	v_pk_fma_f32 v[22:23], v[72:73], v[30:31], v[22:23]
	v_pk_fma_f32 v[20:21], v[94:95], v[160:161], v[20:21]
	v_pk_fma_f32 v[22:23], v[76:77], v[32:33], v[22:23]
	v_pk_fma_f32 v[20:21], v[98:99], v[24:25], v[20:21]
	v_pk_fma_f32 v[22:23], v[80:81], v[40:41], v[22:23]
	v_add_f32_e32 v173, v20, v21
	v_mul_f32_e32 v21, v42, v19
	v_pk_fma_f32 v[18:19], v[42:43], v[18:19], v[104:105]
	v_pk_fma_f32 v[22:23], v[84:85], v[156:157], v[22:23]
	v_pk_fma_f32 v[18:19], v[46:47], v[10:11], v[18:19]
	v_pk_fma_f32 v[22:23], v[88:89], v[158:159], v[22:23]
	v_pk_fma_f32 v[18:19], v[50:51], v[12:13], v[18:19]
	v_pk_fma_f32 v[22:23], v[92:93], v[160:161], v[22:23]
	v_pk_fma_f32 v[18:19], v[54:55], v[14:15], v[18:19]
	v_pk_fma_f32 v[22:23], v[96:97], v[24:25], v[22:23]
	v_pk_fma_f32 v[18:19], v[58:59], v[16:17], v[18:19]
	v_pk_fma_f32 v[22:23], v[100:101], v[34:35], v[22:23]
	v_pk_fma_f32 v[18:19], v[62:63], v[26:27], v[18:19]
	v_add_f32_e32 v22, v22, v23
	v_pk_fma_f32 v[18:19], v[66:67], v[28:29], v[18:19]
	v_mov_b32_e32 v20, v104
	v_pk_fma_f32 v[18:19], v[70:71], v[30:31], v[18:19]
	v_mul_f32_e32 v105, v101, v38
	v_pk_fma_f32 v[18:19], v[74:75], v[32:33], v[18:19]
	v_pk_fma_f32 v[20:21], v[44:45], v[10:11], v[20:21]
	v_pk_fma_f32 v[18:19], v[78:79], v[40:41], v[18:19]
	v_pk_fma_f32 v[20:21], v[48:49], v[12:13], v[20:21]
	v_pk_fma_f32 v[18:19], v[82:83], v[156:157], v[18:19]
	v_pk_fma_f32 v[20:21], v[52:53], v[14:15], v[20:21]
	v_pk_fma_f32 v[18:19], v[86:87], v[158:159], v[18:19]
	v_pk_fma_f32 v[20:21], v[56:57], v[16:17], v[20:21]
	v_pk_fma_f32 v[18:19], v[90:91], v[160:161], v[18:19]
	v_pk_fma_f32 v[20:21], v[60:61], v[26:27], v[20:21]
	v_pk_fma_f32 v[18:19], v[94:95], v[24:25], v[18:19]
	v_pk_fma_f32 v[20:21], v[64:65], v[28:29], v[20:21]
	v_pk_fma_f32 v[18:19], v[98:99], v[34:35], v[18:19]
	v_pk_fma_f32 v[20:21], v[68:69], v[30:31], v[20:21]
	v_add_f32_e32 v23, v18, v19
	v_mul_f32_e32 v19, v42, v11
	v_mov_b32_e32 v18, v104
	v_pk_fma_f32 v[10:11], v[42:43], v[10:11], v[104:105]
	v_pk_fma_f32 v[18:19], v[44:45], v[12:13], v[18:19]
	v_pk_fma_f32 v[10:11], v[46:47], v[12:13], v[10:11]
	v_pk_fma_f32 v[12:13], v[48:49], v[14:15], v[18:19]
	v_pk_fma_f32 v[10:11], v[50:51], v[14:15], v[10:11]
	v_pk_fma_f32 v[12:13], v[52:53], v[16:17], v[12:13]
	v_pk_fma_f32 v[10:11], v[54:55], v[16:17], v[10:11]
	v_pk_fma_f32 v[12:13], v[56:57], v[26:27], v[12:13]
	v_pk_fma_f32 v[10:11], v[58:59], v[26:27], v[10:11]
	v_pk_fma_f32 v[12:13], v[60:61], v[28:29], v[12:13]
	v_pk_fma_f32 v[10:11], v[62:63], v[28:29], v[10:11]
	v_pk_fma_f32 v[12:13], v[64:65], v[30:31], v[12:13]
	v_pk_fma_f32 v[10:11], v[66:67], v[30:31], v[10:11]
	v_pk_fma_f32 v[12:13], v[68:69], v[32:33], v[12:13]
	v_pk_fma_f32 v[20:21], v[72:73], v[32:33], v[20:21]
	v_pk_fma_f32 v[10:11], v[70:71], v[32:33], v[10:11]
	v_pk_fma_f32 v[12:13], v[72:73], v[40:41], v[12:13]
	v_pk_fma_f32 v[20:21], v[76:77], v[40:41], v[20:21]
	v_pk_fma_f32 v[10:11], v[74:75], v[40:41], v[10:11]
	v_pk_fma_f32 v[12:13], v[76:77], v[156:157], v[12:13]
	v_pk_fma_f32 v[20:21], v[80:81], v[156:157], v[20:21]
	v_pk_fma_f32 v[10:11], v[78:79], v[156:157], v[10:11]
	v_pk_fma_f32 v[12:13], v[80:81], v[158:159], v[12:13]
	v_pk_fma_f32 v[20:21], v[84:85], v[158:159], v[20:21]
	v_pk_fma_f32 v[10:11], v[82:83], v[158:159], v[10:11]
	v_pk_fma_f32 v[12:13], v[84:85], v[160:161], v[12:13]
	v_pk_fma_f32 v[20:21], v[88:89], v[160:161], v[20:21]
	v_pk_fma_f32 v[10:11], v[86:87], v[160:161], v[10:11]
	v_pk_fma_f32 v[12:13], v[88:89], v[24:25], v[12:13]
	v_pk_fma_f32 v[20:21], v[92:93], v[24:25], v[20:21]
	v_pk_fma_f32 v[10:11], v[90:91], v[24:25], v[10:11]
	v_pk_fma_f32 v[12:13], v[92:93], v[34:35], v[12:13]
	v_pk_fma_f32 v[20:21], v[96:97], v[34:35], v[20:21]
	v_pk_fma_f32 v[10:11], v[94:95], v[34:35], v[10:11]
	v_pk_fma_f32 v[12:13], v[96:97], v[36:37], v[12:13]
	v_pk_fma_f32 v[20:21], v[100:101], v[36:37], v[20:21]
	v_pk_fma_f32 v[10:11], v[98:99], v[36:37], v[10:11]
	v_pk_fma_f32 v[12:13], v[100:101], v[38:39], v[12:13]
	v_add_u32_e32 v105, s6, v162
	v_add_f32_e32 v20, v20, v21
	v_add_f32_e32 v10, v10, v11
	v_add_f32_e32 v11, v12, v13
	s_barrier
	ds_write2st64_b32 v163, v164, v165 offset1:4
	ds_write2st64_b32 v163, v166, v167 offset0:8 offset1:12
	ds_write2st64_b32 v163, v168, v169 offset0:16 offset1:20
	ds_write2st64_b32 v163, v170, v171 offset0:24 offset1:28
	ds_write2st64_b32 v163, v174, v175 offset0:32 offset1:36
	ds_write2st64_b32 v163, v176, v177 offset0:40 offset1:44
	ds_write2st64_b32 v163, v178, v179 offset0:48 offset1:52
	ds_write2st64_b32 v163, v180, v181 offset0:56 offset1:60
	ds_write2st64_b32 v163, v182, v183 offset0:64 offset1:68
	ds_write2st64_b32 v163, v184, v185 offset0:72 offset1:76
	ds_write2st64_b32 v163, v186, v187 offset0:80 offset1:84
	ds_write2st64_b32 v163, v188, v189 offset0:88 offset1:92
	ds_write2st64_b32 v163, v190, v172 offset0:96 offset1:100
	ds_write2st64_b32 v163, v173, v22 offset0:104 offset1:108
	ds_write2st64_b32 v163, v23, v20 offset0:112 offset1:116
	ds_write2st64_b32 v163, v10, v11 offset0:120 offset1:124
	s_waitcnt lgkmcnt(0)
	s_barrier
	ds_read_b128 v[38:41], v105
	ds_read_b128 v[14:17], v105 offset:49152
	ds_read_b128 v[34:37], v105 offset:8192
	ds_read_b128 v[30:33], v105 offset:16384
	ds_read_b128 v[26:29], v105 offset:24576
	s_waitcnt lgkmcnt(4)
	v_mov_b32_e32 v10, v39
	v_mov_b32_e32 v11, v40
	v_mov_b32_e32 v12, v38
	v_mov_b32_e32 v13, v41
	v_pk_add_f32 v[10:11], v[10:11], v[12:13]
	s_waitcnt lgkmcnt(2)
	v_mov_b32_e32 v12, v34
	v_add_f32_e32 v160, v10, v11
	v_mov_b32_e32 v10, v35
	v_mov_b32_e32 v11, v36
	v_mov_b32_e32 v13, v37
	v_pk_add_f32 v[10:11], v[10:11], v[12:13]
	ds_read_b128 v[22:25], v105 offset:32768
	ds_read_b128 v[18:21], v105 offset:40960
	v_add_f32_e32 v161, v10, v11
	s_waitcnt lgkmcnt(3)
	v_mov_b32_e32 v10, v31
	v_mov_b32_e32 v11, v32
	v_mov_b32_e32 v12, v30
	v_mov_b32_e32 v13, v33
	v_pk_add_f32 v[10:11], v[10:11], v[12:13]
	s_waitcnt lgkmcnt(2)
	v_mov_b32_e32 v12, v26
	v_add_f32_e32 v162, v10, v11
	v_mov_b32_e32 v10, v27
	v_mov_b32_e32 v11, v28
	v_mov_b32_e32 v13, v29
	v_pk_add_f32 v[10:11], v[10:11], v[12:13]
	s_waitcnt lgkmcnt(1)
	v_mov_b32_e32 v12, v22
	v_add_f32_e32 v163, v10, v11
	v_mov_b32_e32 v10, v23
	v_mov_b32_e32 v11, v24
	v_mov_b32_e32 v13, v25
	v_pk_add_f32 v[10:11], v[10:11], v[12:13]
	s_waitcnt lgkmcnt(0)
	v_mov_b32_e32 v12, v18
	v_add_f32_e32 v164, v10, v11
	v_mov_b32_e32 v10, v19
	v_mov_b32_e32 v11, v20
	v_mov_b32_e32 v13, v21
	v_pk_add_f32 v[10:11], v[10:11], v[12:13]
	v_mov_b32_e32 v12, v14
	v_add_f32_e32 v165, v10, v11
	v_mov_b32_e32 v10, v15
	v_mov_b32_e32 v11, v16
	v_mov_b32_e32 v13, v17
	v_pk_add_f32 v[10:11], v[10:11], v[12:13]
	s_cmpk_gt_i32 s65, 0x1df
	v_add_f32_e32 v166, v10, v11
	ds_read_b128 v[10:13], v105 offset:57344
	s_waitcnt lgkmcnt(0)
	v_mov_b32_e32 v156, v11
	v_mov_b32_e32 v157, v12
	v_mov_b32_e32 v158, v10
	v_mov_b32_e32 v159, v13
	v_pk_add_f32 v[156:157], v[156:157], v[158:159]
	v_add_f32_dpp v158, v162, v162 quad_perm:[1,0,3,2] row_mask:0xf bank_mask:0xf bound_ctrl:1
	v_add_f32_e32 v105, v156, v157
	v_add_f32_dpp v156, v160, v160 quad_perm:[1,0,3,2] row_mask:0xf bank_mask:0xf bound_ctrl:1
	v_add_f32_dpp v157, v161, v161 quad_perm:[1,0,3,2] row_mask:0xf bank_mask:0xf bound_ctrl:1
	v_add_f32_dpp v159, v163, v163 quad_perm:[1,0,3,2] row_mask:0xf bank_mask:0xf bound_ctrl:1
	v_add_f32_dpp v156, v156, v156 quad_perm:[2,3,0,1] row_mask:0xf bank_mask:0xf bound_ctrl:1
	v_add_f32_dpp v157, v157, v157 quad_perm:[2,3,0,1] row_mask:0xf bank_mask:0xf bound_ctrl:1
	s_nop 0
	v_add_f32_dpp v156, v156, v156 row_half_mirror row_mask:0xf bank_mask:0xf bound_ctrl:1
	s_nop 0
	v_add_f32_dpp v157, v157, v157 row_half_mirror row_mask:0xf bank_mask:0xf bound_ctrl:1
	v_add_f32_dpp v158, v158, v158 quad_perm:[2,3,0,1] row_mask:0xf bank_mask:0xf bound_ctrl:1
	v_add_f32_dpp v156, v156, v156 row_mirror row_mask:0xf bank_mask:0xf bound_ctrl:1
	v_add_f32_dpp v157, v157, v157 row_mirror row_mask:0xf bank_mask:0xf bound_ctrl:1
	v_add_f32_dpp v158, v158, v158 row_half_mirror row_mask:0xf bank_mask:0xf bound_ctrl:1
	v_add_f32_dpp v156, v156, v156 row_bcast:15 row_mask:0xa bank_mask:0xf
	v_add_f32_dpp v159, v159, v159 quad_perm:[2,3,0,1] row_mask:0xf bank_mask:0xf bound_ctrl:1
	v_add_f32_dpp v158, v158, v158 row_mirror row_mask:0xf bank_mask:0xf bound_ctrl:1
	v_add_f32_dpp v157, v157, v157 row_bcast:15 row_mask:0xa bank_mask:0xf
	v_add_f32_dpp v160, v164, v164 quad_perm:[1,0,3,2] row_mask:0xf bank_mask:0xf bound_ctrl:1
	v_add_f32_dpp v159, v159, v159 row_half_mirror row_mask:0xf bank_mask:0xf bound_ctrl:1
	v_add_f32_dpp v158, v158, v158 row_bcast:15 row_mask:0xa bank_mask:0xf
	v_add_f32_dpp v160, v160, v160 quad_perm:[2,3,0,1] row_mask:0xf bank_mask:0xf bound_ctrl:1
	v_add_f32_dpp v159, v159, v159 row_mirror row_mask:0xf bank_mask:0xf bound_ctrl:1
	v_add_f32_dpp v161, v165, v165 quad_perm:[1,0,3,2] row_mask:0xf bank_mask:0xf bound_ctrl:1
	v_add_f32_dpp v160, v160, v160 row_half_mirror row_mask:0xf bank_mask:0xf bound_ctrl:1
	v_add_f32_dpp v159, v159, v159 row_bcast:15 row_mask:0xa bank_mask:0xf
	v_add_f32_dpp v161, v161, v161 quad_perm:[2,3,0,1] row_mask:0xf bank_mask:0xf bound_ctrl:1
	v_add_f32_dpp v160, v160, v160 row_mirror row_mask:0xf bank_mask:0xf bound_ctrl:1
	v_add_f32_dpp v162, v166, v166 quad_perm:[1,0,3,2] row_mask:0xf bank_mask:0xf bound_ctrl:1
	v_add_f32_dpp v161, v161, v161 row_half_mirror row_mask:0xf bank_mask:0xf bound_ctrl:1
	v_add_f32_dpp v160, v160, v160 row_bcast:15 row_mask:0xa bank_mask:0xf
	v_add_f32_dpp v162, v162, v162 quad_perm:[2,3,0,1] row_mask:0xf bank_mask:0xf bound_ctrl:1
	v_add_f32_dpp v161, v161, v161 row_mirror row_mask:0xf bank_mask:0xf bound_ctrl:1
	v_add_f32_dpp v105, v105, v105 quad_perm:[1,0,3,2] row_mask:0xf bank_mask:0xf bound_ctrl:1
	v_add_f32_dpp v162, v162, v162 row_half_mirror row_mask:0xf bank_mask:0xf bound_ctrl:1
	v_add_f32_dpp v161, v161, v161 row_bcast:15 row_mask:0xa bank_mask:0xf
	v_add_f32_dpp v105, v105, v105 quad_perm:[2,3,0,1] row_mask:0xf bank_mask:0xf bound_ctrl:1
	v_add_f32_dpp v162, v162, v162 row_mirror row_mask:0xf bank_mask:0xf bound_ctrl:1
	s_nop 0
	v_add_f32_dpp v105, v105, v105 row_half_mirror row_mask:0xf bank_mask:0xf bound_ctrl:1
	s_nop 0
	v_add_f32_dpp v162, v162, v162 row_bcast:15 row_mask:0xa bank_mask:0xf
	v_add_f32_dpp v105, v105, v105 row_mirror row_mask:0xf bank_mask:0xf bound_ctrl:1
	s_nop 1
	v_add_f32_dpp v105, v105, v105 row_bcast:15 row_mask:0xa bank_mask:0xf
	s_nop 1
	v_add_f32_dpp v156, v156, v156 row_bcast:31 row_mask:0xc bank_mask:0xf
	s_nop 0
	v_readlane_b32 s6, v156, 63
	s_nop 0
	v_add_f32_dpp v157, v157, v157 row_bcast:31 row_mask:0xc bank_mask:0xf
	v_fma_f32 v39, s6, v239, v39
	v_fma_f32 v38, s6, v239, v38
	v_add_f32_dpp v158, v158, v158 row_bcast:31 row_mask:0xc bank_mask:0xf
	v_fma_f32 v41, s6, v239, v41
	v_fmac_f32_e32 v40, s6, v239
	v_add_f32_dpp v159, v159, v159 row_bcast:31 row_mask:0xc bank_mask:0xf
	v_readlane_b32 s7, v157, 63
	v_readlane_b32 s8, v158, 63
	v_add_f32_dpp v160, v160, v160 row_bcast:31 row_mask:0xc bank_mask:0xf
	v_readlane_b32 s9, v159, 63
	v_pk_mul_f32 v[156:157], v[40:41], v[40:41]
	v_add_f32_dpp v161, v161, v161 row_bcast:31 row_mask:0xc bank_mask:0xf
	v_pk_mul_f32 v[158:159], v[38:39], v[38:39]
	v_readlane_b32 s10, v160, 63
	v_add_f32_dpp v162, v162, v162 row_bcast:31 row_mask:0xc bank_mask:0xf
	v_readlane_b32 s11, v161, 63
	v_pk_mov_b32 v[160:161], v[158:159], v[156:157] op_sel:[1,0]
	v_add_f32_dpp v105, v105, v105 row_bcast:31 row_mask:0xc bank_mask:0xf
	v_mov_b32_e32 v159, v157
	v_pk_add_f32 v[156:157], v[160:161], v[158:159]
	v_fma_f32 v35, s7, v239, v35
	v_fma_f32 v34, s7, v239, v34
	v_fma_f32 v37, s7, v239, v37
	v_fmac_f32_e32 v36, s7, v239
	v_readlane_b32 s67, v105, 63
	v_add_f32_e32 v105, v156, v157
	v_pk_mul_f32 v[156:157], v[36:37], v[36:37]
	v_pk_mul_f32 v[158:159], v[34:35], v[34:35]
	v_fma_f32 v31, s8, v239, v31
	v_pk_mov_b32 v[160:161], v[158:159], v[156:157] op_sel:[1,0]
	v_mov_b32_e32 v159, v157
	v_pk_add_f32 v[156:157], v[160:161], v[158:159]
	v_fma_f32 v30, s8, v239, v30
	v_fma_f32 v33, s8, v239, v33
	v_fmac_f32_e32 v32, s8, v239
	v_readlane_b32 s66, v162, 63
	v_add_f32_e32 v162, v156, v157
	v_pk_mul_f32 v[156:157], v[32:33], v[32:33]
	v_pk_mul_f32 v[158:159], v[30:31], v[30:31]
	v_fma_f32 v27, s9, v239, v27
	v_pk_mov_b32 v[160:161], v[158:159], v[156:157] op_sel:[1,0]
	v_mov_b32_e32 v159, v157
	v_pk_add_f32 v[156:157], v[160:161], v[158:159]
	v_fma_f32 v26, s9, v239, v26
	v_fma_f32 v29, s9, v239, v29
	v_fmac_f32_e32 v28, s9, v239
	v_add_f32_e32 v163, v156, v157
	v_pk_mul_f32 v[156:157], v[28:29], v[28:29]
	v_pk_mul_f32 v[158:159], v[26:27], v[26:27]
	v_fma_f32 v23, s10, v239, v23
	v_pk_mov_b32 v[160:161], v[158:159], v[156:157] op_sel:[1,0]
	v_mov_b32_e32 v159, v157
	v_pk_add_f32 v[156:157], v[160:161], v[158:159]
	v_fma_f32 v22, s10, v239, v22
	v_fma_f32 v25, s10, v239, v25
	v_fmac_f32_e32 v24, s10, v239
	v_add_f32_e32 v164, v156, v157
	v_pk_mul_f32 v[156:157], v[24:25], v[24:25]
	v_pk_mul_f32 v[158:159], v[22:23], v[22:23]
	v_fma_f32 v19, s11, v239, v19
	v_pk_mov_b32 v[160:161], v[158:159], v[156:157] op_sel:[1,0]
	v_mov_b32_e32 v159, v157
	v_pk_add_f32 v[156:157], v[160:161], v[158:159]
	v_fma_f32 v18, s11, v239, v18
	v_fma_f32 v21, s11, v239, v21
	v_fmac_f32_e32 v20, s11, v239
	v_add_f32_e32 v165, v156, v157
	v_pk_mul_f32 v[156:157], v[20:21], v[20:21]
	v_pk_mul_f32 v[158:159], v[18:19], v[18:19]
	v_fma_f32 v15, s66, v239, v15
	v_pk_mov_b32 v[160:161], v[158:159], v[156:157] op_sel:[1,0]
	v_mov_b32_e32 v159, v157
	v_pk_add_f32 v[156:157], v[160:161], v[158:159]
	v_fma_f32 v14, s66, v239, v14
	v_fma_f32 v17, s66, v239, v17
	v_fmac_f32_e32 v16, s66, v239
	v_add_f32_e32 v166, v156, v157
	v_pk_mul_f32 v[156:157], v[16:17], v[16:17]
	v_pk_mul_f32 v[158:159], v[14:15], v[14:15]
	v_fma_f32 v11, s67, v239, v11
	v_pk_mov_b32 v[160:161], v[158:159], v[156:157] op_sel:[1,0]
	v_mov_b32_e32 v159, v157
	v_pk_add_f32 v[156:157], v[160:161], v[158:159]
	v_fma_f32 v10, s67, v239, v10
	v_fma_f32 v13, s67, v239, v13
	v_fmac_f32_e32 v12, s67, v239
	v_add_f32_e32 v167, v156, v157
	v_pk_mul_f32 v[156:157], v[12:13], v[12:13]
	v_pk_mul_f32 v[158:159], v[10:11], v[10:11]
	v_add_f32_dpp v105, v105, v105 quad_perm:[1,0,3,2] row_mask:0xf bank_mask:0xf bound_ctrl:1
	v_pk_mov_b32 v[160:161], v[158:159], v[156:157] op_sel:[1,0]
	v_mov_b32_e32 v159, v157
	v_pk_add_f32 v[156:157], v[160:161], v[158:159]
	v_add_f32_dpp v105, v105, v105 quad_perm:[2,3,0,1] row_mask:0xf bank_mask:0xf bound_ctrl:1
	v_add_f32_e32 v156, v156, v157
	v_add_f32_dpp v157, v162, v162 quad_perm:[1,0,3,2] row_mask:0xf bank_mask:0xf bound_ctrl:1
	v_add_f32_dpp v105, v105, v105 row_half_mirror row_mask:0xf bank_mask:0xf bound_ctrl:1
	v_add_f32_dpp v158, v163, v163 quad_perm:[1,0,3,2] row_mask:0xf bank_mask:0xf bound_ctrl:1
	v_add_f32_dpp v157, v157, v157 quad_perm:[2,3,0,1] row_mask:0xf bank_mask:0xf bound_ctrl:1
	v_add_f32_dpp v105, v105, v105 row_mirror row_mask:0xf bank_mask:0xf bound_ctrl:1
	s_nop 0
	v_add_f32_dpp v157, v157, v157 row_half_mirror row_mask:0xf bank_mask:0xf bound_ctrl:1
	v_add_f32_dpp v158, v158, v158 quad_perm:[2,3,0,1] row_mask:0xf bank_mask:0xf bound_ctrl:1
	v_add_f32_dpp v105, v105, v105 row_bcast:15 row_mask:0xa bank_mask:0xf
	v_add_f32_dpp v157, v157, v157 row_mirror row_mask:0xf bank_mask:0xf bound_ctrl:1
	v_add_f32_dpp v159, v164, v164 quad_perm:[1,0,3,2] row_mask:0xf bank_mask:0xf bound_ctrl:1
	v_add_f32_dpp v158, v158, v158 row_half_mirror row_mask:0xf bank_mask:0xf bound_ctrl:1
	v_add_f32_dpp v157, v157, v157 row_bcast:15 row_mask:0xa bank_mask:0xf
	v_add_f32_dpp v159, v159, v159 quad_perm:[2,3,0,1] row_mask:0xf bank_mask:0xf bound_ctrl:1
	v_add_f32_dpp v158, v158, v158 row_mirror row_mask:0xf bank_mask:0xf bound_ctrl:1
	v_add_f32_dpp v160, v165, v165 quad_perm:[1,0,3,2] row_mask:0xf bank_mask:0xf bound_ctrl:1
	v_add_f32_dpp v159, v159, v159 row_half_mirror row_mask:0xf bank_mask:0xf bound_ctrl:1
	v_add_f32_dpp v158, v158, v158 row_bcast:15 row_mask:0xa bank_mask:0xf
	v_add_f32_dpp v160, v160, v160 quad_perm:[2,3,0,1] row_mask:0xf bank_mask:0xf bound_ctrl:1
	v_add_f32_dpp v159, v159, v159 row_mirror row_mask:0xf bank_mask:0xf bound_ctrl:1
	v_add_f32_dpp v161, v166, v166 quad_perm:[1,0,3,2] row_mask:0xf bank_mask:0xf bound_ctrl:1
	v_add_f32_dpp v160, v160, v160 row_half_mirror row_mask:0xf bank_mask:0xf bound_ctrl:1
	v_add_f32_dpp v159, v159, v159 row_bcast:15 row_mask:0xa bank_mask:0xf
	v_add_f32_dpp v161, v161, v161 quad_perm:[2,3,0,1] row_mask:0xf bank_mask:0xf bound_ctrl:1
	v_add_f32_dpp v160, v160, v160 row_mirror row_mask:0xf bank_mask:0xf bound_ctrl:1
	v_add_f32_dpp v162, v167, v167 quad_perm:[1,0,3,2] row_mask:0xf bank_mask:0xf bound_ctrl:1
	v_add_f32_dpp v161, v161, v161 row_half_mirror row_mask:0xf bank_mask:0xf bound_ctrl:1
	v_add_f32_dpp v160, v160, v160 row_bcast:15 row_mask:0xa bank_mask:0xf
	v_add_f32_dpp v162, v162, v162 quad_perm:[2,3,0,1] row_mask:0xf bank_mask:0xf bound_ctrl:1
	v_add_f32_dpp v161, v161, v161 row_mirror row_mask:0xf bank_mask:0xf bound_ctrl:1
	v_add_f32_dpp v156, v156, v156 quad_perm:[1,0,3,2] row_mask:0xf bank_mask:0xf bound_ctrl:1
	v_add_f32_dpp v162, v162, v162 row_half_mirror row_mask:0xf bank_mask:0xf bound_ctrl:1
	v_add_f32_dpp v161, v161, v161 row_bcast:15 row_mask:0xa bank_mask:0xf
	v_add_f32_dpp v156, v156, v156 quad_perm:[2,3,0,1] row_mask:0xf bank_mask:0xf bound_ctrl:1
	v_add_f32_dpp v162, v162, v162 row_mirror row_mask:0xf bank_mask:0xf bound_ctrl:1
	s_nop 0
	v_add_f32_dpp v156, v156, v156 row_half_mirror row_mask:0xf bank_mask:0xf bound_ctrl:1
	s_nop 0
	v_add_f32_dpp v162, v162, v162 row_bcast:15 row_mask:0xa bank_mask:0xf
	v_add_f32_dpp v156, v156, v156 row_mirror row_mask:0xf bank_mask:0xf bound_ctrl:1
	s_nop 1
	v_add_f32_dpp v156, v156, v156 row_bcast:15 row_mask:0xa bank_mask:0xf
	s_nop 1
	v_add_f32_dpp v105, v105, v105 row_bcast:31 row_mask:0xc bank_mask:0xf
	s_nop 0
	v_readlane_b32 s8, v105, 63
	s_nop 0
	v_add_f32_dpp v157, v157, v157 row_bcast:31 row_mask:0xc bank_mask:0xf
	v_fma_f32 v105, s8, v235, v225
	v_readlane_b32 s9, v157, 63
	v_add_f32_dpp v158, v158, v158 row_bcast:31 row_mask:0xc bank_mask:0xf
	s_nop 0
	v_readlane_b32 s69, v158, 63
	s_nop 0
	v_add_f32_dpp v159, v159, v159 row_bcast:31 row_mask:0xc bank_mask:0xf
	s_nop 0
	v_readlane_b32 s68, v159, 63
	s_nop 0
	v_add_f32_dpp v160, v160, v160 row_bcast:31 row_mask:0xc bank_mask:0xf
	s_nop 0
	v_readlane_b32 s67, v160, 63
	s_nop 0
	v_add_f32_dpp v161, v161, v161 row_bcast:31 row_mask:0xc bank_mask:0xf
	s_nop 0
	v_readlane_b32 s66, v161, 63
	s_nop 0
	v_add_f32_dpp v162, v162, v162 row_bcast:31 row_mask:0xc bank_mask:0xf
	v_mov_b32_e32 v163, v131
	v_readlane_b32 s7, v162, 63
	s_nop 0
	v_mov_b32_dpp v163, v156 row_bcast:31 row_mask:0xc bank_mask:0xf
	v_add_f32_e32 v156, v156, v163
	s_nop 0
	v_readlane_b32 s6, v156, 63
	v_rsq_f32_e32 v156, v105
	s_nop 0
	v_pk_mul_f32 v[38:39], v[38:39], v[156:157] op_sel_hi:[1,0]
	v_pk_fma_f32 v[38:39], v[2:3], v[38:39], v[6:7]
	v_pk_mul_f32 v[40:41], v[40:41], v[156:157] op_sel_hi:[1,0]
	v_mul_f32_e32 v105, 0xbfb8aa3b, v38
	v_exp_f32_e32 v105, v105
	v_pk_fma_f32 v[40:41], v[4:5], v[40:41], v[8:9]
	v_add_f32_e32 v105, 1.0, v105
	v_rcp_f32_e32 v156, v105
	v_mul_f32_e32 v105, 0xbfb8aa3b, v39
	v_exp_f32_e32 v105, v105
	s_nop 0
	v_add_f32_e32 v105, 1.0, v105
	v_rcp_f32_e32 v157, v105
	v_mul_f32_e32 v105, 0xbfb8aa3b, v40
	v_exp_f32_e32 v105, v105
	v_pk_mul_f32 v[38:39], v[38:39], v[156:157]
	v_add_f32_e32 v105, 1.0, v105
	v_rcp_f32_e32 v156, v105
	v_mul_f32_e32 v105, 0xbfb8aa3b, v41
	v_exp_f32_e32 v105, v105
	s_nop 0
	v_add_f32_e32 v105, 1.0, v105
	v_rcp_f32_e32 v157, v105
	s_nop 0
	v_pk_mul_f32 v[40:41], v[40:41], v[156:157]
	v_cvt_pk_bf16_f32 v156, v38, v39
	v_fma_f32 v39, s9, v235, v225
	v_cvt_pk_bf16_f32 v157, v40, v41
	v_rsq_f32_e32 v40, v39
	v_lshlrev_b32_e32 v38, 3, v130
	global_store_dwordx2 v38, v[156:157], s[56:57] offset:512
	v_pk_mul_f32 v[34:35], v[34:35], v[40:41] op_sel_hi:[1,0]
	s_nop 0
	v_pk_fma_f32 v[34:35], v[2:3], v[34:35], v[6:7]
	v_pk_mul_f32 v[36:37], v[36:37], v[40:41] op_sel_hi:[1,0]
	v_mul_f32_e32 v39, 0xbfb8aa3b, v34
	v_exp_f32_e32 v39, v39
	v_pk_fma_f32 v[36:37], v[4:5], v[36:37], v[8:9]
	v_add_f32_e32 v39, 1.0, v39
	v_rcp_f32_e32 v40, v39
	v_mul_f32_e32 v39, 0xbfb8aa3b, v35
	v_exp_f32_e32 v39, v39
	s_nop 0
	v_add_f32_e32 v39, 1.0, v39
	v_rcp_f32_e32 v41, v39
	v_mul_f32_e32 v39, 0xbfb8aa3b, v36
	v_exp_f32_e32 v39, v39
	v_pk_mul_f32 v[34:35], v[34:35], v[40:41]
	s_nop 0
	v_cvt_pk_bf16_f32 v34, v34, v35
	v_add_f32_e32 v39, 1.0, v39
	v_rcp_f32_e32 v40, v39
	v_mul_f32_e32 v39, 0xbfb8aa3b, v37
	v_exp_f32_e32 v39, v39
	s_nop 0
	v_add_f32_e32 v39, 1.0, v39
	v_rcp_f32_e32 v41, v39
	s_nop 0
	v_pk_mul_f32 v[36:37], v[36:37], v[40:41]
	v_cvt_pk_bf16_f32 v35, v36, v37
	global_store_dwordx2 v38, v[34:35], s[54:55] offset:512
	v_fma_f32 v34, s69, v235, v225
	v_rsq_f32_e32 v34, v34
	s_nop 0
	v_pk_mul_f32 v[30:31], v[30:31], v[34:35] op_sel_hi:[1,0]
	v_pk_fma_f32 v[30:31], v[2:3], v[30:31], v[6:7]
	v_pk_mul_f32 v[32:33], v[32:33], v[34:35] op_sel_hi:[1,0]
	v_pk_mul_f32 v[34:35], v[30:31], s[96:97] op_sel_hi:[1,0]
	v_exp_f32_e32 v34, v34
	v_exp_f32_e32 v35, v35
	v_pk_fma_f32 v[32:33], v[4:5], v[32:33], v[8:9]
	v_pk_add_f32 v[34:35], v[34:35], 1.0 op_sel_hi:[1,0]
	v_rcp_f32_e32 v34, v34
	v_rcp_f32_e32 v35, v35
	s_nop 0
	v_pk_mul_f32 v[30:31], v[30:31], v[34:35]
	v_pk_mul_f32 v[34:35], v[32:33], s[96:97] op_sel_hi:[1,0]
	v_exp_f32_e32 v34, v34
	v_exp_f32_e32 v35, v35
	v_cvt_pk_bf16_f32 v30, v30, v31
	v_pk_add_f32 v[34:35], v[34:35], 1.0 op_sel_hi:[1,0]
	v_rcp_f32_e32 v34, v34
	v_rcp_f32_e32 v35, v35
	s_nop 0
	v_pk_mul_f32 v[32:33], v[32:33], v[34:35]
	v_cvt_pk_bf16_f32 v31, v32, v33
	global_store_dwordx2 v38, v[30:31], s[52:53] offset:512
	v_fma_f32 v30, s68, v235, v225
	v_rsq_f32_e32 v30, v30
	s_nop 0
	v_pk_mul_f32 v[26:27], v[26:27], v[30:31] op_sel_hi:[1,0]
	v_pk_fma_f32 v[26:27], v[2:3], v[26:27], v[6:7]
	v_pk_mul_f32 v[28:29], v[28:29], v[30:31] op_sel_hi:[1,0]
	v_pk_mul_f32 v[30:31], v[26:27], s[96:97] op_sel_hi:[1,0]
	v_exp_f32_e32 v30, v30
	v_exp_f32_e32 v31, v31
	v_pk_fma_f32 v[28:29], v[4:5], v[28:29], v[8:9]
	v_pk_add_f32 v[30:31], v[30:31], 1.0 op_sel_hi:[1,0]
	v_rcp_f32_e32 v30, v30
	v_rcp_f32_e32 v31, v31
	s_nop 0
	v_pk_mul_f32 v[26:27], v[26:27], v[30:31]
	v_pk_mul_f32 v[30:31], v[28:29], s[96:97] op_sel_hi:[1,0]
	v_exp_f32_e32 v30, v30
	v_exp_f32_e32 v31, v31
	v_cvt_pk_bf16_f32 v26, v26, v27
	v_pk_add_f32 v[30:31], v[30:31], 1.0 op_sel_hi:[1,0]
	v_rcp_f32_e32 v30, v30
	v_rcp_f32_e32 v31, v31
	s_nop 0
	v_pk_mul_f32 v[28:29], v[28:29], v[30:31]
	v_cvt_pk_bf16_f32 v27, v28, v29
	global_store_dwordx2 v38, v[26:27], s[50:51] offset:512
	v_fma_f32 v26, s67, v235, v225
	v_rsq_f32_e32 v26, v26
	s_nop 0
	v_pk_mul_f32 v[22:23], v[22:23], v[26:27] op_sel_hi:[1,0]
	v_pk_fma_f32 v[22:23], v[2:3], v[22:23], v[6:7]
	v_pk_mul_f32 v[24:25], v[24:25], v[26:27] op_sel_hi:[1,0]
	v_pk_mul_f32 v[26:27], v[22:23], s[96:97] op_sel_hi:[1,0]
	v_exp_f32_e32 v26, v26
	v_exp_f32_e32 v27, v27
	v_pk_fma_f32 v[24:25], v[4:5], v[24:25], v[8:9]
	v_pk_add_f32 v[26:27], v[26:27], 1.0 op_sel_hi:[1,0]
	v_rcp_f32_e32 v26, v26
	v_rcp_f32_e32 v27, v27
	s_nop 0
	v_pk_mul_f32 v[22:23], v[22:23], v[26:27]
	v_pk_mul_f32 v[26:27], v[24:25], s[96:97] op_sel_hi:[1,0]
	v_exp_f32_e32 v26, v26
	v_exp_f32_e32 v27, v27
	v_cvt_pk_bf16_f32 v22, v22, v23
	v_pk_add_f32 v[26:27], v[26:27], 1.0 op_sel_hi:[1,0]
	v_rcp_f32_e32 v26, v26
	v_rcp_f32_e32 v27, v27
	s_nop 0
	v_pk_mul_f32 v[24:25], v[24:25], v[26:27]
	v_cvt_pk_bf16_f32 v23, v24, v25
	global_store_dwordx2 v38, v[22:23], s[48:49] offset:512
	v_fma_f32 v22, s66, v235, v225
	v_rsq_f32_e32 v22, v22
	s_nop 0
	v_pk_mul_f32 v[18:19], v[18:19], v[22:23] op_sel_hi:[1,0]
	v_pk_fma_f32 v[18:19], v[2:3], v[18:19], v[6:7]
	v_pk_mul_f32 v[20:21], v[20:21], v[22:23] op_sel_hi:[1,0]
	v_pk_mul_f32 v[22:23], v[18:19], s[96:97] op_sel_hi:[1,0]
	v_exp_f32_e32 v22, v22
	v_exp_f32_e32 v23, v23
	v_pk_fma_f32 v[20:21], v[4:5], v[20:21], v[8:9]
	v_pk_add_f32 v[22:23], v[22:23], 1.0 op_sel_hi:[1,0]
	v_rcp_f32_e32 v22, v22
	v_rcp_f32_e32 v23, v23
	s_nop 0
	v_pk_mul_f32 v[18:19], v[18:19], v[22:23]
	v_pk_mul_f32 v[22:23], v[20:21], s[96:97] op_sel_hi:[1,0]
	v_exp_f32_e32 v22, v22
	v_exp_f32_e32 v23, v23
	v_cvt_pk_bf16_f32 v18, v18, v19
	v_pk_add_f32 v[22:23], v[22:23], 1.0 op_sel_hi:[1,0]
	v_rcp_f32_e32 v22, v22
	v_rcp_f32_e32 v23, v23
	s_nop 0
	v_pk_mul_f32 v[20:21], v[20:21], v[22:23]
	v_cvt_pk_bf16_f32 v19, v20, v21
	global_store_dwordx2 v38, v[18:19], s[46:47] offset:512
	v_fma_f32 v18, s7, v235, v225
	v_rsq_f32_e32 v18, v18
	s_nop 0
	v_pk_mul_f32 v[14:15], v[14:15], v[18:19] op_sel_hi:[1,0]
	v_pk_fma_f32 v[14:15], v[2:3], v[14:15], v[6:7]
	v_pk_mul_f32 v[16:17], v[16:17], v[18:19] op_sel_hi:[1,0]
	v_pk_mul_f32 v[18:19], v[14:15], s[96:97] op_sel_hi:[1,0]
	v_exp_f32_e32 v18, v18
	v_exp_f32_e32 v19, v19
	v_pk_fma_f32 v[16:17], v[4:5], v[16:17], v[8:9]
	v_pk_add_f32 v[18:19], v[18:19], 1.0 op_sel_hi:[1,0]
	v_rcp_f32_e32 v18, v18
	v_rcp_f32_e32 v19, v19
	s_nop 0
	v_pk_mul_f32 v[14:15], v[14:15], v[18:19]
	v_pk_mul_f32 v[18:19], v[16:17], s[96:97] op_sel_hi:[1,0]
	v_exp_f32_e32 v18, v18
	v_exp_f32_e32 v19, v19
	v_cvt_pk_bf16_f32 v14, v14, v15
	v_pk_add_f32 v[18:19], v[18:19], 1.0 op_sel_hi:[1,0]
	v_rcp_f32_e32 v18, v18
	v_rcp_f32_e32 v19, v19
	s_nop 0
	v_pk_mul_f32 v[16:17], v[16:17], v[18:19]
	v_cvt_pk_bf16_f32 v15, v16, v17
	global_store_dwordx2 v38, v[14:15], s[44:45] offset:512
	v_fma_f32 v14, s6, v235, v225
	v_rsq_f32_e32 v14, v14
	s_mov_b32 s6, s65
	v_pk_mul_f32 v[10:11], v[10:11], v[14:15] op_sel_hi:[1,0]
	v_pk_fma_f32 v[10:11], v[2:3], v[10:11], v[6:7]
	v_pk_mul_f32 v[12:13], v[12:13], v[14:15] op_sel_hi:[1,0]
	v_pk_mul_f32 v[14:15], v[10:11], s[96:97] op_sel_hi:[1,0]
	v_exp_f32_e32 v14, v14
	v_exp_f32_e32 v15, v15
	v_pk_fma_f32 v[12:13], v[4:5], v[12:13], v[8:9]
	v_pk_add_f32 v[14:15], v[14:15], 1.0 op_sel_hi:[1,0]
	v_rcp_f32_e32 v14, v14
	v_rcp_f32_e32 v15, v15
	s_nop 0
	v_pk_mul_f32 v[10:11], v[10:11], v[14:15]
	v_pk_mul_f32 v[14:15], v[12:13], s[96:97] op_sel_hi:[1,0]
	v_exp_f32_e32 v14, v14
	v_exp_f32_e32 v15, v15
	v_cvt_pk_bf16_f32 v10, v10, v11
	v_pk_add_f32 v[14:15], v[14:15], 1.0 op_sel_hi:[1,0]
	v_rcp_f32_e32 v14, v14
	v_rcp_f32_e32 v15, v15
	s_nop 0
	v_pk_mul_f32 v[12:13], v[12:13], v[14:15]
	v_cvt_pk_bf16_f32 v11, v12, v13
	global_store_dwordx2 v38, v[10:11], s[42:43] offset:512
	s_barrier
	s_cbranch_scc1 .LBB0_344

.LBB0_332:
	s_waitcnt vmcnt(2)
	v_lshlrev_b32_e32 v12, 16, v154
	v_and_b32_e32 v13, 0xffff0000, v154
	v_lshlrev_b32_e32 v14, 16, v155
	v_and_b32_e32 v15, 0xffff0000, v155
	v_pk_mul_f32 v[12:13], v[12:13], s[96:97] op_sel_hi:[1,0]
	v_pk_mul_f32 v[14:15], v[14:15], s[96:97] op_sel_hi:[1,0]
	v_exp_f32_e32 v12, v12
	v_exp_f32_e32 v13, v13
	v_exp_f32_e32 v14, v14
	v_exp_f32_e32 v15, v15
	v_pk_add_f32 v[12:13], v[12:13], 1.0 op_sel_hi:[1,0]
	v_pk_add_f32 v[14:15], v[14:15], 1.0 op_sel_hi:[1,0]
	v_rcp_f32_e32 v12, v12
	v_rcp_f32_e32 v13, v13
	v_rcp_f32_e32 v14, v14
	v_rcp_f32_e32 v15, v15
	s_waitcnt vmcnt(1)
	v_and_b32_e32 v17, 0xffff0000, v152
	v_and_b32_e32 v19, 0xffff0000, v153
	v_lshlrev_b32_e32 v16, 16, v152
	v_lshlrev_b32_e32 v18, 16, v153
	s_cmp_ge_i32 s7, s43
	v_pk_mul_f32 v[14:15], v[14:15], v[18:19]
	v_pk_mul_f32 v[12:13], v[12:13], v[16:17]
	s_cselect_b64 vcc, -1, 0
	v_lshl_add_u32 v20, s7, 10, v11
	v_cndmask_b32_e32 v13, 0, v13, vcc
	v_cndmask_b32_e32 v12, 0, v12, vcc
	v_cndmask_b32_e32 v15, 0, v15, vcc
	v_cndmask_b32_e32 v14, 0, v14, vcc
	ds_write_b128 v20, v[12:15]
	s_cmpk_gt_i32 s7, 0x55
	s_cbranch_scc1 .LBB0_322
.LBB0_333:
	s_waitcnt vmcnt(4)
	v_lshlrev_b32_e32 v12, 16, v150
	v_and_b32_e32 v13, 0xffff0000, v150
	v_lshlrev_b32_e32 v14, 16, v151
	v_and_b32_e32 v15, 0xffff0000, v151
	v_pk_mul_f32 v[12:13], v[12:13], s[96:97] op_sel_hi:[1,0]
	v_pk_mul_f32 v[14:15], v[14:15], s[96:97] op_sel_hi:[1,0]
	v_exp_f32_e32 v12, v12
	v_exp_f32_e32 v13, v13
	v_exp_f32_e32 v14, v14
	v_exp_f32_e32 v15, v15
	v_pk_add_f32 v[12:13], v[12:13], 1.0 op_sel_hi:[1,0]
	v_pk_add_f32 v[14:15], v[14:15], 1.0 op_sel_hi:[1,0]
	v_rcp_f32_e32 v12, v12
	v_rcp_f32_e32 v13, v13
	v_rcp_f32_e32 v14, v14
	v_rcp_f32_e32 v15, v15
	s_add_i32 s8, s7, 8
	s_waitcnt vmcnt(3)
	v_and_b32_e32 v17, 0xffff0000, v148
	v_and_b32_e32 v19, 0xffff0000, v149
	v_lshlrev_b32_e32 v16, 16, v148
	v_lshlrev_b32_e32 v18, 16, v149
	s_cmp_ge_i32 s8, s43
	v_pk_mul_f32 v[14:15], v[14:15], v[18:19]
	v_pk_mul_f32 v[12:13], v[12:13], v[16:17]
	s_cselect_b64 vcc, -1, 0
	v_lshl_add_u32 v20, s8, 10, v11
	v_cndmask_b32_e32 v13, 0, v13, vcc
	v_cndmask_b32_e32 v12, 0, v12, vcc
	v_cndmask_b32_e32 v15, 0, v15, vcc
	v_cndmask_b32_e32 v14, 0, v14, vcc
	ds_write_b128 v20, v[12:15]
	s_cmpk_gt_i32 s7, 0x4d
	s_cbranch_scc1 .LBB0_323
.LBB0_334:
	s_waitcnt vmcnt(6)
	v_lshlrev_b32_e32 v12, 16, v146
	v_and_b32_e32 v13, 0xffff0000, v146
	v_lshlrev_b32_e32 v14, 16, v147
	v_and_b32_e32 v15, 0xffff0000, v147
	v_pk_mul_f32 v[12:13], v[12:13], s[96:97] op_sel_hi:[1,0]
	v_pk_mul_f32 v[14:15], v[14:15], s[96:97] op_sel_hi:[1,0]
	v_exp_f32_e32 v12, v12
	v_exp_f32_e32 v13, v13
	v_exp_f32_e32 v14, v14
	v_exp_f32_e32 v15, v15
	v_pk_add_f32 v[12:13], v[12:13], 1.0 op_sel_hi:[1,0]
	v_pk_add_f32 v[14:15], v[14:15], 1.0 op_sel_hi:[1,0]
	v_rcp_f32_e32 v12, v12
	v_rcp_f32_e32 v13, v13
	v_rcp_f32_e32 v14, v14
	v_rcp_f32_e32 v15, v15
	s_add_i32 s8, s7, 16
	s_waitcnt vmcnt(5)
	v_and_b32_e32 v17, 0xffff0000, v144
	v_and_b32_e32 v19, 0xffff0000, v145
	v_lshlrev_b32_e32 v16, 16, v144
	v_lshlrev_b32_e32 v18, 16, v145
	s_cmp_ge_i32 s8, s43
	v_pk_mul_f32 v[14:15], v[14:15], v[18:19]
	v_pk_mul_f32 v[12:13], v[12:13], v[16:17]
	s_cselect_b64 vcc, -1, 0
	v_lshl_add_u32 v20, s8, 10, v11
	v_cndmask_b32_e32 v13, 0, v13, vcc
	v_cndmask_b32_e32 v12, 0, v12, vcc
	v_cndmask_b32_e32 v15, 0, v15, vcc
	v_cndmask_b32_e32 v14, 0, v14, vcc
	ds_write_b128 v20, v[12:15]
	s_cmpk_gt_i32 s7, 0x45
	s_cbranch_scc1 .LBB0_324
.LBB0_335:
	s_waitcnt vmcnt(8)
	v_lshlrev_b32_e32 v12, 16, v142
	v_and_b32_e32 v13, 0xffff0000, v142
	v_lshlrev_b32_e32 v14, 16, v143
	v_and_b32_e32 v15, 0xffff0000, v143
	v_pk_mul_f32 v[12:13], v[12:13], s[96:97] op_sel_hi:[1,0]
	v_pk_mul_f32 v[14:15], v[14:15], s[96:97] op_sel_hi:[1,0]
	v_exp_f32_e32 v12, v12
	v_exp_f32_e32 v13, v13
	v_exp_f32_e32 v14, v14
	v_exp_f32_e32 v15, v15
	v_pk_add_f32 v[12:13], v[12:13], 1.0 op_sel_hi:[1,0]
	v_pk_add_f32 v[14:15], v[14:15], 1.0 op_sel_hi:[1,0]
	v_rcp_f32_e32 v12, v12
	v_rcp_f32_e32 v13, v13
	v_rcp_f32_e32 v14, v14
	v_rcp_f32_e32 v15, v15
	s_add_i32 s8, s7, 24
	s_waitcnt vmcnt(7)
	v_and_b32_e32 v17, 0xffff0000, v140
	v_and_b32_e32 v19, 0xffff0000, v141
	v_lshlrev_b32_e32 v16, 16, v140
	v_lshlrev_b32_e32 v18, 16, v141
	s_cmp_ge_i32 s8, s43
	v_pk_mul_f32 v[14:15], v[14:15], v[18:19]
	v_pk_mul_f32 v[12:13], v[12:13], v[16:17]
	s_cselect_b64 vcc, -1, 0
	v_lshl_add_u32 v20, s8, 10, v11
	v_cndmask_b32_e32 v13, 0, v13, vcc
	v_cndmask_b32_e32 v12, 0, v12, vcc
	v_cndmask_b32_e32 v15, 0, v15, vcc
	v_cndmask_b32_e32 v14, 0, v14, vcc
	ds_write_b128 v20, v[12:15]
	s_cmp_gt_i32 s7, 61
	s_cbranch_scc1 .LBB0_325
.LBB0_336:
	s_waitcnt vmcnt(10)
	v_lshlrev_b32_e32 v12, 16, v138
	v_and_b32_e32 v13, 0xffff0000, v138
	v_lshlrev_b32_e32 v14, 16, v139
	v_and_b32_e32 v15, 0xffff0000, v139
	v_pk_mul_f32 v[12:13], v[12:13], s[96:97] op_sel_hi:[1,0]
	v_pk_mul_f32 v[14:15], v[14:15], s[96:97] op_sel_hi:[1,0]
	v_exp_f32_e32 v12, v12
	v_exp_f32_e32 v13, v13
	v_exp_f32_e32 v14, v14
	v_exp_f32_e32 v15, v15
	v_pk_add_f32 v[12:13], v[12:13], 1.0 op_sel_hi:[1,0]
	v_pk_add_f32 v[14:15], v[14:15], 1.0 op_sel_hi:[1,0]
	v_rcp_f32_e32 v12, v12
	v_rcp_f32_e32 v13, v13
	v_rcp_f32_e32 v14, v14
	v_rcp_f32_e32 v15, v15
	s_add_i32 s8, s7, 32
	s_waitcnt vmcnt(9)
	v_and_b32_e32 v17, 0xffff0000, v136
	v_and_b32_e32 v19, 0xffff0000, v137
	v_lshlrev_b32_e32 v16, 16, v136
	v_lshlrev_b32_e32 v18, 16, v137
	s_cmp_ge_i32 s8, s43
	v_pk_mul_f32 v[14:15], v[14:15], v[18:19]
	v_pk_mul_f32 v[12:13], v[12:13], v[16:17]
	s_cselect_b64 vcc, -1, 0
	v_lshl_add_u32 v20, s8, 10, v11
	v_cndmask_b32_e32 v13, 0, v13, vcc
	v_cndmask_b32_e32 v12, 0, v12, vcc
	v_cndmask_b32_e32 v15, 0, v15, vcc
	v_cndmask_b32_e32 v14, 0, v14, vcc
	ds_write_b128 v20, v[12:15]
	s_cmp_gt_i32 s7, 53
	s_cbranch_scc1 .LBB0_326
.LBB0_337:
	s_waitcnt vmcnt(12)
	v_lshlrev_b32_e32 v12, 16, v134
	v_and_b32_e32 v13, 0xffff0000, v134
	v_lshlrev_b32_e32 v14, 16, v135
	v_and_b32_e32 v15, 0xffff0000, v135
	v_pk_mul_f32 v[12:13], v[12:13], s[96:97] op_sel_hi:[1,0]
	v_pk_mul_f32 v[14:15], v[14:15], s[96:97] op_sel_hi:[1,0]
	v_exp_f32_e32 v12, v12
	v_exp_f32_e32 v13, v13
	v_exp_f32_e32 v14, v14
	v_exp_f32_e32 v15, v15
	v_pk_add_f32 v[12:13], v[12:13], 1.0 op_sel_hi:[1,0]
	v_pk_add_f32 v[14:15], v[14:15], 1.0 op_sel_hi:[1,0]
	v_rcp_f32_e32 v12, v12
	v_rcp_f32_e32 v13, v13
	v_rcp_f32_e32 v14, v14
	v_rcp_f32_e32 v15, v15
	s_add_i32 s8, s7, 40
	s_waitcnt vmcnt(11)
	v_and_b32_e32 v17, 0xffff0000, v132
	v_and_b32_e32 v19, 0xffff0000, v133
	v_lshlrev_b32_e32 v16, 16, v132
	v_lshlrev_b32_e32 v18, 16, v133
	s_cmp_ge_i32 s8, s43
	v_pk_mul_f32 v[14:15], v[14:15], v[18:19]
	v_pk_mul_f32 v[12:13], v[12:13], v[16:17]
	s_cselect_b64 vcc, -1, 0
	v_lshl_add_u32 v20, s8, 10, v11
	v_cndmask_b32_e32 v13, 0, v13, vcc
	v_cndmask_b32_e32 v12, 0, v12, vcc
	v_cndmask_b32_e32 v15, 0, v15, vcc
	v_cndmask_b32_e32 v14, 0, v14, vcc
	ds_write_b128 v20, v[12:15]
	s_cmp_gt_i32 s7, 45
	s_cbranch_scc1 .LBB0_327
.LBB0_338:
	s_waitcnt vmcnt(14)
	v_lshlrev_b32_e32 v12, 16, v128
	v_and_b32_e32 v13, 0xffff0000, v128
	v_lshlrev_b32_e32 v14, 16, v129
	v_and_b32_e32 v15, 0xffff0000, v129
	v_pk_mul_f32 v[12:13], v[12:13], s[96:97] op_sel_hi:[1,0]
	v_pk_mul_f32 v[14:15], v[14:15], s[96:97] op_sel_hi:[1,0]
	v_exp_f32_e32 v12, v12
	v_exp_f32_e32 v13, v13
	v_exp_f32_e32 v14, v14
	v_exp_f32_e32 v15, v15
	v_pk_add_f32 v[12:13], v[12:13], 1.0 op_sel_hi:[1,0]
	v_pk_add_f32 v[14:15], v[14:15], 1.0 op_sel_hi:[1,0]
	v_rcp_f32_e32 v12, v12
	v_rcp_f32_e32 v13, v13
	v_rcp_f32_e32 v14, v14
	v_rcp_f32_e32 v15, v15
	s_add_i32 s8, s7, 48
	s_waitcnt vmcnt(13)
	v_and_b32_e32 v17, 0xffff0000, v126
	v_and_b32_e32 v19, 0xffff0000, v127
	v_lshlrev_b32_e32 v16, 16, v126
	v_lshlrev_b32_e32 v18, 16, v127
	s_cmp_ge_i32 s8, s43
	v_pk_mul_f32 v[14:15], v[14:15], v[18:19]
	v_pk_mul_f32 v[12:13], v[12:13], v[16:17]
	s_cselect_b64 vcc, -1, 0
	v_lshl_add_u32 v20, s8, 10, v11
	v_cndmask_b32_e32 v13, 0, v13, vcc
	v_cndmask_b32_e32 v12, 0, v12, vcc
	v_cndmask_b32_e32 v15, 0, v15, vcc
	v_cndmask_b32_e32 v14, 0, v14, vcc
	ds_write_b128 v20, v[12:15]
	s_cmp_gt_i32 s7, 37
	s_cbranch_scc1 .LBB0_328
.LBB0_339:
	s_waitcnt vmcnt(16)
	v_lshlrev_b32_e32 v12, 16, v124
	v_and_b32_e32 v13, 0xffff0000, v124
	v_lshlrev_b32_e32 v14, 16, v125
	v_and_b32_e32 v15, 0xffff0000, v125
	v_pk_mul_f32 v[12:13], v[12:13], s[96:97] op_sel_hi:[1,0]
	v_pk_mul_f32 v[14:15], v[14:15], s[96:97] op_sel_hi:[1,0]
	v_exp_f32_e32 v12, v12
	v_exp_f32_e32 v13, v13
	v_exp_f32_e32 v14, v14
	v_exp_f32_e32 v15, v15
	v_pk_add_f32 v[12:13], v[12:13], 1.0 op_sel_hi:[1,0]
	v_pk_add_f32 v[14:15], v[14:15], 1.0 op_sel_hi:[1,0]
	v_rcp_f32_e32 v12, v12
	v_rcp_f32_e32 v13, v13
	v_rcp_f32_e32 v14, v14
	v_rcp_f32_e32 v15, v15
	s_add_i32 s8, s7, 56
	s_waitcnt vmcnt(15)
	v_and_b32_e32 v17, 0xffff0000, v122
	v_and_b32_e32 v19, 0xffff0000, v123
	v_lshlrev_b32_e32 v16, 16, v122
	v_lshlrev_b32_e32 v18, 16, v123
	s_cmp_ge_i32 s8, s43
	v_pk_mul_f32 v[14:15], v[14:15], v[18:19]
	v_pk_mul_f32 v[12:13], v[12:13], v[16:17]
	s_cselect_b64 vcc, -1, 0
	v_lshl_add_u32 v20, s8, 10, v11
	v_cndmask_b32_e32 v13, 0, v13, vcc
	v_cndmask_b32_e32 v12, 0, v12, vcc
	v_cndmask_b32_e32 v15, 0, v15, vcc
	v_cndmask_b32_e32 v14, 0, v14, vcc
	ds_write_b128 v20, v[12:15]
	s_cmp_gt_i32 s7, 29
	s_cbranch_scc1 .LBB0_329
.LBB0_340:
	s_waitcnt vmcnt(14)
	v_lshlrev_b32_e32 v12, 16, v120
	v_and_b32_e32 v13, 0xffff0000, v120
	v_lshlrev_b32_e32 v14, 16, v121
	v_and_b32_e32 v15, 0xffff0000, v121
	v_pk_mul_f32 v[12:13], v[12:13], s[96:97] op_sel_hi:[1,0]
	v_pk_mul_f32 v[14:15], v[14:15], s[96:97] op_sel_hi:[1,0]
	v_exp_f32_e32 v12, v12
	v_exp_f32_e32 v13, v13
	v_exp_f32_e32 v14, v14
	v_exp_f32_e32 v15, v15
	v_pk_add_f32 v[12:13], v[12:13], 1.0 op_sel_hi:[1,0]
	v_pk_add_f32 v[14:15], v[14:15], 1.0 op_sel_hi:[1,0]
	v_rcp_f32_e32 v12, v12
	v_rcp_f32_e32 v13, v13
	v_rcp_f32_e32 v14, v14
	v_rcp_f32_e32 v15, v15
	s_add_i32 s8, s7, 64
	s_waitcnt vmcnt(17)
	v_and_b32_e32 v17, 0xffff0000, v118
	v_and_b32_e32 v19, 0xffff0000, v119
	v_lshlrev_b32_e32 v16, 16, v118
	v_lshlrev_b32_e32 v18, 16, v119
	s_cmp_ge_i32 s8, s43
	v_pk_mul_f32 v[14:15], v[14:15], v[18:19]
	v_pk_mul_f32 v[12:13], v[12:13], v[16:17]
	s_cselect_b64 vcc, -1, 0
	v_lshl_add_u32 v20, s8, 10, v11
	v_cndmask_b32_e32 v13, 0, v13, vcc
	v_cndmask_b32_e32 v12, 0, v12, vcc
	v_cndmask_b32_e32 v15, 0, v15, vcc
	v_cndmask_b32_e32 v14, 0, v14, vcc
	ds_write_b128 v20, v[12:15]
	s_cmp_gt_i32 s7, 21
	s_cbranch_scc1 .LBB0_330
.LBB0_341:
	s_waitcnt vmcnt(12)
	v_lshlrev_b32_e32 v12, 16, v116
	v_and_b32_e32 v13, 0xffff0000, v116
	v_lshlrev_b32_e32 v14, 16, v117
	v_and_b32_e32 v15, 0xffff0000, v117
	v_pk_mul_f32 v[12:13], v[12:13], s[96:97] op_sel_hi:[1,0]
	v_pk_mul_f32 v[14:15], v[14:15], s[96:97] op_sel_hi:[1,0]
	v_exp_f32_e32 v12, v12
	v_exp_f32_e32 v13, v13
	v_exp_f32_e32 v14, v14
	v_exp_f32_e32 v15, v15
	v_pk_add_f32 v[12:13], v[12:13], 1.0 op_sel_hi:[1,0]
	v_pk_add_f32 v[14:15], v[14:15], 1.0 op_sel_hi:[1,0]
	v_rcp_f32_e32 v12, v12
	v_rcp_f32_e32 v13, v13
	v_rcp_f32_e32 v14, v14
	v_rcp_f32_e32 v15, v15
	s_add_i32 s8, s7, 0x48
	s_waitcnt vmcnt(19)
	v_and_b32_e32 v17, 0xffff0000, v114
	v_and_b32_e32 v19, 0xffff0000, v115
	v_lshlrev_b32_e32 v16, 16, v114
	v_lshlrev_b32_e32 v18, 16, v115
	s_cmp_ge_i32 s8, s43
	v_pk_mul_f32 v[14:15], v[14:15], v[18:19]
	v_pk_mul_f32 v[12:13], v[12:13], v[16:17]
	s_cselect_b64 vcc, -1, 0
	v_lshl_add_u32 v20, s8, 10, v11
	v_cndmask_b32_e32 v13, 0, v13, vcc
	v_cndmask_b32_e32 v12, 0, v12, vcc
	v_cndmask_b32_e32 v15, 0, v15, vcc
	v_cndmask_b32_e32 v14, 0, v14, vcc
	ds_write_b128 v20, v[12:15]
	s_cmp_gt_i32 s7, 13
	s_cbranch_scc1 .LBB0_331
.LBB0_342:
	s_waitcnt vmcnt(10)
	v_lshlrev_b32_e32 v12, 16, v112
	v_and_b32_e32 v13, 0xffff0000, v112
	v_lshlrev_b32_e32 v14, 16, v113
	v_and_b32_e32 v15, 0xffff0000, v113
	v_pk_mul_f32 v[12:13], v[12:13], s[96:97] op_sel_hi:[1,0]
	v_pk_mul_f32 v[14:15], v[14:15], s[96:97] op_sel_hi:[1,0]
	v_exp_f32_e32 v12, v12
	v_exp_f32_e32 v13, v13
	v_exp_f32_e32 v14, v14
	v_exp_f32_e32 v15, v15
	v_pk_add_f32 v[12:13], v[12:13], 1.0 op_sel_hi:[1,0]
	v_pk_add_f32 v[14:15], v[14:15], 1.0 op_sel_hi:[1,0]
	v_rcp_f32_e32 v12, v12
	v_rcp_f32_e32 v13, v13
	v_rcp_f32_e32 v14, v14
	v_rcp_f32_e32 v15, v15
	s_add_i32 s8, s7, 0x50
	s_waitcnt vmcnt(21)
	v_and_b32_e32 v17, 0xffff0000, v110
	v_and_b32_e32 v19, 0xffff0000, v111
	v_lshlrev_b32_e32 v16, 16, v110
	v_lshlrev_b32_e32 v18, 16, v111
	s_cmp_ge_i32 s8, s43
	v_pk_mul_f32 v[14:15], v[14:15], v[18:19]
	v_pk_mul_f32 v[12:13], v[12:13], v[16:17]
	s_cselect_b64 vcc, -1, 0
	v_lshl_add_u32 v20, s8, 10, v11
	v_cndmask_b32_e32 v13, 0, v13, vcc
	v_cndmask_b32_e32 v12, 0, v12, vcc
	v_cndmask_b32_e32 v15, 0, v15, vcc
	v_cndmask_b32_e32 v14, 0, v14, vcc
	ds_write_b128 v20, v[12:15]
	s_cmp_gt_i32 s7, 5
	s_cbranch_scc1 .LBB0_319
.LBB0_343:
	s_waitcnt vmcnt(8)
	v_lshlrev_b32_e32 v12, 16, v108
	v_and_b32_e32 v13, 0xffff0000, v108
	v_lshlrev_b32_e32 v14, 16, v109
	v_and_b32_e32 v15, 0xffff0000, v109
	v_pk_mul_f32 v[12:13], v[12:13], s[96:97] op_sel_hi:[1,0]
	v_pk_mul_f32 v[14:15], v[14:15], s[96:97] op_sel_hi:[1,0]
	v_exp_f32_e32 v12, v12
	v_exp_f32_e32 v13, v13
	v_exp_f32_e32 v14, v14
	v_exp_f32_e32 v15, v15
	v_pk_add_f32 v[12:13], v[12:13], 1.0 op_sel_hi:[1,0]
	v_pk_add_f32 v[14:15], v[14:15], 1.0 op_sel_hi:[1,0]
	v_rcp_f32_e32 v12, v12
	v_rcp_f32_e32 v13, v13
	v_rcp_f32_e32 v14, v14
	v_rcp_f32_e32 v15, v15
	s_add_i32 s8, s7, 0x58
	s_waitcnt vmcnt(23)
	v_and_b32_e32 v17, 0xffff0000, v106
	v_and_b32_e32 v19, 0xffff0000, v107
	v_lshlrev_b32_e32 v16, 16, v106
	v_lshlrev_b32_e32 v18, 16, v107
	s_cmp_ge_i32 s8, s43
	v_pk_mul_f32 v[14:15], v[14:15], v[18:19]
	v_pk_mul_f32 v[12:13], v[12:13], v[16:17]
	s_cselect_b64 vcc, -1, 0
	v_lshl_add_u32 v11, s8, 10, v11
	v_cndmask_b32_e32 v13, 0, v13, vcc
	v_cndmask_b32_e32 v12, 0, v12, vcc
	v_cndmask_b32_e32 v15, 0, v15, vcc
	v_cndmask_b32_e32 v14, 0, v14, vcc
	ds_write_b128 v11, v[12:15]
	s_branch .LBB0_319
